# K-loops: removed the back-to-back s_setprio 0 / s_setprio 1 pair in the middle of each 32-MFMA run
# baseline (speedup 1.0000x reference)
; #define G8_STA(bufoff, ptr, sg, h) G8_STAGE1(bufoff, (ptr) + (h) * ((sg) ? hA1 : hA0), ((sg) ? voffA1 : voffA0), ((sg) ? r64A1 : r64A0))
; #define G8_STB(bufoff, ptr, sg, h) G8_STAGE1(bufoff, (ptr) + (h) * ((sg) ? hB1 : hB0), ((sg) ? voffB1 : voffB0), ((sg) ? r64B1 : r64B0))
; #define G8_LDA(dst, b, h) do { _Pragma("unroll") for (int m = 0; m < 4; ++m) _Pragma("unroll") for (int k = 0; k < 2; ++k) dst[m][k] = *(const LAS bf16x8*)(lds + G8_SA(b, h) + aoff + m * 2048 + k * 1024); } while (0)
; #define G8_LDB(dst, b, h) do { _Pragma("unroll") for (int n = 0; n < 2; ++n) _Pragma("unroll") for (int k = 0; k < 2; ++k) dst[n][k] = *(const LAS bf16x8*)(lds + G8_SB(b, h) + boff + n * 2048 + k * 1024); } while (0)
; #define G8_MMA(ai, bj, At, Bt) do { __builtin_amdgcn_s_setprio(1); _Pragma("unroll") for (int m = 0; m < 4; ++m) _Pragma("unroll") for (int n = 0; n < 2; ++n) _Pragma("unroll") for (int k = 0; k < 2; ++k) \
;         acc[ai][bj][m][n] = __builtin_amdgcn_mfma_f32_16x16x32_bf16(Bt[n][k], At[m][k], acc[ai][bj][m][n], 0, 0, 0); __builtin_amdgcn_s_setprio(0); } while (0)
; #define G8_BAR __builtin_amdgcn_s_barrier()
; template <class P>
; __device__ __forceinline__ void gemm_phase(LAS unsigned char* lds, const P& p, const int G, const int c) {
;     ...
;         for (int t = 0; t < nt; t += 2) {
;             const bool last = (t == nt - 2);
;             const bool sg1 = (NS > 1) && (t + 1 >= nt0);
;             const bool sg2 = (NS > 1) && !last && (t + 2 >= nt0);
;             const char* a1 = sg1 ? cA1 + (long)(t + 1 - nt0) * ksA1 : cA0 + (long)(t + 1) * ksA0;
;             const char* a2 = last ? nA0 : (sg2 ? cA1 + (long)(t + 2 - nt0) * ksA1 : cA0 + (long)(t + 2) * ksA0);
;             const char* b2 = last ? nB0 : (sg2 ? cB1 + (long)(t + 2 - nt0) * ksB1 : cB0 + (long)(t + 2) * ksB0);
;             const char* a3 = a2 + (sg2 ? ksA1 : ksA0); const char* b3 = b2 + (sg2 ? ksB1 : ksB0);
;             G8_LDB(B0, 0, 0); G8_LDB(B1, 0, 1); G8_SCHED; G8_LDA(At, 0, 0); G8_STA(G8_SA(1, 1), a1, sg1, 1);
;             G8_WAIT_V(8); G8_WAIT_L(0); G8_BAR; G8_MMA(0, 0, At, B0); G8_MMA(0, 1, At, B1); G8_BAR; G8_SCHED;
;             G8_LDA(At, 0, 1); G8_STB(G8_SB(0, 0), b2, sg2, 0); G8_STB(G8_SB(0, 1), b2, sg2, 1); G8_STA(G8_SA(0, 0), a2, sg2, 0);
;             G8_WAIT_V(8); G8_WAIT_L(0); G8_BAR; G8_MMA(1, 0, At, B0); G8_MMA(1, 1, At, B1); G8_BAR; G8_SCHED;
.LBB0_155:
	ds_read_b128 v[56:59], v173
	ds_read_b128 v[60:63], v173 offset:1024
	ds_read_b128 v[176:179], v173 offset:2048
	ds_read_b128 v[180:183], v173 offset:3072
	ds_read_b128 v[184:187], v174
	ds_read_b128 v[188:191], v174 offset:1024
	ds_read_b128 v[192:195], v174 offset:2048
	ds_read_b128 v[196:199], v174 offset:3072
	s_add_u32 s53, s82, s84
	s_addc_u32 s56, s83, s85
	s_add_u32 s53, s53, 0x820000
	s_addc_u32 s56, s56, 0
	s_cmp_eq_u32 s84, 0x38e0000
	s_cselect_b32 s57, s18, s56
	s_cselect_b32 s56, s19, s53
	s_cselect_b32 s65, s30, s29
	s_cselect_b32 s64, s31, s28
	v_lshl_add_u64 v[64:65], v[54:55], 0, s[84:85]
	s_mov_b64 s[66:67], 0x414000
	v_lshl_add_u64 v[234:235], v[64:65], 0, s[66:67]
	s_add_i32 m0, s27, 0xc000
	s_mov_b64 s[66:67], 0x416000
	ds_read_b128 v[200:203], v175
	ds_read_b128 v[204:207], v175 offset:1024
	ds_read_b128 v[210:213], v175 offset:2048
	ds_read_b128 v[214:217], v175 offset:3072
	ds_read_b128 v[218:221], v175 offset:4096
	ds_read_b128 v[222:225], v175 offset:5120
	ds_read_b128 v[226:229], v175 offset:6144
	ds_read_b128 v[230:233], v175 offset:7168
	global_load_lds_dwordx4 v[234:235], off
	v_lshl_add_u64 v[64:65], v[64:65], 0, s[66:67]
	s_add_i32 m0, s27, 0xe000
	s_nop 0
	global_load_lds_dwordx4 v[64:65], off
	s_waitcnt vmcnt(8)
	s_waitcnt lgkmcnt(0)
	s_barrier
	s_setprio 1
	s_waitcnt lgkmcnt(0)
	v_mfma_f32_16x16x32_bf16 v[98:101], v[56:59], v[200:203], v[98:101]
	v_mfma_f32_16x16x32_bf16 v[138:141], v[176:179], v[200:203], v[138:141]
	v_mfma_f32_16x16x32_bf16 v[70:73], v[56:59], v[210:213], v[70:73]
	v_mfma_f32_16x16x32_bf16 v[114:117], v[176:179], v[210:213], v[114:117]
	v_mfma_f32_16x16x32_bf16 v[46:49], v[56:59], v[218:221], v[46:49]
	v_mfma_f32_16x16x32_bf16 v[110:113], v[176:179], v[218:221], v[110:113]
	v_mfma_f32_16x16x32_bf16 v[38:41], v[56:59], v[226:229], v[38:41]
	v_mfma_f32_16x16x32_bf16 v[130:133], v[176:179], v[226:229], v[130:133]
	v_mfma_f32_16x16x32_bf16 v[98:101], v[60:63], v[204:207], v[98:101]
	v_mfma_f32_16x16x32_bf16 v[138:141], v[180:183], v[204:207], v[138:141]
	v_mfma_f32_16x16x32_bf16 v[70:73], v[60:63], v[214:217], v[70:73]
	v_mfma_f32_16x16x32_bf16 v[114:117], v[180:183], v[214:217], v[114:117]
	v_mfma_f32_16x16x32_bf16 v[46:49], v[60:63], v[222:225], v[46:49]
	v_mfma_f32_16x16x32_bf16 v[110:113], v[180:183], v[222:225], v[110:113]
	v_mfma_f32_16x16x32_bf16 v[38:41], v[60:63], v[230:233], v[38:41]
	v_mfma_f32_16x16x32_bf16 v[130:133], v[180:183], v[230:233], v[130:133]
	v_mfma_f32_16x16x32_bf16 v[134:137], v[184:187], v[200:203], v[134:137]
	v_mfma_f32_16x16x32_bf16 v[74:77], v[192:195], v[200:203], v[74:77]
	v_mfma_f32_16x16x32_bf16 v[106:109], v[184:187], v[210:213], v[106:109]
	v_mfma_f32_16x16x32_bf16 v[50:53], v[192:195], v[210:213], v[50:53]
	v_mfma_f32_16x16x32_bf16 v[102:105], v[184:187], v[218:221], v[102:105]
	v_mfma_f32_16x16x32_bf16 v[42:45], v[192:195], v[218:221], v[42:45]
	v_mfma_f32_16x16x32_bf16 v[126:129], v[184:187], v[226:229], v[126:129]
	v_mfma_f32_16x16x32_bf16 v[34:37], v[192:195], v[226:229], v[34:37]
	v_mfma_f32_16x16x32_bf16 v[134:137], v[188:191], v[204:207], v[134:137]
	v_mfma_f32_16x16x32_bf16 v[74:77], v[196:199], v[204:207], v[74:77]
	v_mfma_f32_16x16x32_bf16 v[106:109], v[188:191], v[214:217], v[106:109]
	v_mfma_f32_16x16x32_bf16 v[50:53], v[196:199], v[214:217], v[50:53]
	v_mfma_f32_16x16x32_bf16 v[102:105], v[188:191], v[222:225], v[102:105]
	v_mfma_f32_16x16x32_bf16 v[42:45], v[196:199], v[222:225], v[42:45]
	v_mfma_f32_16x16x32_bf16 v[126:129], v[188:191], v[230:233], v[126:129]
	v_mfma_f32_16x16x32_bf16 v[34:37], v[196:199], v[230:233], v[34:37]
	s_setprio 0
	s_barrier
	s_add_i32 s53, s50, s2
	v_lshl_add_u64 v[234:235], s[64:65], 0, v[142:143]
	s_mov_b32 m0, s53
	ds_read_b128 v[200:203], v175 offset:16384
	ds_read_b128 v[204:207], v175 offset:17408
	ds_read_b128 v[210:213], v175 offset:18432
	ds_read_b128 v[214:217], v175 offset:19456
	ds_read_b128 v[218:221], v175 offset:20480
	ds_read_b128 v[222:225], v175 offset:21504
	ds_read_b128 v[226:229], v175 offset:22528
	ds_read_b128 v[230:233], v175 offset:23552
	global_load_lds_dwordx4 v[234:235], off
	v_lshl_add_u64 v[64:65], v[234:235], 0, s[4:5]
	s_add_i32 m0, s53, 0x2000
	s_add_i32 s53, s51, s2
	global_load_lds_dwordx4 v[64:65], off
	v_lshl_add_u64 v[64:65], v[234:235], 0, s[6:7]
	s_mov_b32 m0, s53
	v_lshl_add_u64 v[236:237], s[56:57], 0, v[144:145]
	global_load_lds_dwordx4 v[64:65], off
	v_lshl_add_u64 v[64:65], v[234:235], 0, s[8:9]
	s_add_i32 m0, s53, 0x2000
	s_nop 0
	global_load_lds_dwordx4 v[64:65], off
	s_mov_b32 m0, s27
	v_lshl_add_u64 v[64:65], v[236:237], 0, s[4:5]
	global_load_lds_dwordx4 v[236:237], off
	s_mov_b32 m0, s33
	s_nop 0
	global_load_lds_dwordx4 v[64:65], off
	s_waitcnt vmcnt(8)
	s_waitcnt lgkmcnt(0)
	s_barrier
; #define G8_STA(bufoff, ptr, sg, h) G8_STAGE1(bufoff, (ptr) + (h) * ((sg) ? hA1 : hA0), ((sg) ? voffA1 : voffA0), ((sg) ? r64A1 : r64A0))
; #define G8_STB(bufoff, ptr, sg, h) G8_STAGE1(bufoff, (ptr) + (h) * ((sg) ? hB1 : hB0), ((sg) ? voffB1 : voffB0), ((sg) ? r64B1 : r64B0))
; #define G8_LDA(dst, b, h) do { _Pragma("unroll") for (int m = 0; m < 4; ++m) _Pragma("unroll") for (int k = 0; k < 2; ++k) dst[m][k] = *(const LAS bf16x8*)(lds + G8_SA(b, h) + aoff + m * 2048 + k * 1024); } while (0)
; #define G8_LDB(dst, b, h) do { _Pragma("unroll") for (int n = 0; n < 2; ++n) _Pragma("unroll") for (int k = 0; k < 2; ++k) dst[n][k] = *(const LAS bf16x8*)(lds + G8_SB(b, h) + boff + n * 2048 + k * 1024); } while (0)
; #define G8_MMA(ai, bj, At, Bt) do { __builtin_amdgcn_s_setprio(1); _Pragma("unroll") for (int m = 0; m < 4; ++m) _Pragma("unroll") for (int n = 0; n < 2; ++n) _Pragma("unroll") for (int k = 0; k < 2; ++k) \
;         acc[ai][bj][m][n] = __builtin_amdgcn_mfma_f32_16x16x32_bf16(Bt[n][k], At[m][k], acc[ai][bj][m][n], 0, 0, 0); __builtin_amdgcn_s_setprio(0); } while (0)
; #define G8_WAIT_V(n) asm volatile("s_waitcnt vmcnt(" #n ")" ::: "memory")
; #define G8_WAIT_L(n) asm volatile("s_waitcnt lgkmcnt(" #n ")" ::: "memory")
; #define G8_BAR __builtin_amdgcn_s_barrier()
; #define G8_SCHED __builtin_amdgcn_sched_barrier(0)
; template <class P>
; __device__ __forceinline__ void gemm_phase(LAS unsigned char* lds, const P& p, const int G, const int c) {
;     ...
;             G8_LDA(At, 0, 1); G8_STB(G8_SB(0, 0), b2, sg2, 0); G8_STB(G8_SB(0, 1), b2, sg2, 1); G8_STA(G8_SA(0, 0), a2, sg2, 0);
;             G8_WAIT_V(8); G8_WAIT_L(0); G8_BAR; G8_MMA(1, 0, At, B0); G8_MMA(1, 1, At, B1); G8_BAR; G8_SCHED;
;             G8_LDB(B0, 1, 0); G8_LDB(B1, 1, 1); G8_SCHED; G8_LDA(At, 1, 0); G8_STA(G8_SA(0, 1), a2, sg2, 1);
;             G8_WAIT_V(8); G8_WAIT_L(0); G8_BAR; G8_MMA(0, 0, At, B0); G8_MMA(0, 1, At, B1); G8_BAR; G8_SCHED;
	s_setprio 1
	s_waitcnt lgkmcnt(0)
	v_mfma_f32_16x16x32_bf16 v[30:33], v[56:59], v[200:203], v[30:33]
	v_mfma_f32_16x16x32_bf16 v[122:125], v[176:179], v[200:203], v[122:125]
	v_mfma_f32_16x16x32_bf16 v[22:25], v[56:59], v[210:213], v[22:25]
	v_mfma_f32_16x16x32_bf16 v[94:97], v[176:179], v[210:213], v[94:97]
	v_mfma_f32_16x16x32_bf16 v[14:17], v[56:59], v[218:221], v[14:17]
	v_mfma_f32_16x16x32_bf16 v[90:93], v[176:179], v[218:221], v[90:93]
	v_mfma_f32_16x16x32_bf16 v[6:9], v[56:59], v[226:229], v[6:9]
	v_mfma_f32_16x16x32_bf16 v[30:33], v[60:63], v[204:207], v[30:33]
	v_mfma_f32_16x16x32_bf16 v[122:125], v[180:183], v[204:207], v[122:125]
	v_mfma_f32_16x16x32_bf16 v[22:25], v[60:63], v[214:217], v[22:25]
	v_mfma_f32_16x16x32_bf16 v[94:97], v[180:183], v[214:217], v[94:97]
	v_mfma_f32_16x16x32_bf16 v[14:17], v[60:63], v[222:225], v[14:17]
	v_mfma_f32_16x16x32_bf16 v[90:93], v[180:183], v[222:225], v[90:93]
	v_mfma_f32_16x16x32_bf16 v[6:9], v[60:63], v[230:233], v[6:9]
	v_mfma_f32_16x16x32_bf16 v[56:59], v[176:179], v[226:229], v[78:81]
	v_mfma_f32_16x16x32_bf16 v[56:59], v[180:183], v[230:233], v[56:59]
	v_mfma_f32_16x16x32_bf16 v[78:81], v[184:187], v[210:213], v[86:89]
	v_mfma_f32_16x16x32_bf16 v[26:29], v[192:195], v[200:203], v[26:29]
	v_mfma_f32_16x16x32_bf16 v[86:89], v[188:191], v[214:217], v[78:81]
	v_mfma_f32_16x16x32_bf16 v[18:21], v[192:195], v[210:213], v[18:21]
	v_mfma_f32_16x16x32_bf16 v[78:81], v[184:187], v[218:221], v[82:85]
	v_mfma_f32_16x16x32_bf16 v[10:13], v[192:195], v[218:221], v[10:13]
	v_mfma_f32_16x16x32_bf16 v[64:67], v[184:187], v[226:229], v[66:69]
	v_mfma_f32_16x16x32_bf16 v[2:5], v[192:195], v[226:229], v[2:5]
	v_mfma_f32_16x16x32_bf16 v[60:63], v[184:187], v[200:203], v[118:121]
	v_mfma_f32_16x16x32_bf16 v[26:29], v[196:199], v[204:207], v[26:29]
	v_mfma_f32_16x16x32_bf16 v[18:21], v[196:199], v[214:217], v[18:21]
	v_mfma_f32_16x16x32_bf16 v[82:85], v[188:191], v[222:225], v[78:81]
	v_mfma_f32_16x16x32_bf16 v[10:13], v[196:199], v[222:225], v[10:13]
	v_mfma_f32_16x16x32_bf16 v[64:67], v[188:191], v[230:233], v[64:67]
	v_mfma_f32_16x16x32_bf16 v[2:5], v[196:199], v[230:233], v[2:5]
	v_mfma_f32_16x16x32_bf16 v[60:63], v[188:191], v[204:207], v[60:63]
	s_setprio 0
	s_barrier
	s_add_i32 s53, 0, 0x18000
	v_add_u32_e32 v68, s53, v152
	s_add_i32 s56, 0, 0x1c000
	ds_read_b128 v[78:81], v68
	ds_read_b128 v[118:121], v68 offset:1024
	ds_read_b128 v[176:179], v68 offset:2048
	ds_read_b128 v[180:183], v68 offset:3072
	v_add_u32_e32 v68, s56, v152
	ds_read_b128 v[184:187], v68
	ds_read_b128 v[188:191], v68 offset:1024
	ds_read_b128 v[192:195], v68 offset:2048
	ds_read_b128 v[196:199], v68 offset:3072
	s_mov_b32 m0, s34
	v_lshl_add_u64 v[68:69], v[236:237], 0, s[6:7]
	ds_read_b128 v[200:203], v175 offset:32768
	ds_read_b128 v[204:207], v175 offset:33792
	ds_read_b128 v[210:213], v175 offset:34816
	ds_read_b128 v[214:217], v175 offset:35840
	ds_read_b128 v[218:221], v175 offset:36864
	ds_read_b128 v[222:225], v175 offset:37888
	ds_read_b128 v[226:229], v175 offset:38912
	ds_read_b128 v[230:233], v175 offset:39936
	global_load_lds_dwordx4 v[68:69], off
	v_lshl_add_u64 v[68:69], v[236:237], 0, s[8:9]
	s_mov_b32 m0, s35
	s_nop 0
	global_load_lds_dwordx4 v[68:69], off
	s_waitcnt vmcnt(8)
	s_waitcnt lgkmcnt(0)
	s_barrier
	s_setprio 1
	s_waitcnt lgkmcnt(0)
	v_mfma_f32_16x16x32_bf16 v[98:101], v[78:81], v[200:203], v[98:101]
	v_mfma_f32_16x16x32_bf16 v[138:141], v[176:179], v[200:203], v[138:141]
	v_mfma_f32_16x16x32_bf16 v[68:71], v[78:81], v[210:213], v[70:73]
	v_mfma_f32_16x16x32_bf16 v[114:117], v[176:179], v[210:213], v[114:117]
	v_mfma_f32_16x16x32_bf16 v[46:49], v[78:81], v[218:221], v[46:49]
	v_mfma_f32_16x16x32_bf16 v[110:113], v[176:179], v[218:221], v[110:113]
	v_mfma_f32_16x16x32_bf16 v[38:41], v[78:81], v[226:229], v[38:41]
	v_mfma_f32_16x16x32_bf16 v[130:133], v[176:179], v[226:229], v[130:133]
	v_mfma_f32_16x16x32_bf16 v[98:101], v[118:121], v[204:207], v[98:101]
	v_mfma_f32_16x16x32_bf16 v[138:141], v[180:183], v[204:207], v[138:141]
	v_mfma_f32_16x16x32_bf16 v[70:73], v[118:121], v[214:217], v[68:71]
	v_mfma_f32_16x16x32_bf16 v[114:117], v[180:183], v[214:217], v[114:117]
	v_mfma_f32_16x16x32_bf16 v[46:49], v[118:121], v[222:225], v[46:49]
	v_mfma_f32_16x16x32_bf16 v[110:113], v[180:183], v[222:225], v[110:113]
	v_mfma_f32_16x16x32_bf16 v[38:41], v[118:121], v[230:233], v[38:41]
	v_mfma_f32_16x16x32_bf16 v[130:133], v[180:183], v[230:233], v[130:133]
	v_mfma_f32_16x16x32_bf16 v[134:137], v[184:187], v[200:203], v[134:137]
	v_mfma_f32_16x16x32_bf16 v[74:77], v[192:195], v[200:203], v[74:77]
	v_mfma_f32_16x16x32_bf16 v[106:109], v[184:187], v[210:213], v[106:109]
	v_mfma_f32_16x16x32_bf16 v[50:53], v[192:195], v[210:213], v[50:53]
	v_mfma_f32_16x16x32_bf16 v[102:105], v[184:187], v[218:221], v[102:105]
	v_mfma_f32_16x16x32_bf16 v[42:45], v[192:195], v[218:221], v[42:45]
	v_mfma_f32_16x16x32_bf16 v[126:129], v[184:187], v[226:229], v[126:129]
	v_mfma_f32_16x16x32_bf16 v[34:37], v[192:195], v[226:229], v[34:37]
	v_mfma_f32_16x16x32_bf16 v[134:137], v[188:191], v[204:207], v[134:137]
	v_mfma_f32_16x16x32_bf16 v[74:77], v[196:199], v[204:207], v[74:77]
	v_mfma_f32_16x16x32_bf16 v[106:109], v[188:191], v[214:217], v[106:109]
	v_mfma_f32_16x16x32_bf16 v[50:53], v[196:199], v[214:217], v[50:53]
	v_mfma_f32_16x16x32_bf16 v[102:105], v[188:191], v[222:225], v[102:105]
	v_mfma_f32_16x16x32_bf16 v[42:45], v[196:199], v[222:225], v[42:45]
	v_mfma_f32_16x16x32_bf16 v[126:129], v[188:191], v[230:233], v[126:129]
	v_mfma_f32_16x16x32_bf16 v[34:37], v[196:199], v[230:233], v[34:37]
	s_setprio 0
	s_barrier
; #define G8_STA(bufoff, ptr, sg, h) G8_STAGE1(bufoff, (ptr) + (h) * ((sg) ? hA1 : hA0), ((sg) ? voffA1 : voffA0), ((sg) ? r64A1 : r64A0))
; #define G8_STB(bufoff, ptr, sg, h) G8_STAGE1(bufoff, (ptr) + (h) * ((sg) ? hB1 : hB0), ((sg) ? voffB1 : voffB0), ((sg) ? r64B1 : r64B0))
; #define G8_LDA(dst, b, h) do { _Pragma("unroll") for (int m = 0; m < 4; ++m) _Pragma("unroll") for (int k = 0; k < 2; ++k) dst[m][k] = *(const LAS bf16x8*)(lds + G8_SA(b, h) + aoff + m * 2048 + k * 1024); } while (0)
; #define G8_LDB(dst, b, h) do { _Pragma("unroll") for (int n = 0; n < 2; ++n) _Pragma("unroll") for (int k = 0; k < 2; ++k) dst[n][k] = *(const LAS bf16x8*)(lds + G8_SB(b, h) + boff + n * 2048 + k * 1024); } while (0)
; #define G8_MMA(ai, bj, At, Bt) do { __builtin_amdgcn_s_setprio(1); _Pragma("unroll") for (int m = 0; m < 4; ++m) _Pragma("unroll") for (int n = 0; n < 2; ++n) _Pragma("unroll") for (int k = 0; k < 2; ++k) \
;         acc[ai][bj][m][n] = __builtin_amdgcn_mfma_f32_16x16x32_bf16(Bt[n][k], At[m][k], acc[ai][bj][m][n], 0, 0, 0); __builtin_amdgcn_s_setprio(0); } while (0)
; #define G8_WAIT_V(n) asm volatile("s_waitcnt vmcnt(" #n ")" ::: "memory")
; #define G8_WAIT_L(n) asm volatile("s_waitcnt lgkmcnt(" #n ")" ::: "memory")
; #define G8_BAR __builtin_amdgcn_s_barrier()
; #define G8_SCHED __builtin_amdgcn_sched_barrier(0)
; template <class P>
; __device__ __forceinline__ void gemm_phase(LAS unsigned char* lds, const P& p, const int G, const int c) {
;     ...
;             G8_LDB(B0, 1, 0); G8_LDB(B1, 1, 1); G8_SCHED; G8_LDA(At, 1, 0); G8_STA(G8_SA(0, 1), a2, sg2, 1);
;             G8_WAIT_V(8); G8_WAIT_L(0); G8_BAR; G8_MMA(0, 0, At, B0); G8_MMA(0, 1, At, B1); G8_BAR; G8_SCHED;
;             G8_LDA(At, 1, 1); G8_STB(G8_SB(1, 0), b3, sg2, 0); G8_STB(G8_SB(1, 1), b3, sg2, 1); G8_STA(G8_SA(1, 0), a3, sg2, 0);
;             G8_WAIT_V(8); G8_WAIT_L(0); G8_BAR; G8_MMA(1, 0, At, B0); G8_MMA(1, 1, At, B1); G8_BAR; G8_SCHED;
;         }
;         if (wr == 0) G8_BAR;
	s_add_i32 s53, s53, s2
	v_lshl_add_u64 v[68:69], v[234:235], 0, s[12:13]
	s_mov_b32 m0, s53
	ds_read_b128 v[200:203], v175 offset:49152
	ds_read_b128 v[204:207], v175 offset:50176
	ds_read_b128 v[210:213], v175 offset:51200
	ds_read_b128 v[214:217], v175 offset:52224
	ds_read_b128 v[218:221], v175 offset:53248
	ds_read_b128 v[222:225], v175 offset:54272
	ds_read_b128 v[226:229], v175 offset:55296
	ds_read_b128 v[230:233], v175 offset:56320
	global_load_lds_dwordx4 v[68:69], off
	v_lshl_add_u64 v[68:69], v[234:235], 0, s[14:15]
	s_add_i32 m0, s53, 0x2000
	s_add_i32 s53, s56, s2
	global_load_lds_dwordx4 v[68:69], off
	v_lshl_add_u64 v[68:69], v[234:235], 0, s[22:23]
	s_mov_b32 m0, s53
	s_nop 0
	global_load_lds_dwordx4 v[68:69], off
	v_lshl_add_u64 v[68:69], v[234:235], 0, s[36:37]
	s_add_i32 m0, s53, 0x2000
	s_nop 0
	global_load_lds_dwordx4 v[68:69], off
	v_lshl_add_u64 v[68:69], v[236:237], 0, s[16:17]
	s_mov_b32 m0, s47
	s_nop 0
	global_load_lds_dwordx4 v[68:69], off
	v_lshl_add_u64 v[68:69], v[236:237], 0, s[20:21]
	s_mov_b32 m0, s48
	s_nop 0
	global_load_lds_dwordx4 v[68:69], off
	s_waitcnt vmcnt(8)
	s_waitcnt lgkmcnt(0)
	s_barrier
	s_setprio 1
	s_waitcnt lgkmcnt(0)
	v_mfma_f32_16x16x32_bf16 v[30:33], v[78:81], v[200:203], v[30:33]
	v_mfma_f32_16x16x32_bf16 v[122:125], v[176:179], v[200:203], v[122:125]
	v_mfma_f32_16x16x32_bf16 v[22:25], v[78:81], v[210:213], v[22:25]
	v_mfma_f32_16x16x32_bf16 v[94:97], v[176:179], v[210:213], v[94:97]
	v_mfma_f32_16x16x32_bf16 v[14:17], v[78:81], v[218:221], v[14:17]
	v_mfma_f32_16x16x32_bf16 v[90:93], v[176:179], v[218:221], v[90:93]
	v_mfma_f32_16x16x32_bf16 v[6:9], v[78:81], v[226:229], v[6:9]
	v_mfma_f32_16x16x32_bf16 v[56:59], v[176:179], v[226:229], v[56:59]
	v_mfma_f32_16x16x32_bf16 v[30:33], v[118:121], v[204:207], v[30:33]
	v_mfma_f32_16x16x32_bf16 v[122:125], v[180:183], v[204:207], v[122:125]
	v_mfma_f32_16x16x32_bf16 v[22:25], v[118:121], v[214:217], v[22:25]
	v_mfma_f32_16x16x32_bf16 v[94:97], v[180:183], v[214:217], v[94:97]
	v_mfma_f32_16x16x32_bf16 v[14:17], v[118:121], v[222:225], v[14:17]
	v_mfma_f32_16x16x32_bf16 v[90:93], v[180:183], v[222:225], v[90:93]
	v_mfma_f32_16x16x32_bf16 v[6:9], v[118:121], v[230:233], v[6:9]
	v_mfma_f32_16x16x32_bf16 v[78:81], v[180:183], v[230:233], v[56:59]
	v_mfma_f32_16x16x32_bf16 v[56:59], v[184:187], v[200:203], v[60:63]
	v_mfma_f32_16x16x32_bf16 v[118:121], v[188:191], v[204:207], v[56:59]
	v_mfma_f32_16x16x32_bf16 v[56:59], v[184:187], v[210:213], v[86:89]
	v_mfma_f32_16x16x32_bf16 v[86:89], v[188:191], v[214:217], v[56:59]
	v_mfma_f32_16x16x32_bf16 v[56:59], v[184:187], v[218:221], v[82:85]
	v_mfma_f32_16x16x32_bf16 v[26:29], v[192:195], v[200:203], v[26:29]
	v_mfma_f32_16x16x32_bf16 v[18:21], v[192:195], v[210:213], v[18:21]
	v_mfma_f32_16x16x32_bf16 v[82:85], v[188:191], v[222:225], v[56:59]
	v_mfma_f32_16x16x32_bf16 v[10:13], v[192:195], v[218:221], v[10:13]
	v_mfma_f32_16x16x32_bf16 v[56:59], v[184:187], v[226:229], v[64:67]
	v_mfma_f32_16x16x32_bf16 v[2:5], v[192:195], v[226:229], v[2:5]
	v_mfma_f32_16x16x32_bf16 v[26:29], v[196:199], v[204:207], v[26:29]
	v_mfma_f32_16x16x32_bf16 v[18:21], v[196:199], v[214:217], v[18:21]
	v_mfma_f32_16x16x32_bf16 v[10:13], v[196:199], v[222:225], v[10:13]
	v_mfma_f32_16x16x32_bf16 v[66:69], v[188:191], v[230:233], v[56:59]
	v_mfma_f32_16x16x32_bf16 v[2:5], v[196:199], v[230:233], v[2:5]
	s_setprio 0
	s_barrier
	s_add_i32 s52, s52, 2
	s_add_u32 s28, s28, 0x200000
	s_addc_u32 s29, s29, 0
	s_add_u32 s84, s84, 0x820000
	s_addc_u32 s85, s85, 0
	s_cmp_gt_u32 s52, 13
	s_cbranch_scc0 .LBB0_155
	s_and_b64 vcc, exec, s[38:39]
	s_cbranch_vccz .LBB0_158
	s_barrier

; #define G8_STA(bufoff, ptr, sg, h) G8_STAGE1(bufoff, (ptr) + (h) * ((sg) ? hA1 : hA0), ((sg) ? voffA1 : voffA0), ((sg) ? r64A1 : r64A0))
; #define G8_STB(bufoff, ptr, sg, h) G8_STAGE1(bufoff, (ptr) + (h) * ((sg) ? hB1 : hB0), ((sg) ? voffB1 : voffB0), ((sg) ? r64B1 : r64B0))
; #define G8_LDA(dst, b, h) do { _Pragma("unroll") for (int m = 0; m < 4; ++m) _Pragma("unroll") for (int k = 0; k < 2; ++k) dst[m][k] = *(const LAS bf16x8*)(lds + G8_SA(b, h) + aoff + m * 2048 + k * 1024); } while (0)
; #define G8_LDB(dst, b, h) do { _Pragma("unroll") for (int n = 0; n < 2; ++n) _Pragma("unroll") for (int k = 0; k < 2; ++k) dst[n][k] = *(const LAS bf16x8*)(lds + G8_SB(b, h) + boff + n * 2048 + k * 1024); } while (0)
; #define G8_MMA(ai, bj, At, Bt) do { __builtin_amdgcn_s_setprio(1); _Pragma("unroll") for (int m = 0; m < 4; ++m) _Pragma("unroll") for (int n = 0; n < 2; ++n) _Pragma("unroll") for (int k = 0; k < 2; ++k) \
;         acc[ai][bj][m][n] = __builtin_amdgcn_mfma_f32_16x16x32_bf16(Bt[n][k], At[m][k], acc[ai][bj][m][n], 0, 0, 0); __builtin_amdgcn_s_setprio(0); } while (0)
; #define G8_BAR __builtin_amdgcn_s_barrier()
; template <class P>
; __device__ __forceinline__ void gemm_phase(LAS unsigned char* lds, const P& p, const int G, const int c) {
;     ...
;         for (int t = 0; t < nt; t += 2) {
;             const bool last = (t == nt - 2);
;             const bool sg1 = (NS > 1) && (t + 1 >= nt0);
;             const bool sg2 = (NS > 1) && !last && (t + 2 >= nt0);
;             const char* a1 = sg1 ? cA1 + (long)(t + 1 - nt0) * ksA1 : cA0 + (long)(t + 1) * ksA0;
;             const char* a2 = last ? nA0 : (sg2 ? cA1 + (long)(t + 2 - nt0) * ksA1 : cA0 + (long)(t + 2) * ksA0);
;             const char* b2 = last ? nB0 : (sg2 ? cB1 + (long)(t + 2 - nt0) * ksB1 : cB0 + (long)(t + 2) * ksB0);
;             const char* a3 = a2 + (sg2 ? ksA1 : ksA0); const char* b3 = b2 + (sg2 ? ksB1 : ksB0);
;             G8_LDB(B0, 0, 0); G8_LDB(B1, 0, 1); G8_SCHED; G8_LDA(At, 0, 0); G8_STA(G8_SA(1, 1), a1, sg1, 1);
;             G8_WAIT_V(8); G8_WAIT_L(0); G8_BAR; G8_MMA(0, 0, At, B0); G8_MMA(0, 1, At, B1); G8_BAR; G8_SCHED;
;             G8_LDA(At, 0, 1); G8_STB(G8_SB(0, 0), b2, sg2, 0); G8_STB(G8_SB(0, 1), b2, sg2, 1); G8_STA(G8_SA(0, 0), a2, sg2, 0);
;             G8_WAIT_V(8); G8_WAIT_L(0); G8_BAR; G8_MMA(1, 0, At, B0); G8_MMA(1, 1, At, B1); G8_BAR; G8_SCHED;
.LBB0_277:
	v_add_u32_e32 v144, s52, v1
	ds_read_b128 v[132:135], v144
	ds_read_b128 v[136:139], v144 offset:1024
	ds_read_b128 v[140:143], v144 offset:2048
	ds_read_b128 v[176:179], v144 offset:3072
	v_add_u32_e32 v144, s53, v1
	ds_read_b128 v[180:183], v144
	ds_read_b128 v[184:187], v144 offset:1024
	ds_read_b128 v[188:191], v144 offset:2048
	ds_read_b128 v[192:195], v144 offset:3072
	s_add_i32 s57, s57, 2
	s_and_b64 s[30:31], exec, s[30:31]
	s_cselect_b32 s31, s7, s49
	s_cselect_b32 s30, s18, s19
	v_lshl_add_u64 v[144:145], v[130:131], 0, s[76:77]
	s_mov_b64 s[64:65], 0x414000
	v_lshl_add_u64 v[230:231], v[144:145], 0, s[64:65]
	s_add_i32 m0, s27, 0xc000
	s_mov_b64 s[64:65], 0x416000
	ds_read_b128 v[196:199], v175
	ds_read_b128 v[200:203], v175 offset:1024
	ds_read_b128 v[204:207], v175 offset:2048
	ds_read_b128 v[210:213], v175 offset:3072
	ds_read_b128 v[214:217], v175 offset:4096
	ds_read_b128 v[218:221], v175 offset:5120
	ds_read_b128 v[222:225], v175 offset:6144
	ds_read_b128 v[226:229], v175 offset:7168
	global_load_lds_dwordx4 v[230:231], off
	v_lshl_add_u64 v[144:145], v[144:145], 0, s[64:65]
	s_add_i32 m0, s27, 0xe000
	s_nop 0
	global_load_lds_dwordx4 v[144:145], off
	s_waitcnt vmcnt(8)
	s_waitcnt lgkmcnt(0)
	s_barrier
	s_setprio 1
	s_waitcnt lgkmcnt(0)
	v_mfma_f32_16x16x32_bf16 v[126:129], v[132:135], v[196:199], v[126:129]
	v_mfma_f32_16x16x32_bf16 v[122:125], v[140:143], v[196:199], v[122:125]
	v_mfma_f32_16x16x32_bf16 v[118:121], v[132:135], v[204:207], v[118:121]
	v_mfma_f32_16x16x32_bf16 v[114:117], v[140:143], v[204:207], v[114:117]
	v_mfma_f32_16x16x32_bf16 v[106:109], v[132:135], v[214:217], v[106:109]
	v_mfma_f32_16x16x32_bf16 v[98:101], v[140:143], v[214:217], v[98:101]
	v_mfma_f32_16x16x32_bf16 v[94:97], v[132:135], v[222:225], v[94:97]
	v_mfma_f32_16x16x32_bf16 v[86:89], v[140:143], v[222:225], v[86:89]
	v_mfma_f32_16x16x32_bf16 v[126:129], v[136:139], v[200:203], v[126:129]
	v_mfma_f32_16x16x32_bf16 v[122:125], v[176:179], v[200:203], v[122:125]
	v_mfma_f32_16x16x32_bf16 v[118:121], v[136:139], v[210:213], v[118:121]
	v_mfma_f32_16x16x32_bf16 v[114:117], v[176:179], v[210:213], v[114:117]
	v_mfma_f32_16x16x32_bf16 v[106:109], v[136:139], v[218:221], v[106:109]
	v_mfma_f32_16x16x32_bf16 v[98:101], v[176:179], v[218:221], v[98:101]
	v_mfma_f32_16x16x32_bf16 v[94:97], v[136:139], v[226:229], v[94:97]
	v_mfma_f32_16x16x32_bf16 v[86:89], v[176:179], v[226:229], v[86:89]
	v_mfma_f32_16x16x32_bf16 v[110:113], v[180:183], v[196:199], v[110:113]
	v_mfma_f32_16x16x32_bf16 v[102:105], v[188:191], v[196:199], v[102:105]
	v_mfma_f32_16x16x32_bf16 v[90:93], v[180:183], v[204:207], v[90:93]
	v_mfma_f32_16x16x32_bf16 v[82:85], v[188:191], v[204:207], v[82:85]
	v_mfma_f32_16x16x32_bf16 v[78:81], v[180:183], v[214:217], v[78:81]
	v_mfma_f32_16x16x32_bf16 v[74:77], v[188:191], v[214:217], v[74:77]
	v_mfma_f32_16x16x32_bf16 v[70:73], v[180:183], v[222:225], v[70:73]
	v_mfma_f32_16x16x32_bf16 v[66:69], v[188:191], v[222:225], v[66:69]
	v_mfma_f32_16x16x32_bf16 v[110:113], v[184:187], v[200:203], v[110:113]
	v_mfma_f32_16x16x32_bf16 v[102:105], v[192:195], v[200:203], v[102:105]
	v_mfma_f32_16x16x32_bf16 v[90:93], v[184:187], v[210:213], v[90:93]
	v_mfma_f32_16x16x32_bf16 v[82:85], v[192:195], v[210:213], v[82:85]
	v_mfma_f32_16x16x32_bf16 v[78:81], v[184:187], v[218:221], v[78:81]
	v_mfma_f32_16x16x32_bf16 v[74:77], v[192:195], v[218:221], v[74:77]
	v_mfma_f32_16x16x32_bf16 v[70:73], v[184:187], v[226:229], v[70:73]
	v_mfma_f32_16x16x32_bf16 v[66:69], v[192:195], v[226:229], v[66:69]
	s_setprio 0
	s_barrier
	v_lshl_add_u64 v[144:145], s[30:31], 0, v[148:149]
	s_add_i32 s30, s52, s26
	s_mov_b32 m0, s30
	ds_read_b128 v[196:199], v175 offset:16384
	ds_read_b128 v[200:203], v175 offset:17408
	ds_read_b128 v[204:207], v175 offset:18432
	ds_read_b128 v[210:213], v175 offset:19456
	ds_read_b128 v[214:217], v175 offset:20480
	ds_read_b128 v[218:221], v175 offset:21504
	ds_read_b128 v[222:225], v175 offset:22528
	ds_read_b128 v[226:229], v175 offset:23552
	global_load_lds_dwordx4 v[144:145], off
	v_lshl_add_u64 v[230:231], v[144:145], 0, s[10:11]
	s_add_i32 m0, s30, 0x2000
	s_add_i32 s30, s53, s26
	global_load_lds_dwordx4 v[230:231], off
	v_lshl_add_u64 v[230:231], v[144:145], 0, s[12:13]
	s_mov_b32 m0, s30
	s_nop 0
	global_load_lds_dwordx4 v[230:231], off
	v_lshl_add_u64 v[230:231], v[144:145], 0, s[14:15]
	s_add_i32 m0, s30, 0x2000
	s_nop 0
	global_load_lds_dwordx4 v[230:231], off
	v_lshl_add_u64 v[230:231], s[28:29], 0, v[150:151]
	s_mov_b32 m0, s27
	v_lshl_add_u64 v[232:233], v[230:231], 0, s[10:11]
	global_load_lds_dwordx4 v[230:231], off
	s_mov_b32 m0, s33
	s_nop 0
	global_load_lds_dwordx4 v[232:233], off
	s_waitcnt vmcnt(8)
	s_waitcnt lgkmcnt(0)
	s_barrier
; #define G8_STA(bufoff, ptr, sg, h) G8_STAGE1(bufoff, (ptr) + (h) * ((sg) ? hA1 : hA0), ((sg) ? voffA1 : voffA0), ((sg) ? r64A1 : r64A0))
; #define G8_STB(bufoff, ptr, sg, h) G8_STAGE1(bufoff, (ptr) + (h) * ((sg) ? hB1 : hB0), ((sg) ? voffB1 : voffB0), ((sg) ? r64B1 : r64B0))
; #define G8_LDA(dst, b, h) do { _Pragma("unroll") for (int m = 0; m < 4; ++m) _Pragma("unroll") for (int k = 0; k < 2; ++k) dst[m][k] = *(const LAS bf16x8*)(lds + G8_SA(b, h) + aoff + m * 2048 + k * 1024); } while (0)
; #define G8_LDB(dst, b, h) do { _Pragma("unroll") for (int n = 0; n < 2; ++n) _Pragma("unroll") for (int k = 0; k < 2; ++k) dst[n][k] = *(const LAS bf16x8*)(lds + G8_SB(b, h) + boff + n * 2048 + k * 1024); } while (0)
; #define G8_MMA(ai, bj, At, Bt) do { __builtin_amdgcn_s_setprio(1); _Pragma("unroll") for (int m = 0; m < 4; ++m) _Pragma("unroll") for (int n = 0; n < 2; ++n) _Pragma("unroll") for (int k = 0; k < 2; ++k) \
;         acc[ai][bj][m][n] = __builtin_amdgcn_mfma_f32_16x16x32_bf16(Bt[n][k], At[m][k], acc[ai][bj][m][n], 0, 0, 0); __builtin_amdgcn_s_setprio(0); } while (0)
; #define G8_WAIT_V(n) asm volatile("s_waitcnt vmcnt(" #n ")" ::: "memory")
; #define G8_WAIT_L(n) asm volatile("s_waitcnt lgkmcnt(" #n ")" ::: "memory")
; #define G8_BAR __builtin_amdgcn_s_barrier()
; #define G8_SCHED __builtin_amdgcn_sched_barrier(0)
; template <class P>
; __device__ __forceinline__ void gemm_phase(LAS unsigned char* lds, const P& p, const int G, const int c) {
;     ...
;             G8_LDA(At, 0, 1); G8_STB(G8_SB(0, 0), b2, sg2, 0); G8_STB(G8_SB(0, 1), b2, sg2, 1); G8_STA(G8_SA(0, 0), a2, sg2, 0);
;             G8_WAIT_V(8); G8_WAIT_L(0); G8_BAR; G8_MMA(1, 0, At, B0); G8_MMA(1, 1, At, B1); G8_BAR; G8_SCHED;
;             G8_LDB(B0, 1, 0); G8_LDB(B1, 1, 1); G8_SCHED; G8_LDA(At, 1, 0); G8_STA(G8_SA(0, 1), a2, sg2, 1);
;             G8_WAIT_V(8); G8_WAIT_L(0); G8_BAR; G8_MMA(0, 0, At, B0); G8_MMA(0, 1, At, B1); G8_BAR; G8_SCHED;
;             G8_LDA(At, 1, 1); G8_STB(G8_SB(1, 0), b3, sg2, 0); G8_STB(G8_SB(1, 1), b3, sg2, 1); G8_STA(G8_SA(1, 0), a3, sg2, 0);
	s_setprio 1
	s_waitcnt lgkmcnt(0)
	v_mfma_f32_16x16x32_bf16 v[62:65], v[132:135], v[196:199], v[62:65]
	v_mfma_f32_16x16x32_bf16 v[58:61], v[140:143], v[196:199], v[58:61]
	v_mfma_f32_16x16x32_bf16 v[54:57], v[132:135], v[204:207], v[54:57]
	v_mfma_f32_16x16x32_bf16 v[50:53], v[140:143], v[204:207], v[50:53]
	v_mfma_f32_16x16x32_bf16 v[46:49], v[132:135], v[214:217], v[46:49]
	v_mfma_f32_16x16x32_bf16 v[38:41], v[140:143], v[214:217], v[38:41]
	v_mfma_f32_16x16x32_bf16 v[30:33], v[132:135], v[222:225], v[30:33]
	v_mfma_f32_16x16x32_bf16 v[22:25], v[140:143], v[222:225], v[22:25]
	v_mfma_f32_16x16x32_bf16 v[62:65], v[136:139], v[200:203], v[62:65]
	v_mfma_f32_16x16x32_bf16 v[58:61], v[176:179], v[200:203], v[58:61]
	v_mfma_f32_16x16x32_bf16 v[54:57], v[136:139], v[210:213], v[54:57]
	v_mfma_f32_16x16x32_bf16 v[50:53], v[176:179], v[210:213], v[50:53]
	v_mfma_f32_16x16x32_bf16 v[46:49], v[136:139], v[218:221], v[46:49]
	v_mfma_f32_16x16x32_bf16 v[38:41], v[176:179], v[218:221], v[38:41]
	v_mfma_f32_16x16x32_bf16 v[30:33], v[136:139], v[226:229], v[30:33]
	v_mfma_f32_16x16x32_bf16 v[22:25], v[176:179], v[226:229], v[22:25]
	v_mfma_f32_16x16x32_bf16 v[42:45], v[180:183], v[196:199], v[42:45]
	v_mfma_f32_16x16x32_bf16 v[34:37], v[188:191], v[196:199], v[34:37]
	v_mfma_f32_16x16x32_bf16 v[26:29], v[180:183], v[204:207], v[26:29]
	v_mfma_f32_16x16x32_bf16 v[18:21], v[188:191], v[204:207], v[18:21]
	v_mfma_f32_16x16x32_bf16 v[14:17], v[180:183], v[214:217], v[14:17]
	v_mfma_f32_16x16x32_bf16 v[10:13], v[188:191], v[214:217], v[10:13]
	v_mfma_f32_16x16x32_bf16 v[6:9], v[180:183], v[222:225], v[6:9]
	v_mfma_f32_16x16x32_bf16 v[2:5], v[188:191], v[222:225], v[2:5]
	v_mfma_f32_16x16x32_bf16 v[42:45], v[184:187], v[200:203], v[42:45]
	v_mfma_f32_16x16x32_bf16 v[34:37], v[192:195], v[200:203], v[34:37]
	v_mfma_f32_16x16x32_bf16 v[26:29], v[184:187], v[210:213], v[26:29]
	v_mfma_f32_16x16x32_bf16 v[18:21], v[192:195], v[210:213], v[18:21]
	v_mfma_f32_16x16x32_bf16 v[14:17], v[184:187], v[218:221], v[14:17]
	v_mfma_f32_16x16x32_bf16 v[10:13], v[192:195], v[218:221], v[10:13]
	v_mfma_f32_16x16x32_bf16 v[6:9], v[184:187], v[226:229], v[6:9]
	v_mfma_f32_16x16x32_bf16 v[2:5], v[192:195], v[226:229], v[2:5]
	s_setprio 0
	s_barrier
	s_add_i32 s28, 0, 0x18000
	s_add_i32 s29, 0, 0x1c000
	v_add_u32_e32 v176, s28, v1
	v_add_u32_e32 v192, s29, v1
	ds_read_b128 v[132:135], v176
	ds_read_b128 v[136:139], v176 offset:1024
	ds_read_b128 v[140:143], v176 offset:2048
	ds_read_b128 v[176:179], v176 offset:3072
	ds_read_b128 v[180:183], v192
	ds_read_b128 v[184:187], v192 offset:1024
	ds_read_b128 v[188:191], v192 offset:2048
	ds_read_b128 v[192:195], v192 offset:3072
	s_mov_b32 m0, s34
	v_lshl_add_u64 v[232:233], v[230:231], 0, s[12:13]
	ds_read_b128 v[196:199], v175 offset:32768
	ds_read_b128 v[200:203], v175 offset:33792
	ds_read_b128 v[204:207], v175 offset:34816
	ds_read_b128 v[210:213], v175 offset:35840
	ds_read_b128 v[214:217], v175 offset:36864
	ds_read_b128 v[218:221], v175 offset:37888
	ds_read_b128 v[222:225], v175 offset:38912
	ds_read_b128 v[226:229], v175 offset:39936
	global_load_lds_dwordx4 v[232:233], off
	v_lshl_add_u64 v[232:233], v[230:231], 0, s[14:15]
	s_mov_b32 m0, s35
	s_nop 0
	global_load_lds_dwordx4 v[232:233], off
	s_waitcnt vmcnt(8)
	s_waitcnt lgkmcnt(0)
	s_barrier
	s_setprio 1
	s_waitcnt lgkmcnt(0)
	v_mfma_f32_16x16x32_bf16 v[126:129], v[132:135], v[196:199], v[126:129]
	v_mfma_f32_16x16x32_bf16 v[122:125], v[140:143], v[196:199], v[122:125]
	v_mfma_f32_16x16x32_bf16 v[118:121], v[132:135], v[204:207], v[118:121]
	v_mfma_f32_16x16x32_bf16 v[114:117], v[140:143], v[204:207], v[114:117]
	v_mfma_f32_16x16x32_bf16 v[106:109], v[132:135], v[214:217], v[106:109]
	v_mfma_f32_16x16x32_bf16 v[98:101], v[140:143], v[214:217], v[98:101]
	v_mfma_f32_16x16x32_bf16 v[94:97], v[132:135], v[222:225], v[94:97]
	v_mfma_f32_16x16x32_bf16 v[86:89], v[140:143], v[222:225], v[86:89]
	v_mfma_f32_16x16x32_bf16 v[126:129], v[136:139], v[200:203], v[126:129]
	v_mfma_f32_16x16x32_bf16 v[122:125], v[176:179], v[200:203], v[122:125]
	v_mfma_f32_16x16x32_bf16 v[118:121], v[136:139], v[210:213], v[118:121]
	v_mfma_f32_16x16x32_bf16 v[114:117], v[176:179], v[210:213], v[114:117]
	v_mfma_f32_16x16x32_bf16 v[106:109], v[136:139], v[218:221], v[106:109]
	v_mfma_f32_16x16x32_bf16 v[98:101], v[176:179], v[218:221], v[98:101]
	v_mfma_f32_16x16x32_bf16 v[94:97], v[136:139], v[226:229], v[94:97]
	v_mfma_f32_16x16x32_bf16 v[86:89], v[176:179], v[226:229], v[86:89]
	v_mfma_f32_16x16x32_bf16 v[110:113], v[180:183], v[196:199], v[110:113]
	v_mfma_f32_16x16x32_bf16 v[102:105], v[188:191], v[196:199], v[102:105]
	v_mfma_f32_16x16x32_bf16 v[90:93], v[180:183], v[204:207], v[90:93]
	v_mfma_f32_16x16x32_bf16 v[82:85], v[188:191], v[204:207], v[82:85]
	v_mfma_f32_16x16x32_bf16 v[78:81], v[180:183], v[214:217], v[78:81]
	v_mfma_f32_16x16x32_bf16 v[74:77], v[188:191], v[214:217], v[74:77]
	v_mfma_f32_16x16x32_bf16 v[70:73], v[180:183], v[222:225], v[70:73]
	v_mfma_f32_16x16x32_bf16 v[66:69], v[188:191], v[222:225], v[66:69]
	v_mfma_f32_16x16x32_bf16 v[110:113], v[184:187], v[200:203], v[110:113]
	v_mfma_f32_16x16x32_bf16 v[102:105], v[192:195], v[200:203], v[102:105]
	v_mfma_f32_16x16x32_bf16 v[90:93], v[184:187], v[210:213], v[90:93]
	v_mfma_f32_16x16x32_bf16 v[82:85], v[192:195], v[210:213], v[82:85]
	v_mfma_f32_16x16x32_bf16 v[78:81], v[184:187], v[218:221], v[78:81]
	v_mfma_f32_16x16x32_bf16 v[74:77], v[192:195], v[218:221], v[74:77]
	v_mfma_f32_16x16x32_bf16 v[70:73], v[184:187], v[226:229], v[70:73]
	v_mfma_f32_16x16x32_bf16 v[66:69], v[192:195], v[226:229], v[66:69]
	s_setprio 0
	s_barrier
; #define G8_STA(bufoff, ptr, sg, h) G8_STAGE1(bufoff, (ptr) + (h) * ((sg) ? hA1 : hA0), ((sg) ? voffA1 : voffA0), ((sg) ? r64A1 : r64A0))
; #define G8_STB(bufoff, ptr, sg, h) G8_STAGE1(bufoff, (ptr) + (h) * ((sg) ? hB1 : hB0), ((sg) ? voffB1 : voffB0), ((sg) ? r64B1 : r64B0))
; #define G8_LDA(dst, b, h) do { _Pragma("unroll") for (int m = 0; m < 4; ++m) _Pragma("unroll") for (int k = 0; k < 2; ++k) dst[m][k] = *(const LAS bf16x8*)(lds + G8_SA(b, h) + aoff + m * 2048 + k * 1024); } while (0)
; #define G8_MMA(ai, bj, At, Bt) do { __builtin_amdgcn_s_setprio(1); _Pragma("unroll") for (int m = 0; m < 4; ++m) _Pragma("unroll") for (int n = 0; n < 2; ++n) _Pragma("unroll") for (int k = 0; k < 2; ++k) \
;         acc[ai][bj][m][n] = __builtin_amdgcn_mfma_f32_16x16x32_bf16(Bt[n][k], At[m][k], acc[ai][bj][m][n], 0, 0, 0); __builtin_amdgcn_s_setprio(0); } while (0)
; #define G8_WAIT_V(n) asm volatile("s_waitcnt vmcnt(" #n ")" ::: "memory")
; #define G8_WAIT_L(n) asm volatile("s_waitcnt lgkmcnt(" #n ")" ::: "memory")
; #define G8_BAR __builtin_amdgcn_s_barrier()
; #define G8_SCHED __builtin_amdgcn_sched_barrier(0)
; template <class P>
; __device__ __forceinline__ void gemm_phase(LAS unsigned char* lds, const P& p, const int G, const int c) {
;     ...
;             G8_LDA(At, 1, 1); G8_STB(G8_SB(1, 0), b3, sg2, 0); G8_STB(G8_SB(1, 1), b3, sg2, 1); G8_STA(G8_SA(1, 0), a3, sg2, 0);
;             G8_WAIT_V(8); G8_WAIT_L(0); G8_BAR; G8_MMA(1, 0, At, B0); G8_MMA(1, 1, At, B1); G8_BAR; G8_SCHED;
;         }
	s_add_i32 s28, s28, s26
	v_lshl_add_u64 v[232:233], v[144:145], 0, s[20:21]
	s_mov_b32 m0, s28
	ds_read_b128 v[196:199], v175 offset:49152
	ds_read_b128 v[200:203], v175 offset:50176
	ds_read_b128 v[204:207], v175 offset:51200
	ds_read_b128 v[210:213], v175 offset:52224
	ds_read_b128 v[214:217], v175 offset:53248
	ds_read_b128 v[218:221], v175 offset:54272
	ds_read_b128 v[222:225], v175 offset:55296
	ds_read_b128 v[226:229], v175 offset:56320
	global_load_lds_dwordx4 v[232:233], off
	v_lshl_add_u64 v[232:233], v[144:145], 0, s[22:23]
	s_add_i32 m0, s28, 0x2000
	s_add_i32 s28, s29, s26
	global_load_lds_dwordx4 v[232:233], off
	v_lshl_add_u64 v[232:233], v[144:145], 0, s[40:41]
	s_mov_b32 m0, s28
	v_lshl_add_u64 v[144:145], v[144:145], 0, s[42:43]
	global_load_lds_dwordx4 v[232:233], off
	s_add_i32 m0, s28, 0x2000
	s_nop 0
	global_load_lds_dwordx4 v[144:145], off
	v_lshl_add_u64 v[144:145], v[230:231], 0, s[36:37]
	s_mov_b32 m0, s50
	s_nop 0
	global_load_lds_dwordx4 v[144:145], off
	v_lshl_add_u64 v[144:145], v[230:231], 0, s[38:39]
	s_mov_b32 m0, s51
	s_nop 0
	global_load_lds_dwordx4 v[144:145], off
	s_waitcnt vmcnt(8)
	s_waitcnt lgkmcnt(0)
	s_barrier
	s_setprio 1
	s_waitcnt lgkmcnt(0)
	v_mfma_f32_16x16x32_bf16 v[62:65], v[132:135], v[196:199], v[62:65]
	v_mfma_f32_16x16x32_bf16 v[58:61], v[140:143], v[196:199], v[58:61]
	v_mfma_f32_16x16x32_bf16 v[54:57], v[132:135], v[204:207], v[54:57]
	v_mfma_f32_16x16x32_bf16 v[50:53], v[140:143], v[204:207], v[50:53]
	v_mfma_f32_16x16x32_bf16 v[46:49], v[132:135], v[214:217], v[46:49]
	v_mfma_f32_16x16x32_bf16 v[38:41], v[140:143], v[214:217], v[38:41]
	v_mfma_f32_16x16x32_bf16 v[30:33], v[132:135], v[222:225], v[30:33]
	v_mfma_f32_16x16x32_bf16 v[22:25], v[140:143], v[222:225], v[22:25]
	v_mfma_f32_16x16x32_bf16 v[62:65], v[136:139], v[200:203], v[62:65]
	v_mfma_f32_16x16x32_bf16 v[58:61], v[176:179], v[200:203], v[58:61]
	v_mfma_f32_16x16x32_bf16 v[54:57], v[136:139], v[210:213], v[54:57]
	v_mfma_f32_16x16x32_bf16 v[50:53], v[176:179], v[210:213], v[50:53]
	v_mfma_f32_16x16x32_bf16 v[46:49], v[136:139], v[218:221], v[46:49]
	v_mfma_f32_16x16x32_bf16 v[38:41], v[176:179], v[218:221], v[38:41]
	v_mfma_f32_16x16x32_bf16 v[30:33], v[136:139], v[226:229], v[30:33]
	v_mfma_f32_16x16x32_bf16 v[22:25], v[176:179], v[226:229], v[22:25]
	v_mfma_f32_16x16x32_bf16 v[42:45], v[180:183], v[196:199], v[42:45]
	v_mfma_f32_16x16x32_bf16 v[34:37], v[188:191], v[196:199], v[34:37]
	v_mfma_f32_16x16x32_bf16 v[26:29], v[180:183], v[204:207], v[26:29]
	v_mfma_f32_16x16x32_bf16 v[18:21], v[188:191], v[204:207], v[18:21]
	v_mfma_f32_16x16x32_bf16 v[14:17], v[180:183], v[214:217], v[14:17]
	v_mfma_f32_16x16x32_bf16 v[10:13], v[188:191], v[214:217], v[10:13]
	v_mfma_f32_16x16x32_bf16 v[6:9], v[180:183], v[222:225], v[6:9]
	v_mfma_f32_16x16x32_bf16 v[2:5], v[188:191], v[222:225], v[2:5]
	v_mfma_f32_16x16x32_bf16 v[42:45], v[184:187], v[200:203], v[42:45]
	v_mfma_f32_16x16x32_bf16 v[34:37], v[192:195], v[200:203], v[34:37]
	v_mfma_f32_16x16x32_bf16 v[26:29], v[184:187], v[210:213], v[26:29]
	v_mfma_f32_16x16x32_bf16 v[18:21], v[192:195], v[210:213], v[18:21]
	v_mfma_f32_16x16x32_bf16 v[14:17], v[184:187], v[218:221], v[14:17]
	v_mfma_f32_16x16x32_bf16 v[10:13], v[192:195], v[218:221], v[10:13]
	v_mfma_f32_16x16x32_bf16 v[6:9], v[184:187], v[226:229], v[6:9]
	v_mfma_f32_16x16x32_bf16 v[2:5], v[192:195], v[226:229], v[2:5]
	s_setprio 0
	s_barrier
	s_add_u32 s19, s19, 0x40000
	s_addc_u32 s49, s49, 0
	s_add_u32 s76, s76, 0x820000
	s_addc_u32 s77, s77, 0
	s_cmp_ge_u32 s57, s5
	s_cbranch_scc1 .LBB0_282

; #define G8_STA(bufoff, ptr, sg, h) G8_STAGE1(bufoff, (ptr) + (h) * ((sg) ? hA1 : hA0), ((sg) ? voffA1 : voffA0), ((sg) ? r64A1 : r64A0))
; #define G8_STB(bufoff, ptr, sg, h) G8_STAGE1(bufoff, (ptr) + (h) * ((sg) ? hB1 : hB0), ((sg) ? voffB1 : voffB0), ((sg) ? r64B1 : r64B0))
; #define G8_LDA(dst, b, h) do { _Pragma("unroll") for (int m = 0; m < 4; ++m) _Pragma("unroll") for (int k = 0; k < 2; ++k) dst[m][k] = *(const LAS bf16x8*)(lds + G8_SA(b, h) + aoff + m * 2048 + k * 1024); } while (0)
; #define G8_LDB(dst, b, h) do { _Pragma("unroll") for (int n = 0; n < 2; ++n) _Pragma("unroll") for (int k = 0; k < 2; ++k) dst[n][k] = *(const LAS bf16x8*)(lds + G8_SB(b, h) + boff + n * 2048 + k * 1024); } while (0)
; #define G8_MMA(ai, bj, At, Bt) do { __builtin_amdgcn_s_setprio(1); _Pragma("unroll") for (int m = 0; m < 4; ++m) _Pragma("unroll") for (int n = 0; n < 2; ++n) _Pragma("unroll") for (int k = 0; k < 2; ++k) \
;         acc[ai][bj][m][n] = __builtin_amdgcn_mfma_f32_16x16x32_bf16(Bt[n][k], At[m][k], acc[ai][bj][m][n], 0, 0, 0); __builtin_amdgcn_s_setprio(0); } while (0)
; #define G8_BAR __builtin_amdgcn_s_barrier()
; template <class P>
; __device__ __forceinline__ void gemm_phase(LAS unsigned char* lds, const P& p, const int G, const int c) {
;     ...
;         for (int t = 0; t < nt; t += 2) {
;             const bool last = (t == nt - 2);
;             const bool sg1 = (NS > 1) && (t + 1 >= nt0);
;             const bool sg2 = (NS > 1) && !last && (t + 2 >= nt0);
;             const char* a1 = sg1 ? cA1 + (long)(t + 1 - nt0) * ksA1 : cA0 + (long)(t + 1) * ksA0;
;             const char* a2 = last ? nA0 : (sg2 ? cA1 + (long)(t + 2 - nt0) * ksA1 : cA0 + (long)(t + 2) * ksA0);
;             const char* b2 = last ? nB0 : (sg2 ? cB1 + (long)(t + 2 - nt0) * ksB1 : cB0 + (long)(t + 2) * ksB0);
;             const char* a3 = a2 + (sg2 ? ksA1 : ksA0); const char* b3 = b2 + (sg2 ? ksB1 : ksB0);
;             G8_LDB(B0, 0, 0); G8_LDB(B1, 0, 1); G8_SCHED; G8_LDA(At, 0, 0); G8_STA(G8_SA(1, 1), a1, sg1, 1);
;             G8_WAIT_V(8); G8_WAIT_L(0); G8_BAR; G8_MMA(0, 0, At, B0); G8_MMA(0, 1, At, B1); G8_BAR; G8_SCHED;
;             G8_LDA(At, 0, 1); G8_STB(G8_SB(0, 0), b2, sg2, 0); G8_STB(G8_SB(0, 1), b2, sg2, 1); G8_STA(G8_SA(0, 0), a2, sg2, 0);
;             G8_WAIT_V(8); G8_WAIT_L(0); G8_BAR; G8_MMA(1, 0, At, B0); G8_MMA(1, 1, At, B1); G8_BAR; G8_SCHED;
.LBB0_410:
	v_add_u32_e32 v130, s65, v137
	ds_read_b128 v[142:145], v130
	ds_read_b128 v[146:149], v130 offset:1024
	ds_read_b128 v[162:165], v130 offset:2048
	ds_read_b128 v[166:169], v130 offset:3072
	v_add_u32_e32 v130, s66, v137
	ds_read_b128 v[170:173], v130
	ds_read_b128 v[174:177], v130 offset:1024
	ds_read_b128 v[178:181], v130 offset:2048
	ds_read_b128 v[182:185], v130 offset:3072
	s_add_i32 s74, s74, 2
	s_and_b64 s[30:31], exec, s[30:31]
	s_cselect_b32 s31, s7, s53
	s_cselect_b32 s30, s18, s19
	v_lshl_add_u64 v[206:207], v[140:141], 0, s[70:71]
	v_lshl_add_u64 v[222:223], v[206:207], 0, s[76:77]
	s_add_i32 m0, s27, 0xc000
	ds_read_b128 v[186:189], v158
	ds_read_b128 v[190:193], v158 offset:1024
	ds_read_b128 v[194:197], v158 offset:2048
	ds_read_b128 v[198:201], v158 offset:3072
	ds_read_b128 v[202:205], v158 offset:4096
	ds_read_b128 v[210:213], v158 offset:5120
	ds_read_b128 v[214:217], v158 offset:6144
	ds_read_b128 v[218:221], v158 offset:7168
	global_load_lds_dwordx4 v[222:223], off
	v_lshl_add_u64 v[206:207], v[206:207], 0, s[48:49]
	s_add_i32 m0, s27, 0xe000
	s_nop 0
	global_load_lds_dwordx4 v[206:207], off
	s_waitcnt vmcnt(8)
	s_waitcnt lgkmcnt(0)
	s_barrier
	s_setprio 1
	s_waitcnt lgkmcnt(0)
	v_mfma_f32_16x16x32_bf16 v[126:129], v[142:145], v[186:189], v[126:129]
	v_mfma_f32_16x16x32_bf16 v[122:125], v[162:165], v[186:189], v[122:125]
	v_mfma_f32_16x16x32_bf16 v[110:113], v[142:145], v[194:197], v[110:113]
	v_mfma_f32_16x16x32_bf16 v[106:109], v[162:165], v[194:197], v[106:109]
	v_mfma_f32_16x16x32_bf16 v[94:97], v[142:145], v[202:205], v[94:97]
	v_mfma_f32_16x16x32_bf16 v[90:93], v[162:165], v[202:205], v[90:93]
	v_mfma_f32_16x16x32_bf16 v[78:81], v[142:145], v[214:217], v[78:81]
	v_mfma_f32_16x16x32_bf16 v[74:77], v[162:165], v[214:217], v[74:77]
	v_mfma_f32_16x16x32_bf16 v[126:129], v[146:149], v[190:193], v[126:129]
	v_mfma_f32_16x16x32_bf16 v[122:125], v[166:169], v[190:193], v[122:125]
	v_mfma_f32_16x16x32_bf16 v[110:113], v[146:149], v[198:201], v[110:113]
	v_mfma_f32_16x16x32_bf16 v[106:109], v[166:169], v[198:201], v[106:109]
	v_mfma_f32_16x16x32_bf16 v[94:97], v[146:149], v[210:213], v[94:97]
	v_mfma_f32_16x16x32_bf16 v[90:93], v[166:169], v[210:213], v[90:93]
	v_mfma_f32_16x16x32_bf16 v[78:81], v[146:149], v[218:221], v[78:81]
	v_mfma_f32_16x16x32_bf16 v[74:77], v[166:169], v[218:221], v[74:77]
	v_mfma_f32_16x16x32_bf16 v[118:121], v[170:173], v[186:189], v[118:121]
	v_mfma_f32_16x16x32_bf16 v[114:117], v[178:181], v[186:189], v[114:117]
	v_mfma_f32_16x16x32_bf16 v[102:105], v[170:173], v[194:197], v[102:105]
	v_mfma_f32_16x16x32_bf16 v[98:101], v[178:181], v[194:197], v[98:101]
	v_mfma_f32_16x16x32_bf16 v[86:89], v[170:173], v[202:205], v[86:89]
	v_mfma_f32_16x16x32_bf16 v[82:85], v[178:181], v[202:205], v[82:85]
	v_mfma_f32_16x16x32_bf16 v[70:73], v[170:173], v[214:217], v[70:73]
	v_mfma_f32_16x16x32_bf16 v[66:69], v[178:181], v[214:217], v[66:69]
	v_mfma_f32_16x16x32_bf16 v[118:121], v[174:177], v[190:193], v[118:121]
	v_mfma_f32_16x16x32_bf16 v[114:117], v[182:185], v[190:193], v[114:117]
	v_mfma_f32_16x16x32_bf16 v[102:105], v[174:177], v[198:201], v[102:105]
	v_mfma_f32_16x16x32_bf16 v[98:101], v[182:185], v[198:201], v[98:101]
	v_mfma_f32_16x16x32_bf16 v[86:89], v[174:177], v[210:213], v[86:89]
	v_mfma_f32_16x16x32_bf16 v[82:85], v[182:185], v[210:213], v[82:85]
	v_mfma_f32_16x16x32_bf16 v[70:73], v[174:177], v[218:221], v[70:73]
	v_mfma_f32_16x16x32_bf16 v[66:69], v[182:185], v[218:221], v[66:69]
	s_setprio 0
	s_barrier
	v_lshl_add_u64 v[206:207], s[30:31], 0, v[132:133]
	s_add_i32 s30, s65, s26
	s_mov_b32 m0, s30
	ds_read_b128 v[186:189], v158 offset:16384
	ds_read_b128 v[190:193], v158 offset:17408
	ds_read_b128 v[194:197], v158 offset:18432
	ds_read_b128 v[198:201], v158 offset:19456
	ds_read_b128 v[202:205], v158 offset:20480
	ds_read_b128 v[210:213], v158 offset:21504
	ds_read_b128 v[214:217], v158 offset:22528
	ds_read_b128 v[218:221], v158 offset:23552
	global_load_lds_dwordx4 v[206:207], off
	v_lshl_add_u64 v[222:223], v[206:207], 0, s[8:9]
	s_add_i32 m0, s30, 0x2000
	s_add_i32 s30, s66, s26
	global_load_lds_dwordx4 v[222:223], off
	v_lshl_add_u64 v[222:223], v[206:207], 0, s[10:11]
	s_mov_b32 m0, s30
	s_nop 0
	global_load_lds_dwordx4 v[222:223], off
	v_lshl_add_u64 v[222:223], v[206:207], 0, s[12:13]
	s_add_i32 m0, s30, 0x2000
	s_nop 0
	global_load_lds_dwordx4 v[222:223], off
	v_lshl_add_u64 v[222:223], s[28:29], 0, v[134:135]
	s_mov_b32 m0, s27
	v_lshl_add_u64 v[224:225], v[222:223], 0, s[8:9]
	global_load_lds_dwordx4 v[222:223], off
	s_mov_b32 m0, s33
	s_nop 0
	global_load_lds_dwordx4 v[224:225], off
	s_waitcnt vmcnt(8)
	s_waitcnt lgkmcnt(0)
	s_barrier
; #define G8_STA(bufoff, ptr, sg, h) G8_STAGE1(bufoff, (ptr) + (h) * ((sg) ? hA1 : hA0), ((sg) ? voffA1 : voffA0), ((sg) ? r64A1 : r64A0))
; #define G8_STB(bufoff, ptr, sg, h) G8_STAGE1(bufoff, (ptr) + (h) * ((sg) ? hB1 : hB0), ((sg) ? voffB1 : voffB0), ((sg) ? r64B1 : r64B0))
; #define G8_LDA(dst, b, h) do { _Pragma("unroll") for (int m = 0; m < 4; ++m) _Pragma("unroll") for (int k = 0; k < 2; ++k) dst[m][k] = *(const LAS bf16x8*)(lds + G8_SA(b, h) + aoff + m * 2048 + k * 1024); } while (0)
; #define G8_LDB(dst, b, h) do { _Pragma("unroll") for (int n = 0; n < 2; ++n) _Pragma("unroll") for (int k = 0; k < 2; ++k) dst[n][k] = *(const LAS bf16x8*)(lds + G8_SB(b, h) + boff + n * 2048 + k * 1024); } while (0)
; #define G8_MMA(ai, bj, At, Bt) do { __builtin_amdgcn_s_setprio(1); _Pragma("unroll") for (int m = 0; m < 4; ++m) _Pragma("unroll") for (int n = 0; n < 2; ++n) _Pragma("unroll") for (int k = 0; k < 2; ++k) \
;         acc[ai][bj][m][n] = __builtin_amdgcn_mfma_f32_16x16x32_bf16(Bt[n][k], At[m][k], acc[ai][bj][m][n], 0, 0, 0); __builtin_amdgcn_s_setprio(0); } while (0)
; #define G8_WAIT_V(n) asm volatile("s_waitcnt vmcnt(" #n ")" ::: "memory")
; #define G8_WAIT_L(n) asm volatile("s_waitcnt lgkmcnt(" #n ")" ::: "memory")
; #define G8_BAR __builtin_amdgcn_s_barrier()
; #define G8_SCHED __builtin_amdgcn_sched_barrier(0)
; template <class P>
; __device__ __forceinline__ void gemm_phase(LAS unsigned char* lds, const P& p, const int G, const int c) {
;     ...
;             G8_LDA(At, 0, 1); G8_STB(G8_SB(0, 0), b2, sg2, 0); G8_STB(G8_SB(0, 1), b2, sg2, 1); G8_STA(G8_SA(0, 0), a2, sg2, 0);
;             G8_WAIT_V(8); G8_WAIT_L(0); G8_BAR; G8_MMA(1, 0, At, B0); G8_MMA(1, 1, At, B1); G8_BAR; G8_SCHED;
;             G8_LDB(B0, 1, 0); G8_LDB(B1, 1, 1); G8_SCHED; G8_LDA(At, 1, 0); G8_STA(G8_SA(0, 1), a2, sg2, 1);
;             G8_WAIT_V(8); G8_WAIT_L(0); G8_BAR; G8_MMA(0, 0, At, B0); G8_MMA(0, 1, At, B1); G8_BAR; G8_SCHED;
;             G8_LDA(At, 1, 1); G8_STB(G8_SB(1, 0), b3, sg2, 0); G8_STB(G8_SB(1, 1), b3, sg2, 1); G8_STA(G8_SA(1, 0), a3, sg2, 0);
	s_setprio 1
	s_waitcnt lgkmcnt(0)
	v_mfma_f32_16x16x32_bf16 v[62:65], v[142:145], v[186:189], v[62:65]
	v_mfma_f32_16x16x32_bf16 v[58:61], v[162:165], v[186:189], v[58:61]
	v_mfma_f32_16x16x32_bf16 v[46:49], v[142:145], v[194:197], v[46:49]
	v_mfma_f32_16x16x32_bf16 v[42:45], v[162:165], v[194:197], v[42:45]
	v_mfma_f32_16x16x32_bf16 v[30:33], v[142:145], v[202:205], v[30:33]
	v_mfma_f32_16x16x32_bf16 v[26:29], v[162:165], v[202:205], v[26:29]
	v_mfma_f32_16x16x32_bf16 v[14:17], v[142:145], v[214:217], v[14:17]
	v_mfma_f32_16x16x32_bf16 v[10:13], v[162:165], v[214:217], v[10:13]
	v_mfma_f32_16x16x32_bf16 v[62:65], v[146:149], v[190:193], v[62:65]
	v_mfma_f32_16x16x32_bf16 v[58:61], v[166:169], v[190:193], v[58:61]
	v_mfma_f32_16x16x32_bf16 v[46:49], v[146:149], v[198:201], v[46:49]
	v_mfma_f32_16x16x32_bf16 v[42:45], v[166:169], v[198:201], v[42:45]
	v_mfma_f32_16x16x32_bf16 v[30:33], v[146:149], v[210:213], v[30:33]
	v_mfma_f32_16x16x32_bf16 v[26:29], v[166:169], v[210:213], v[26:29]
	v_mfma_f32_16x16x32_bf16 v[14:17], v[146:149], v[218:221], v[14:17]
	v_mfma_f32_16x16x32_bf16 v[10:13], v[166:169], v[218:221], v[10:13]
	v_mfma_f32_16x16x32_bf16 v[54:57], v[170:173], v[186:189], v[54:57]
	v_mfma_f32_16x16x32_bf16 v[50:53], v[178:181], v[186:189], v[50:53]
	v_mfma_f32_16x16x32_bf16 v[38:41], v[170:173], v[194:197], v[38:41]
	v_mfma_f32_16x16x32_bf16 v[34:37], v[178:181], v[194:197], v[34:37]
	v_mfma_f32_16x16x32_bf16 v[22:25], v[170:173], v[202:205], v[22:25]
	v_mfma_f32_16x16x32_bf16 v[18:21], v[178:181], v[202:205], v[18:21]
	v_mfma_f32_16x16x32_bf16 v[6:9], v[170:173], v[214:217], v[6:9]
	v_mfma_f32_16x16x32_bf16 v[2:5], v[178:181], v[214:217], v[2:5]
	v_mfma_f32_16x16x32_bf16 v[54:57], v[174:177], v[190:193], v[54:57]
	v_mfma_f32_16x16x32_bf16 v[50:53], v[182:185], v[190:193], v[50:53]
	v_mfma_f32_16x16x32_bf16 v[38:41], v[174:177], v[198:201], v[38:41]
	v_mfma_f32_16x16x32_bf16 v[34:37], v[182:185], v[198:201], v[34:37]
	v_mfma_f32_16x16x32_bf16 v[22:25], v[174:177], v[210:213], v[22:25]
	v_mfma_f32_16x16x32_bf16 v[18:21], v[182:185], v[210:213], v[18:21]
	v_mfma_f32_16x16x32_bf16 v[6:9], v[174:177], v[218:221], v[6:9]
	v_mfma_f32_16x16x32_bf16 v[2:5], v[182:185], v[218:221], v[2:5]
	s_setprio 0
	s_barrier
	s_add_i32 s28, 0, 0x18000
	v_add_u32_e32 v130, s28, v137
	s_add_i32 s29, 0, 0x1c000
	ds_read_b128 v[142:145], v130
	ds_read_b128 v[146:149], v130 offset:1024
	ds_read_b128 v[162:165], v130 offset:2048
	ds_read_b128 v[166:169], v130 offset:3072
	v_add_u32_e32 v130, s29, v137
	ds_read_b128 v[170:173], v130
	ds_read_b128 v[174:177], v130 offset:1024
	ds_read_b128 v[178:181], v130 offset:2048
	ds_read_b128 v[182:185], v130 offset:3072
	s_mov_b32 m0, s34
	v_lshl_add_u64 v[224:225], v[222:223], 0, s[10:11]
	ds_read_b128 v[186:189], v158 offset:32768
	ds_read_b128 v[190:193], v158 offset:33792
	ds_read_b128 v[194:197], v158 offset:34816
	ds_read_b128 v[198:201], v158 offset:35840
	ds_read_b128 v[202:205], v158 offset:36864
	ds_read_b128 v[210:213], v158 offset:37888
	ds_read_b128 v[214:217], v158 offset:38912
	ds_read_b128 v[218:221], v158 offset:39936
	global_load_lds_dwordx4 v[224:225], off
	v_lshl_add_u64 v[224:225], v[222:223], 0, s[12:13]
	s_mov_b32 m0, s35
	s_nop 0
	global_load_lds_dwordx4 v[224:225], off
	s_waitcnt vmcnt(8)
	s_waitcnt lgkmcnt(0)
	s_barrier
	s_setprio 1
	s_waitcnt lgkmcnt(0)
	v_mfma_f32_16x16x32_bf16 v[126:129], v[142:145], v[186:189], v[126:129]
	v_mfma_f32_16x16x32_bf16 v[122:125], v[162:165], v[186:189], v[122:125]
	v_mfma_f32_16x16x32_bf16 v[110:113], v[142:145], v[194:197], v[110:113]
	v_mfma_f32_16x16x32_bf16 v[106:109], v[162:165], v[194:197], v[106:109]
	v_mfma_f32_16x16x32_bf16 v[94:97], v[142:145], v[202:205], v[94:97]
	v_mfma_f32_16x16x32_bf16 v[90:93], v[162:165], v[202:205], v[90:93]
	v_mfma_f32_16x16x32_bf16 v[78:81], v[142:145], v[214:217], v[78:81]
	v_mfma_f32_16x16x32_bf16 v[74:77], v[162:165], v[214:217], v[74:77]
	v_mfma_f32_16x16x32_bf16 v[126:129], v[146:149], v[190:193], v[126:129]
	v_mfma_f32_16x16x32_bf16 v[122:125], v[166:169], v[190:193], v[122:125]
	v_mfma_f32_16x16x32_bf16 v[110:113], v[146:149], v[198:201], v[110:113]
	v_mfma_f32_16x16x32_bf16 v[106:109], v[166:169], v[198:201], v[106:109]
	v_mfma_f32_16x16x32_bf16 v[94:97], v[146:149], v[210:213], v[94:97]
	v_mfma_f32_16x16x32_bf16 v[90:93], v[166:169], v[210:213], v[90:93]
	v_mfma_f32_16x16x32_bf16 v[78:81], v[146:149], v[218:221], v[78:81]
	v_mfma_f32_16x16x32_bf16 v[74:77], v[166:169], v[218:221], v[74:77]
	v_mfma_f32_16x16x32_bf16 v[118:121], v[170:173], v[186:189], v[118:121]
	v_mfma_f32_16x16x32_bf16 v[114:117], v[178:181], v[186:189], v[114:117]
	v_mfma_f32_16x16x32_bf16 v[102:105], v[170:173], v[194:197], v[102:105]
	v_mfma_f32_16x16x32_bf16 v[98:101], v[178:181], v[194:197], v[98:101]
	v_mfma_f32_16x16x32_bf16 v[86:89], v[170:173], v[202:205], v[86:89]
	v_mfma_f32_16x16x32_bf16 v[82:85], v[178:181], v[202:205], v[82:85]
	v_mfma_f32_16x16x32_bf16 v[70:73], v[170:173], v[214:217], v[70:73]
	v_mfma_f32_16x16x32_bf16 v[66:69], v[178:181], v[214:217], v[66:69]
	v_mfma_f32_16x16x32_bf16 v[118:121], v[174:177], v[190:193], v[118:121]
	v_mfma_f32_16x16x32_bf16 v[114:117], v[182:185], v[190:193], v[114:117]
	v_mfma_f32_16x16x32_bf16 v[102:105], v[174:177], v[198:201], v[102:105]
	v_mfma_f32_16x16x32_bf16 v[98:101], v[182:185], v[198:201], v[98:101]
	v_mfma_f32_16x16x32_bf16 v[86:89], v[174:177], v[210:213], v[86:89]
	v_mfma_f32_16x16x32_bf16 v[82:85], v[182:185], v[210:213], v[82:85]
	v_mfma_f32_16x16x32_bf16 v[70:73], v[174:177], v[218:221], v[70:73]
	v_mfma_f32_16x16x32_bf16 v[66:69], v[182:185], v[218:221], v[66:69]
	s_setprio 0
	s_barrier
; #define G8_STA(bufoff, ptr, sg, h) G8_STAGE1(bufoff, (ptr) + (h) * ((sg) ? hA1 : hA0), ((sg) ? voffA1 : voffA0), ((sg) ? r64A1 : r64A0))
; #define G8_STB(bufoff, ptr, sg, h) G8_STAGE1(bufoff, (ptr) + (h) * ((sg) ? hB1 : hB0), ((sg) ? voffB1 : voffB0), ((sg) ? r64B1 : r64B0))
; #define G8_LDA(dst, b, h) do { _Pragma("unroll") for (int m = 0; m < 4; ++m) _Pragma("unroll") for (int k = 0; k < 2; ++k) dst[m][k] = *(const LAS bf16x8*)(lds + G8_SA(b, h) + aoff + m * 2048 + k * 1024); } while (0)
; #define G8_MMA(ai, bj, At, Bt) do { __builtin_amdgcn_s_setprio(1); _Pragma("unroll") for (int m = 0; m < 4; ++m) _Pragma("unroll") for (int n = 0; n < 2; ++n) _Pragma("unroll") for (int k = 0; k < 2; ++k) \
;         acc[ai][bj][m][n] = __builtin_amdgcn_mfma_f32_16x16x32_bf16(Bt[n][k], At[m][k], acc[ai][bj][m][n], 0, 0, 0); __builtin_amdgcn_s_setprio(0); } while (0)
; #define G8_WAIT_V(n) asm volatile("s_waitcnt vmcnt(" #n ")" ::: "memory")
; #define G8_WAIT_L(n) asm volatile("s_waitcnt lgkmcnt(" #n ")" ::: "memory")
; #define G8_BAR __builtin_amdgcn_s_barrier()
; #define G8_SCHED __builtin_amdgcn_sched_barrier(0)
; template <class P>
; __device__ __forceinline__ void gemm_phase(LAS unsigned char* lds, const P& p, const int G, const int c) {
;     ...
;             G8_LDA(At, 1, 1); G8_STB(G8_SB(1, 0), b3, sg2, 0); G8_STB(G8_SB(1, 1), b3, sg2, 1); G8_STA(G8_SA(1, 0), a3, sg2, 0);
;             G8_WAIT_V(8); G8_WAIT_L(0); G8_BAR; G8_MMA(1, 0, At, B0); G8_MMA(1, 1, At, B1); G8_BAR; G8_SCHED;
;         }
	s_add_i32 s28, s28, s26
	v_lshl_add_u64 v[224:225], v[206:207], 0, s[20:21]
	s_mov_b32 m0, s28
	ds_read_b128 v[186:189], v158 offset:49152
	ds_read_b128 v[190:193], v158 offset:50176
	ds_read_b128 v[194:197], v158 offset:51200
	ds_read_b128 v[198:201], v158 offset:52224
	ds_read_b128 v[202:205], v158 offset:53248
	ds_read_b128 v[210:213], v158 offset:54272
	ds_read_b128 v[214:217], v158 offset:55296
	ds_read_b128 v[218:221], v158 offset:56320
	global_load_lds_dwordx4 v[224:225], off
	v_lshl_add_u64 v[224:225], v[206:207], 0, s[22:23]
	s_add_i32 m0, s28, 0x2000
	s_add_i32 s28, s29, s26
	global_load_lds_dwordx4 v[224:225], off
	v_lshl_add_u64 v[224:225], v[206:207], 0, s[40:41]
	s_mov_b32 m0, s28
	v_lshl_add_u64 v[206:207], v[206:207], 0, s[42:43]
	global_load_lds_dwordx4 v[224:225], off
	s_add_i32 m0, s28, 0x2000
	s_nop 0
	global_load_lds_dwordx4 v[206:207], off
	v_lshl_add_u64 v[206:207], v[222:223], 0, s[36:37]
	s_mov_b32 m0, s51
	s_nop 0
	global_load_lds_dwordx4 v[206:207], off
	v_lshl_add_u64 v[206:207], v[222:223], 0, s[38:39]
	s_mov_b32 m0, s64
	s_nop 0
	global_load_lds_dwordx4 v[206:207], off
	s_waitcnt vmcnt(8)
	s_waitcnt lgkmcnt(0)
	s_barrier
	s_setprio 1
	s_waitcnt lgkmcnt(0)
	v_mfma_f32_16x16x32_bf16 v[62:65], v[142:145], v[186:189], v[62:65]
	v_mfma_f32_16x16x32_bf16 v[58:61], v[162:165], v[186:189], v[58:61]
	v_mfma_f32_16x16x32_bf16 v[46:49], v[142:145], v[194:197], v[46:49]
	v_mfma_f32_16x16x32_bf16 v[42:45], v[162:165], v[194:197], v[42:45]
	v_mfma_f32_16x16x32_bf16 v[30:33], v[142:145], v[202:205], v[30:33]
	v_mfma_f32_16x16x32_bf16 v[26:29], v[162:165], v[202:205], v[26:29]
	v_mfma_f32_16x16x32_bf16 v[14:17], v[142:145], v[214:217], v[14:17]
	v_mfma_f32_16x16x32_bf16 v[10:13], v[162:165], v[214:217], v[10:13]
	v_mfma_f32_16x16x32_bf16 v[62:65], v[146:149], v[190:193], v[62:65]
	v_mfma_f32_16x16x32_bf16 v[58:61], v[166:169], v[190:193], v[58:61]
	v_mfma_f32_16x16x32_bf16 v[46:49], v[146:149], v[198:201], v[46:49]
	v_mfma_f32_16x16x32_bf16 v[42:45], v[166:169], v[198:201], v[42:45]
	v_mfma_f32_16x16x32_bf16 v[30:33], v[146:149], v[210:213], v[30:33]
	v_mfma_f32_16x16x32_bf16 v[26:29], v[166:169], v[210:213], v[26:29]
	v_mfma_f32_16x16x32_bf16 v[14:17], v[146:149], v[218:221], v[14:17]
	v_mfma_f32_16x16x32_bf16 v[10:13], v[166:169], v[218:221], v[10:13]
	v_mfma_f32_16x16x32_bf16 v[54:57], v[170:173], v[186:189], v[54:57]
	v_mfma_f32_16x16x32_bf16 v[50:53], v[178:181], v[186:189], v[50:53]
	v_mfma_f32_16x16x32_bf16 v[38:41], v[170:173], v[194:197], v[38:41]
	v_mfma_f32_16x16x32_bf16 v[34:37], v[178:181], v[194:197], v[34:37]
	v_mfma_f32_16x16x32_bf16 v[22:25], v[170:173], v[202:205], v[22:25]
	v_mfma_f32_16x16x32_bf16 v[18:21], v[178:181], v[202:205], v[18:21]
	v_mfma_f32_16x16x32_bf16 v[6:9], v[170:173], v[214:217], v[6:9]
	v_mfma_f32_16x16x32_bf16 v[2:5], v[178:181], v[214:217], v[2:5]
	v_mfma_f32_16x16x32_bf16 v[54:57], v[174:177], v[190:193], v[54:57]
	v_mfma_f32_16x16x32_bf16 v[50:53], v[182:185], v[190:193], v[50:53]
	v_mfma_f32_16x16x32_bf16 v[38:41], v[174:177], v[198:201], v[38:41]
	v_mfma_f32_16x16x32_bf16 v[34:37], v[182:185], v[198:201], v[34:37]
	v_mfma_f32_16x16x32_bf16 v[22:25], v[174:177], v[210:213], v[22:25]
	v_mfma_f32_16x16x32_bf16 v[18:21], v[182:185], v[210:213], v[18:21]
	v_mfma_f32_16x16x32_bf16 v[6:9], v[174:177], v[218:221], v[6:9]
	v_mfma_f32_16x16x32_bf16 v[2:5], v[182:185], v[218:221], v[2:5]
	s_setprio 0
	s_barrier
	s_add_u32 s19, s19, 0x100000
	s_addc_u32 s53, s53, 0
	s_add_u32 s70, s70, 0x820000
	s_addc_u32 s71, s71, 0
	s_cmp_ge_u32 s74, s1
	s_cbranch_scc1 .LBB0_415

; #define G8_STA(bufoff, ptr, sg, h) G8_STAGE1(bufoff, (ptr) + (h) * ((sg) ? hA1 : hA0), ((sg) ? voffA1 : voffA0), ((sg) ? r64A1 : r64A0))
; #define G8_STB(bufoff, ptr, sg, h) G8_STAGE1(bufoff, (ptr) + (h) * ((sg) ? hB1 : hB0), ((sg) ? voffB1 : voffB0), ((sg) ? r64B1 : r64B0))
; #define G8_LDA(dst, b, h) do { _Pragma("unroll") for (int m = 0; m < 4; ++m) _Pragma("unroll") for (int k = 0; k < 2; ++k) dst[m][k] = *(const LAS bf16x8*)(lds + G8_SA(b, h) + aoff + m * 2048 + k * 1024); } while (0)
; #define G8_LDB(dst, b, h) do { _Pragma("unroll") for (int n = 0; n < 2; ++n) _Pragma("unroll") for (int k = 0; k < 2; ++k) dst[n][k] = *(const LAS bf16x8*)(lds + G8_SB(b, h) + boff + n * 2048 + k * 1024); } while (0)
; #define G8_MMA(ai, bj, At, Bt) do { __builtin_amdgcn_s_setprio(1); _Pragma("unroll") for (int m = 0; m < 4; ++m) _Pragma("unroll") for (int n = 0; n < 2; ++n) _Pragma("unroll") for (int k = 0; k < 2; ++k) \
;         acc[ai][bj][m][n] = __builtin_amdgcn_mfma_f32_16x16x32_bf16(Bt[n][k], At[m][k], acc[ai][bj][m][n], 0, 0, 0); __builtin_amdgcn_s_setprio(0); } while (0)
; #define G8_BAR __builtin_amdgcn_s_barrier()
; template <class P>
; __device__ __forceinline__ void gemm_phase(LAS unsigned char* lds, const P& p, const int G, const int c) {
;     ...
;         for (int t = 0; t < nt; t += 2) {
;             const bool last = (t == nt - 2);
;             const bool sg1 = (NS > 1) && (t + 1 >= nt0);
;             const bool sg2 = (NS > 1) && !last && (t + 2 >= nt0);
;             const char* a1 = sg1 ? cA1 + (long)(t + 1 - nt0) * ksA1 : cA0 + (long)(t + 1) * ksA0;
;             const char* a2 = last ? nA0 : (sg2 ? cA1 + (long)(t + 2 - nt0) * ksA1 : cA0 + (long)(t + 2) * ksA0);
;             const char* b2 = last ? nB0 : (sg2 ? cB1 + (long)(t + 2 - nt0) * ksB1 : cB0 + (long)(t + 2) * ksB0);
;             const char* a3 = a2 + (sg2 ? ksA1 : ksA0); const char* b3 = b2 + (sg2 ? ksB1 : ksB0);
;             G8_LDB(B0, 0, 0); G8_LDB(B1, 0, 1); G8_SCHED; G8_LDA(At, 0, 0); G8_STA(G8_SA(1, 1), a1, sg1, 1);
;             G8_WAIT_V(8); G8_WAIT_L(0); G8_BAR; G8_MMA(0, 0, At, B0); G8_MMA(0, 1, At, B1); G8_BAR; G8_SCHED;
;             G8_LDA(At, 0, 1); G8_STB(G8_SB(0, 0), b2, sg2, 0); G8_STB(G8_SB(0, 1), b2, sg2, 1); G8_STA(G8_SA(0, 0), a2, sg2, 0);
;             G8_WAIT_V(8); G8_WAIT_L(0); G8_BAR; G8_MMA(1, 0, At, B0); G8_MMA(1, 1, At, B1); G8_BAR; G8_SCHED;
.LBB0_539:
	s_add_u32 s6, s92, s94
	s_addc_u32 s7, s93, s95
	s_add_u32 s6, s6, 0x10000
	s_addc_u32 s7, s7, 0
	s_add_i32 s65, 0, 0x10000
	s_cmp_eq_u32 s94, 0x30000
	s_cselect_b32 s7, s18, s7
	s_cselect_b32 s6, s19, s6
	v_add_u32_e32 v130, s65, v156
	s_cselect_b32 s51, s89, s29
	s_cselect_b32 s50, s88, s28
	s_add_i32 s34, 0, 0x14000
	ds_read_b128 v[160:163], v130
	ds_read_b128 v[164:167], v130 offset:1024
	ds_read_b128 v[168:171], v130 offset:2048
	ds_read_b128 v[172:175], v130 offset:3072
	v_add_u32_e32 v130, s34, v156
	ds_read_b128 v[176:179], v130
	ds_read_b128 v[180:183], v130 offset:1024
	ds_read_b128 v[184:187], v130 offset:2048
	ds_read_b128 v[188:191], v130 offset:3072
	v_lshl_add_u64 v[226:227], v[154:155], 0, s[94:95]
	s_mov_b64 s[54:55], 0xc000
	v_lshl_add_u64 v[228:229], v[226:227], 0, s[54:55]
	s_add_i32 m0, s11, 0xc000
	s_mov_b64 s[54:55], 0xe000
	ds_read_b128 v[192:195], v158
	ds_read_b128 v[196:199], v158 offset:1024
	ds_read_b128 v[200:203], v158 offset:2048
	ds_read_b128 v[204:207], v158 offset:3072
	ds_read_b128 v[210:213], v158 offset:4096
	ds_read_b128 v[214:217], v158 offset:5120
	ds_read_b128 v[218:221], v158 offset:6144
	ds_read_b128 v[222:225], v158 offset:7168
	global_load_lds_dwordx4 v[228:229], off
	v_lshl_add_u64 v[226:227], v[226:227], 0, s[54:55]
	s_add_i32 m0, s11, 0xe000
	s_nop 0
	global_load_lds_dwordx4 v[226:227], off
	s_waitcnt vmcnt(8)
	s_waitcnt lgkmcnt(0)
	s_barrier
	s_setprio 1
	s_waitcnt lgkmcnt(0)
	v_mfma_f32_16x16x32_bf16 v[126:129], v[160:163], v[192:195], v[126:129]
	v_mfma_f32_16x16x32_bf16 v[122:125], v[168:171], v[192:195], v[122:125]
	v_mfma_f32_16x16x32_bf16 v[118:121], v[160:163], v[200:203], v[118:121]
	v_mfma_f32_16x16x32_bf16 v[114:117], v[168:171], v[200:203], v[114:117]
	v_mfma_f32_16x16x32_bf16 v[102:105], v[160:163], v[210:213], v[102:105]
	v_mfma_f32_16x16x32_bf16 v[98:101], v[168:171], v[210:213], v[98:101]
	v_mfma_f32_16x16x32_bf16 v[86:89], v[160:163], v[218:221], v[86:89]
	v_mfma_f32_16x16x32_bf16 v[82:85], v[168:171], v[218:221], v[82:85]
	v_mfma_f32_16x16x32_bf16 v[126:129], v[164:167], v[196:199], v[126:129]
	v_mfma_f32_16x16x32_bf16 v[122:125], v[172:175], v[196:199], v[122:125]
	v_mfma_f32_16x16x32_bf16 v[118:121], v[164:167], v[204:207], v[118:121]
	v_mfma_f32_16x16x32_bf16 v[114:117], v[172:175], v[204:207], v[114:117]
	v_mfma_f32_16x16x32_bf16 v[102:105], v[164:167], v[214:217], v[102:105]
	v_mfma_f32_16x16x32_bf16 v[98:101], v[172:175], v[214:217], v[98:101]
	v_mfma_f32_16x16x32_bf16 v[86:89], v[164:167], v[222:225], v[86:89]
	v_mfma_f32_16x16x32_bf16 v[82:85], v[172:175], v[222:225], v[82:85]
	v_mfma_f32_16x16x32_bf16 v[110:113], v[176:179], v[192:195], v[110:113]
	v_mfma_f32_16x16x32_bf16 v[106:109], v[184:187], v[192:195], v[106:109]
	v_mfma_f32_16x16x32_bf16 v[94:97], v[176:179], v[200:203], v[94:97]
	v_mfma_f32_16x16x32_bf16 v[90:93], v[184:187], v[200:203], v[90:93]
	v_mfma_f32_16x16x32_bf16 v[78:81], v[176:179], v[210:213], v[78:81]
	v_mfma_f32_16x16x32_bf16 v[74:77], v[184:187], v[210:213], v[74:77]
	v_mfma_f32_16x16x32_bf16 v[70:73], v[176:179], v[218:221], v[70:73]
	v_mfma_f32_16x16x32_bf16 v[66:69], v[184:187], v[218:221], v[66:69]
	v_mfma_f32_16x16x32_bf16 v[110:113], v[180:183], v[196:199], v[110:113]
	v_mfma_f32_16x16x32_bf16 v[106:109], v[188:191], v[196:199], v[106:109]
	v_mfma_f32_16x16x32_bf16 v[94:97], v[180:183], v[204:207], v[94:97]
	v_mfma_f32_16x16x32_bf16 v[90:93], v[188:191], v[204:207], v[90:93]
	v_mfma_f32_16x16x32_bf16 v[78:81], v[180:183], v[214:217], v[78:81]
	v_mfma_f32_16x16x32_bf16 v[74:77], v[188:191], v[214:217], v[74:77]
	v_mfma_f32_16x16x32_bf16 v[70:73], v[180:183], v[222:225], v[70:73]
	v_mfma_f32_16x16x32_bf16 v[66:69], v[188:191], v[222:225], v[66:69]
	s_setprio 0
	s_barrier
	s_add_i32 s20, s65, s10
	v_lshl_add_u64 v[226:227], s[50:51], 0, v[132:133]
	s_mov_b32 m0, s20
	ds_read_b128 v[192:195], v158 offset:16384
	ds_read_b128 v[196:199], v158 offset:17408
	ds_read_b128 v[200:203], v158 offset:18432
	ds_read_b128 v[204:207], v158 offset:19456
	ds_read_b128 v[210:213], v158 offset:20480
	ds_read_b128 v[214:217], v158 offset:21504
	ds_read_b128 v[218:221], v158 offset:22528
	ds_read_b128 v[222:225], v158 offset:23552
	global_load_lds_dwordx4 v[226:227], off
	v_lshl_add_u64 v[228:229], v[226:227], 0, s[22:23]
	s_add_i32 m0, s20, 0x2000
	s_add_i32 s20, s34, s10
	global_load_lds_dwordx4 v[228:229], off
	v_lshl_add_u64 v[228:229], v[226:227], 0, s[36:37]
	s_mov_b32 m0, s20
	s_nop 0
	global_load_lds_dwordx4 v[228:229], off
	v_lshl_add_u64 v[228:229], v[226:227], 0, s[38:39]
	s_add_i32 m0, s20, 0x2000
	s_nop 0
	global_load_lds_dwordx4 v[228:229], off
	v_lshl_add_u64 v[228:229], s[6:7], 0, v[134:135]
	s_mov_b32 m0, s11
	v_lshl_add_u64 v[230:231], v[228:229], 0, s[22:23]
	global_load_lds_dwordx4 v[228:229], off
	s_mov_b32 m0, s14
	s_nop 0
	global_load_lds_dwordx4 v[230:231], off
	s_waitcnt vmcnt(8)
	s_waitcnt lgkmcnt(0)
	s_barrier
; #define G8_STA(bufoff, ptr, sg, h) G8_STAGE1(bufoff, (ptr) + (h) * ((sg) ? hA1 : hA0), ((sg) ? voffA1 : voffA0), ((sg) ? r64A1 : r64A0))
; #define G8_STB(bufoff, ptr, sg, h) G8_STAGE1(bufoff, (ptr) + (h) * ((sg) ? hB1 : hB0), ((sg) ? voffB1 : voffB0), ((sg) ? r64B1 : r64B0))
; #define G8_LDA(dst, b, h) do { _Pragma("unroll") for (int m = 0; m < 4; ++m) _Pragma("unroll") for (int k = 0; k < 2; ++k) dst[m][k] = *(const LAS bf16x8*)(lds + G8_SA(b, h) + aoff + m * 2048 + k * 1024); } while (0)
; #define G8_LDB(dst, b, h) do { _Pragma("unroll") for (int n = 0; n < 2; ++n) _Pragma("unroll") for (int k = 0; k < 2; ++k) dst[n][k] = *(const LAS bf16x8*)(lds + G8_SB(b, h) + boff + n * 2048 + k * 1024); } while (0)
; #define G8_MMA(ai, bj, At, Bt) do { __builtin_amdgcn_s_setprio(1); _Pragma("unroll") for (int m = 0; m < 4; ++m) _Pragma("unroll") for (int n = 0; n < 2; ++n) _Pragma("unroll") for (int k = 0; k < 2; ++k) \
;         acc[ai][bj][m][n] = __builtin_amdgcn_mfma_f32_16x16x32_bf16(Bt[n][k], At[m][k], acc[ai][bj][m][n], 0, 0, 0); __builtin_amdgcn_s_setprio(0); } while (0)
; #define G8_WAIT_V(n) asm volatile("s_waitcnt vmcnt(" #n ")" ::: "memory")
; #define G8_WAIT_L(n) asm volatile("s_waitcnt lgkmcnt(" #n ")" ::: "memory")
; #define G8_BAR __builtin_amdgcn_s_barrier()
; #define G8_SCHED __builtin_amdgcn_sched_barrier(0)
; template <class P>
; __device__ __forceinline__ void gemm_phase(LAS unsigned char* lds, const P& p, const int G, const int c) {
;     ...
;             G8_LDA(At, 0, 1); G8_STB(G8_SB(0, 0), b2, sg2, 0); G8_STB(G8_SB(0, 1), b2, sg2, 1); G8_STA(G8_SA(0, 0), a2, sg2, 0);
;             G8_WAIT_V(8); G8_WAIT_L(0); G8_BAR; G8_MMA(1, 0, At, B0); G8_MMA(1, 1, At, B1); G8_BAR; G8_SCHED;
;             G8_LDB(B0, 1, 0); G8_LDB(B1, 1, 1); G8_SCHED; G8_LDA(At, 1, 0); G8_STA(G8_SA(0, 1), a2, sg2, 1);
;             G8_WAIT_V(8); G8_WAIT_L(0); G8_BAR; G8_MMA(0, 0, At, B0); G8_MMA(0, 1, At, B1); G8_BAR; G8_SCHED;
;             G8_LDA(At, 1, 1); G8_STB(G8_SB(1, 0), b3, sg2, 0); G8_STB(G8_SB(1, 1), b3, sg2, 1); G8_STA(G8_SA(1, 0), a3, sg2, 0);
	s_setprio 1
	s_waitcnt lgkmcnt(0)
	v_mfma_f32_16x16x32_bf16 v[62:65], v[160:163], v[192:195], v[62:65]
	v_mfma_f32_16x16x32_bf16 v[58:61], v[168:171], v[192:195], v[58:61]
	v_mfma_f32_16x16x32_bf16 v[54:57], v[160:163], v[200:203], v[54:57]
	v_mfma_f32_16x16x32_bf16 v[50:53], v[168:171], v[200:203], v[50:53]
	v_mfma_f32_16x16x32_bf16 v[38:41], v[160:163], v[210:213], v[38:41]
	v_mfma_f32_16x16x32_bf16 v[34:37], v[168:171], v[210:213], v[34:37]
	v_mfma_f32_16x16x32_bf16 v[22:25], v[160:163], v[218:221], v[22:25]
	v_mfma_f32_16x16x32_bf16 v[18:21], v[168:171], v[218:221], v[18:21]
	v_mfma_f32_16x16x32_bf16 v[62:65], v[164:167], v[196:199], v[62:65]
	v_mfma_f32_16x16x32_bf16 v[58:61], v[172:175], v[196:199], v[58:61]
	v_mfma_f32_16x16x32_bf16 v[54:57], v[164:167], v[204:207], v[54:57]
	v_mfma_f32_16x16x32_bf16 v[50:53], v[172:175], v[204:207], v[50:53]
	v_mfma_f32_16x16x32_bf16 v[38:41], v[164:167], v[214:217], v[38:41]
	v_mfma_f32_16x16x32_bf16 v[34:37], v[172:175], v[214:217], v[34:37]
	v_mfma_f32_16x16x32_bf16 v[22:25], v[164:167], v[222:225], v[22:25]
	v_mfma_f32_16x16x32_bf16 v[18:21], v[172:175], v[222:225], v[18:21]
	v_mfma_f32_16x16x32_bf16 v[46:49], v[176:179], v[192:195], v[46:49]
	v_mfma_f32_16x16x32_bf16 v[42:45], v[184:187], v[192:195], v[42:45]
	v_mfma_f32_16x16x32_bf16 v[30:33], v[176:179], v[200:203], v[30:33]
	v_mfma_f32_16x16x32_bf16 v[26:29], v[184:187], v[200:203], v[26:29]
	v_mfma_f32_16x16x32_bf16 v[14:17], v[176:179], v[210:213], v[14:17]
	v_mfma_f32_16x16x32_bf16 v[10:13], v[184:187], v[210:213], v[10:13]
	v_mfma_f32_16x16x32_bf16 v[6:9], v[176:179], v[218:221], v[6:9]
	v_mfma_f32_16x16x32_bf16 v[2:5], v[184:187], v[218:221], v[2:5]
	v_mfma_f32_16x16x32_bf16 v[46:49], v[180:183], v[196:199], v[46:49]
	v_mfma_f32_16x16x32_bf16 v[42:45], v[188:191], v[196:199], v[42:45]
	v_mfma_f32_16x16x32_bf16 v[30:33], v[180:183], v[204:207], v[30:33]
	v_mfma_f32_16x16x32_bf16 v[26:29], v[188:191], v[204:207], v[26:29]
	v_mfma_f32_16x16x32_bf16 v[14:17], v[180:183], v[214:217], v[14:17]
	v_mfma_f32_16x16x32_bf16 v[10:13], v[188:191], v[214:217], v[10:13]
	v_mfma_f32_16x16x32_bf16 v[6:9], v[180:183], v[222:225], v[6:9]
	v_mfma_f32_16x16x32_bf16 v[2:5], v[188:191], v[222:225], v[2:5]
	s_setprio 0
	s_barrier
	s_add_i32 s35, 0, 0x18000
	v_add_u32_e32 v130, s35, v156
	s_add_i32 s20, 0, 0x1c000
	ds_read_b128 v[160:163], v130
	ds_read_b128 v[164:167], v130 offset:1024
	ds_read_b128 v[168:171], v130 offset:2048
	ds_read_b128 v[172:175], v130 offset:3072
	v_add_u32_e32 v130, s20, v156
	ds_read_b128 v[176:179], v130
	ds_read_b128 v[180:183], v130 offset:1024
	ds_read_b128 v[184:187], v130 offset:2048
	ds_read_b128 v[188:191], v130 offset:3072
	s_mov_b32 m0, s15
	v_lshl_add_u64 v[230:231], v[228:229], 0, s[36:37]
	ds_read_b128 v[192:195], v158 offset:32768
	ds_read_b128 v[196:199], v158 offset:33792
	ds_read_b128 v[200:203], v158 offset:34816
	ds_read_b128 v[204:207], v158 offset:35840
	ds_read_b128 v[210:213], v158 offset:36864
	ds_read_b128 v[214:217], v158 offset:37888
	ds_read_b128 v[218:221], v158 offset:38912
	ds_read_b128 v[222:225], v158 offset:39936
	global_load_lds_dwordx4 v[230:231], off
	v_lshl_add_u64 v[230:231], v[228:229], 0, s[38:39]
	s_mov_b32 m0, s16
	s_nop 0
	global_load_lds_dwordx4 v[230:231], off
	s_waitcnt vmcnt(8)
	s_waitcnt lgkmcnt(0)
	s_barrier
	s_setprio 1
	s_waitcnt lgkmcnt(0)
	v_mfma_f32_16x16x32_bf16 v[126:129], v[160:163], v[192:195], v[126:129]
	v_mfma_f32_16x16x32_bf16 v[122:125], v[168:171], v[192:195], v[122:125]
	v_mfma_f32_16x16x32_bf16 v[118:121], v[160:163], v[200:203], v[118:121]
	v_mfma_f32_16x16x32_bf16 v[114:117], v[168:171], v[200:203], v[114:117]
	v_mfma_f32_16x16x32_bf16 v[102:105], v[160:163], v[210:213], v[102:105]
	v_mfma_f32_16x16x32_bf16 v[98:101], v[168:171], v[210:213], v[98:101]
	v_mfma_f32_16x16x32_bf16 v[86:89], v[160:163], v[218:221], v[86:89]
	v_mfma_f32_16x16x32_bf16 v[82:85], v[168:171], v[218:221], v[82:85]
	v_mfma_f32_16x16x32_bf16 v[126:129], v[164:167], v[196:199], v[126:129]
	v_mfma_f32_16x16x32_bf16 v[122:125], v[172:175], v[196:199], v[122:125]
	v_mfma_f32_16x16x32_bf16 v[118:121], v[164:167], v[204:207], v[118:121]
	v_mfma_f32_16x16x32_bf16 v[114:117], v[172:175], v[204:207], v[114:117]
	v_mfma_f32_16x16x32_bf16 v[102:105], v[164:167], v[214:217], v[102:105]
	v_mfma_f32_16x16x32_bf16 v[98:101], v[172:175], v[214:217], v[98:101]
	v_mfma_f32_16x16x32_bf16 v[86:89], v[164:167], v[222:225], v[86:89]
	v_mfma_f32_16x16x32_bf16 v[82:85], v[172:175], v[222:225], v[82:85]
	v_mfma_f32_16x16x32_bf16 v[110:113], v[176:179], v[192:195], v[110:113]
	v_mfma_f32_16x16x32_bf16 v[106:109], v[184:187], v[192:195], v[106:109]
	v_mfma_f32_16x16x32_bf16 v[94:97], v[176:179], v[200:203], v[94:97]
	v_mfma_f32_16x16x32_bf16 v[90:93], v[184:187], v[200:203], v[90:93]
	v_mfma_f32_16x16x32_bf16 v[78:81], v[176:179], v[210:213], v[78:81]
	v_mfma_f32_16x16x32_bf16 v[74:77], v[184:187], v[210:213], v[74:77]
	v_mfma_f32_16x16x32_bf16 v[70:73], v[176:179], v[218:221], v[70:73]
	v_mfma_f32_16x16x32_bf16 v[66:69], v[184:187], v[218:221], v[66:69]
	v_mfma_f32_16x16x32_bf16 v[110:113], v[180:183], v[196:199], v[110:113]
	v_mfma_f32_16x16x32_bf16 v[106:109], v[188:191], v[196:199], v[106:109]
	v_mfma_f32_16x16x32_bf16 v[94:97], v[180:183], v[204:207], v[94:97]
	v_mfma_f32_16x16x32_bf16 v[90:93], v[188:191], v[204:207], v[90:93]
	v_mfma_f32_16x16x32_bf16 v[78:81], v[180:183], v[214:217], v[78:81]
	v_mfma_f32_16x16x32_bf16 v[74:77], v[188:191], v[214:217], v[74:77]
	v_mfma_f32_16x16x32_bf16 v[70:73], v[180:183], v[222:225], v[70:73]
	v_mfma_f32_16x16x32_bf16 v[66:69], v[188:191], v[222:225], v[66:69]
	s_setprio 0
	s_barrier
; #define G8_STA(bufoff, ptr, sg, h) G8_STAGE1(bufoff, (ptr) + (h) * ((sg) ? hA1 : hA0), ((sg) ? voffA1 : voffA0), ((sg) ? r64A1 : r64A0))
; #define G8_STB(bufoff, ptr, sg, h) G8_STAGE1(bufoff, (ptr) + (h) * ((sg) ? hB1 : hB0), ((sg) ? voffB1 : voffB0), ((sg) ? r64B1 : r64B0))
; #define G8_LDA(dst, b, h) do { _Pragma("unroll") for (int m = 0; m < 4; ++m) _Pragma("unroll") for (int k = 0; k < 2; ++k) dst[m][k] = *(const LAS bf16x8*)(lds + G8_SA(b, h) + aoff + m * 2048 + k * 1024); } while (0)
; #define G8_MMA(ai, bj, At, Bt) do { __builtin_amdgcn_s_setprio(1); _Pragma("unroll") for (int m = 0; m < 4; ++m) _Pragma("unroll") for (int n = 0; n < 2; ++n) _Pragma("unroll") for (int k = 0; k < 2; ++k) \
;         acc[ai][bj][m][n] = __builtin_amdgcn_mfma_f32_16x16x32_bf16(Bt[n][k], At[m][k], acc[ai][bj][m][n], 0, 0, 0); __builtin_amdgcn_s_setprio(0); } while (0)
; #define G8_WAIT_V(n) asm volatile("s_waitcnt vmcnt(" #n ")" ::: "memory")
; #define G8_WAIT_L(n) asm volatile("s_waitcnt lgkmcnt(" #n ")" ::: "memory")
; #define G8_BAR __builtin_amdgcn_s_barrier()
; #define G8_SCHED __builtin_amdgcn_sched_barrier(0)
; template <class P>
; __device__ __forceinline__ void gemm_phase(LAS unsigned char* lds, const P& p, const int G, const int c) {
;     ...
;             G8_LDA(At, 1, 1); G8_STB(G8_SB(1, 0), b3, sg2, 0); G8_STB(G8_SB(1, 1), b3, sg2, 1); G8_STA(G8_SA(1, 0), a3, sg2, 0);
;             G8_WAIT_V(8); G8_WAIT_L(0); G8_BAR; G8_MMA(1, 0, At, B0); G8_MMA(1, 1, At, B1); G8_BAR; G8_SCHED;
;         }
;         if (wr == 0) G8_BAR;
	s_add_i32 s6, s35, s10
	v_lshl_add_u64 v[230:231], v[226:227], 0, s[40:41]
	s_mov_b32 m0, s6
	ds_read_b128 v[192:195], v158 offset:49152
	ds_read_b128 v[196:199], v158 offset:50176
	ds_read_b128 v[200:203], v158 offset:51200
	ds_read_b128 v[204:207], v158 offset:52224
	ds_read_b128 v[210:213], v158 offset:53248
	ds_read_b128 v[214:217], v158 offset:54272
	ds_read_b128 v[218:221], v158 offset:55296
	ds_read_b128 v[222:225], v158 offset:56320
	global_load_lds_dwordx4 v[230:231], off
	v_lshl_add_u64 v[230:231], v[226:227], 0, s[42:43]
	s_add_i32 m0, s6, 0x2000
	s_add_i32 s6, s20, s10
	global_load_lds_dwordx4 v[230:231], off
	v_lshl_add_u64 v[230:231], v[226:227], 0, s[48:49]
	s_mov_b32 m0, s6
	v_lshl_add_u64 v[226:227], v[226:227], 0, s[52:53]
	global_load_lds_dwordx4 v[230:231], off
	s_add_i32 m0, s6, 0x2000
	s_nop 0
	global_load_lds_dwordx4 v[226:227], off
	v_lshl_add_u64 v[226:227], v[228:229], 0, s[8:9]
	s_mov_b32 m0, s24
	s_nop 0
	global_load_lds_dwordx4 v[226:227], off
	v_lshl_add_u64 v[226:227], v[228:229], 0, s[44:45]
	s_mov_b32 m0, s25
	s_nop 0
	global_load_lds_dwordx4 v[226:227], off
	s_waitcnt vmcnt(8)
	s_waitcnt lgkmcnt(0)
	s_barrier
	s_setprio 1
	s_waitcnt lgkmcnt(0)
	v_mfma_f32_16x16x32_bf16 v[62:65], v[160:163], v[192:195], v[62:65]
	v_mfma_f32_16x16x32_bf16 v[58:61], v[168:171], v[192:195], v[58:61]
	v_mfma_f32_16x16x32_bf16 v[54:57], v[160:163], v[200:203], v[54:57]
	v_mfma_f32_16x16x32_bf16 v[50:53], v[168:171], v[200:203], v[50:53]
	v_mfma_f32_16x16x32_bf16 v[38:41], v[160:163], v[210:213], v[38:41]
	v_mfma_f32_16x16x32_bf16 v[34:37], v[168:171], v[210:213], v[34:37]
	v_mfma_f32_16x16x32_bf16 v[22:25], v[160:163], v[218:221], v[22:25]
	v_mfma_f32_16x16x32_bf16 v[18:21], v[168:171], v[218:221], v[18:21]
	v_mfma_f32_16x16x32_bf16 v[62:65], v[164:167], v[196:199], v[62:65]
	v_mfma_f32_16x16x32_bf16 v[58:61], v[172:175], v[196:199], v[58:61]
	v_mfma_f32_16x16x32_bf16 v[54:57], v[164:167], v[204:207], v[54:57]
	v_mfma_f32_16x16x32_bf16 v[50:53], v[172:175], v[204:207], v[50:53]
	v_mfma_f32_16x16x32_bf16 v[38:41], v[164:167], v[214:217], v[38:41]
	v_mfma_f32_16x16x32_bf16 v[34:37], v[172:175], v[214:217], v[34:37]
	v_mfma_f32_16x16x32_bf16 v[22:25], v[164:167], v[222:225], v[22:25]
	v_mfma_f32_16x16x32_bf16 v[18:21], v[172:175], v[222:225], v[18:21]
	v_mfma_f32_16x16x32_bf16 v[46:49], v[176:179], v[192:195], v[46:49]
	v_mfma_f32_16x16x32_bf16 v[42:45], v[184:187], v[192:195], v[42:45]
	v_mfma_f32_16x16x32_bf16 v[30:33], v[176:179], v[200:203], v[30:33]
	v_mfma_f32_16x16x32_bf16 v[26:29], v[184:187], v[200:203], v[26:29]
	v_mfma_f32_16x16x32_bf16 v[14:17], v[176:179], v[210:213], v[14:17]
	v_mfma_f32_16x16x32_bf16 v[10:13], v[184:187], v[210:213], v[10:13]
	v_mfma_f32_16x16x32_bf16 v[6:9], v[176:179], v[218:221], v[6:9]
	v_mfma_f32_16x16x32_bf16 v[2:5], v[184:187], v[218:221], v[2:5]
	v_mfma_f32_16x16x32_bf16 v[46:49], v[180:183], v[196:199], v[46:49]
	v_mfma_f32_16x16x32_bf16 v[42:45], v[188:191], v[196:199], v[42:45]
	v_mfma_f32_16x16x32_bf16 v[30:33], v[180:183], v[204:207], v[30:33]
	v_mfma_f32_16x16x32_bf16 v[26:29], v[188:191], v[204:207], v[26:29]
	v_mfma_f32_16x16x32_bf16 v[14:17], v[180:183], v[214:217], v[14:17]
	v_mfma_f32_16x16x32_bf16 v[10:13], v[188:191], v[214:217], v[10:13]
	v_mfma_f32_16x16x32_bf16 v[6:9], v[180:183], v[222:225], v[6:9]
	v_mfma_f32_16x16x32_bf16 v[2:5], v[188:191], v[222:225], v[2:5]
	s_setprio 0
	s_barrier
	s_add_i32 s47, s47, 2
	s_add_u32 s28, s28, 0x40000
	s_addc_u32 s29, s29, 0
	s_add_u32 s94, s94, 0x10000
	s_addc_u32 s95, s95, 0
	s_cmp_gt_u32 s47, 5
	s_cbranch_scc0 .LBB0_539
	s_and_b64 vcc, exec, s[86:87]
	s_cbranch_vccz .LBB0_542
	s_barrier

; #define G8_STA(bufoff, ptr, sg, h) G8_STAGE1(bufoff, (ptr) + (h) * ((sg) ? hA1 : hA0), ((sg) ? voffA1 : voffA0), ((sg) ? r64A1 : r64A0))
; #define G8_STB(bufoff, ptr, sg, h) G8_STAGE1(bufoff, (ptr) + (h) * ((sg) ? hB1 : hB0), ((sg) ? voffB1 : voffB0), ((sg) ? r64B1 : r64B0))
; #define G8_LDA(dst, b, h) do { _Pragma("unroll") for (int m = 0; m < 4; ++m) _Pragma("unroll") for (int k = 0; k < 2; ++k) dst[m][k] = *(const LAS bf16x8*)(lds + G8_SA(b, h) + aoff + m * 2048 + k * 1024); } while (0)
; #define G8_LDB(dst, b, h) do { _Pragma("unroll") for (int n = 0; n < 2; ++n) _Pragma("unroll") for (int k = 0; k < 2; ++k) dst[n][k] = *(const LAS bf16x8*)(lds + G8_SB(b, h) + boff + n * 2048 + k * 1024); } while (0)
; #define G8_MMA(ai, bj, At, Bt) do { __builtin_amdgcn_s_setprio(1); _Pragma("unroll") for (int m = 0; m < 4; ++m) _Pragma("unroll") for (int n = 0; n < 2; ++n) _Pragma("unroll") for (int k = 0; k < 2; ++k) \
;         acc[ai][bj][m][n] = __builtin_amdgcn_mfma_f32_16x16x32_bf16(Bt[n][k], At[m][k], acc[ai][bj][m][n], 0, 0, 0); __builtin_amdgcn_s_setprio(0); } while (0)
; #define G8_BAR __builtin_amdgcn_s_barrier()
; template <class P>
; __device__ __forceinline__ void gemm_phase(LAS unsigned char* lds, const P& p, const int G, const int c) {
;     ...
;         for (int t = 0; t < nt; t += 2) {
;             const bool last = (t == nt - 2);
;             const bool sg1 = (NS > 1) && (t + 1 >= nt0);
;             const bool sg2 = (NS > 1) && !last && (t + 2 >= nt0);
;             const char* a1 = sg1 ? cA1 + (long)(t + 1 - nt0) * ksA1 : cA0 + (long)(t + 1) * ksA0;
;             const char* a2 = last ? nA0 : (sg2 ? cA1 + (long)(t + 2 - nt0) * ksA1 : cA0 + (long)(t + 2) * ksA0);
;             const char* b2 = last ? nB0 : (sg2 ? cB1 + (long)(t + 2 - nt0) * ksB1 : cB0 + (long)(t + 2) * ksB0);
;             const char* a3 = a2 + (sg2 ? ksA1 : ksA0); const char* b3 = b2 + (sg2 ? ksB1 : ksB0);
;             G8_LDB(B0, 0, 0); G8_LDB(B1, 0, 1); G8_SCHED; G8_LDA(At, 0, 0); G8_STA(G8_SA(1, 1), a1, sg1, 1);
;             G8_WAIT_V(8); G8_WAIT_L(0); G8_BAR; G8_MMA(0, 0, At, B0); G8_MMA(0, 1, At, B1); G8_BAR; G8_SCHED;
;             G8_LDA(At, 0, 1); G8_STB(G8_SB(0, 0), b2, sg2, 0); G8_STB(G8_SB(0, 1), b2, sg2, 1); G8_STA(G8_SA(0, 0), a2, sg2, 0);
;             G8_WAIT_V(8); G8_WAIT_L(0); G8_BAR; G8_MMA(1, 0, At, B0); G8_MMA(1, 1, At, B1); G8_BAR; G8_SCHED;
.LBB0_583:
	v_add_u32_e32 v130, s65, v137
	ds_read_b128 v[150:153], v130
	ds_read_b128 v[154:157], v130 offset:1024
	ds_read_b128 v[158:161], v130 offset:2048
	ds_read_b128 v[162:165], v130 offset:3072
	v_add_u32_e32 v130, s34, v137
	ds_read_b128 v[166:169], v130
	ds_read_b128 v[170:173], v130 offset:1024
	ds_read_b128 v[174:177], v130 offset:2048
	ds_read_b128 v[178:181], v130 offset:3072
	s_cmp_gt_u32 s56, 5
	s_cselect_b64 s[18:19], -1, 0
	s_and_b64 vcc, s[6:7], s[18:19]
	s_and_b64 s[6:7], vcc, exec
	s_movk_i32 s6, 0x80
	s_cselect_b32 s6, 0x10000, s6
	v_lshl_add_u64 v[138:139], s[28:29], 0, v[134:135]
	v_lshl_add_u64 v[206:207], v[138:139], 0, s[36:37]
	s_add_i32 m0, s25, 0xc000
	ds_read_b128 v[182:185], v148
	ds_read_b128 v[186:189], v148 offset:1024
	ds_read_b128 v[190:193], v148 offset:2048
	ds_read_b128 v[194:197], v148 offset:3072
	ds_read_b128 v[198:201], v148 offset:4096
	ds_read_b128 v[202:205], v148 offset:5120
	ds_read_b128 v[210:213], v148 offset:6144
	ds_read_b128 v[214:217], v148 offset:7168
	global_load_lds_dwordx4 v[206:207], off
	v_lshl_add_u64 v[138:139], v[138:139], 0, s[38:39]
	s_add_i32 m0, s25, 0xe000
	s_nop 0
	global_load_lds_dwordx4 v[138:139], off
	s_waitcnt vmcnt(8)
	s_waitcnt lgkmcnt(0)
	s_barrier
	s_setprio 1
	s_waitcnt lgkmcnt(0)
	v_mfma_f32_16x16x32_bf16 v[126:129], v[150:153], v[182:185], v[126:129]
	v_mfma_f32_16x16x32_bf16 v[122:125], v[158:161], v[182:185], v[122:125]
	v_mfma_f32_16x16x32_bf16 v[110:113], v[150:153], v[190:193], v[110:113]
	v_mfma_f32_16x16x32_bf16 v[106:109], v[158:161], v[190:193], v[106:109]
	v_mfma_f32_16x16x32_bf16 v[94:97], v[150:153], v[198:201], v[94:97]
	v_mfma_f32_16x16x32_bf16 v[90:93], v[158:161], v[198:201], v[90:93]
	v_mfma_f32_16x16x32_bf16 v[78:81], v[150:153], v[210:213], v[78:81]
	v_mfma_f32_16x16x32_bf16 v[74:77], v[158:161], v[210:213], v[74:77]
	v_mfma_f32_16x16x32_bf16 v[126:129], v[154:157], v[186:189], v[126:129]
	v_mfma_f32_16x16x32_bf16 v[122:125], v[162:165], v[186:189], v[122:125]
	v_mfma_f32_16x16x32_bf16 v[110:113], v[154:157], v[194:197], v[110:113]
	v_mfma_f32_16x16x32_bf16 v[106:109], v[162:165], v[194:197], v[106:109]
	v_mfma_f32_16x16x32_bf16 v[94:97], v[154:157], v[202:205], v[94:97]
	v_mfma_f32_16x16x32_bf16 v[90:93], v[162:165], v[202:205], v[90:93]
	v_mfma_f32_16x16x32_bf16 v[78:81], v[154:157], v[214:217], v[78:81]
	v_mfma_f32_16x16x32_bf16 v[74:77], v[162:165], v[214:217], v[74:77]
	v_mfma_f32_16x16x32_bf16 v[118:121], v[166:169], v[182:185], v[118:121]
	v_mfma_f32_16x16x32_bf16 v[114:117], v[174:177], v[182:185], v[114:117]
	v_mfma_f32_16x16x32_bf16 v[102:105], v[166:169], v[190:193], v[102:105]
	v_mfma_f32_16x16x32_bf16 v[98:101], v[174:177], v[190:193], v[98:101]
	v_mfma_f32_16x16x32_bf16 v[86:89], v[166:169], v[198:201], v[86:89]
	v_mfma_f32_16x16x32_bf16 v[82:85], v[174:177], v[198:201], v[82:85]
	v_mfma_f32_16x16x32_bf16 v[70:73], v[166:169], v[210:213], v[70:73]
	v_mfma_f32_16x16x32_bf16 v[66:69], v[174:177], v[210:213], v[66:69]
	v_mfma_f32_16x16x32_bf16 v[118:121], v[170:173], v[186:189], v[118:121]
	v_mfma_f32_16x16x32_bf16 v[114:117], v[178:181], v[186:189], v[114:117]
	v_mfma_f32_16x16x32_bf16 v[102:105], v[170:173], v[194:197], v[102:105]
	v_mfma_f32_16x16x32_bf16 v[98:101], v[178:181], v[194:197], v[98:101]
	v_mfma_f32_16x16x32_bf16 v[86:89], v[170:173], v[202:205], v[86:89]
	v_mfma_f32_16x16x32_bf16 v[82:85], v[178:181], v[202:205], v[82:85]
	v_mfma_f32_16x16x32_bf16 v[70:73], v[170:173], v[214:217], v[70:73]
	v_mfma_f32_16x16x32_bf16 v[66:69], v[178:181], v[214:217], v[66:69]
	s_setprio 0
	s_barrier
	s_and_b64 s[18:19], vcc, exec
	s_movk_i32 s7, 0xff00
	s_cselect_b32 s16, 0x4000, s7
	s_cselect_b32 s28, 0, -1
	s_add_i32 s7, s65, s24
	v_cndmask_b32_e32 v130, v132, v136, vcc
	s_and_b64 s[18:19], vcc, exec
	v_and_b32_e32 v130, -2, v130
	s_cselect_b32 s29, 0x2000, s64
	v_lshl_add_u64 v[138:139], s[96:97], 0, v[130:131]
	s_mov_b32 m0, s7
	s_add_u32 s18, s96, s29
	ds_read_b128 v[182:185], v148 offset:16384
	ds_read_b128 v[186:189], v148 offset:17408
	ds_read_b128 v[190:193], v148 offset:18432
	ds_read_b128 v[194:197], v148 offset:19456
	ds_read_b128 v[198:201], v148 offset:20480
	ds_read_b128 v[202:205], v148 offset:21504
	ds_read_b128 v[210:213], v148 offset:22528
	ds_read_b128 v[214:217], v148 offset:23552
	global_load_lds_dwordx4 v[138:139], off
	s_addc_u32 s19, s97, s28
	s_add_i32 m0, s7, 0x2000
	v_lshl_add_u64 v[138:139], s[18:19], 0, v[130:131]
	s_add_u32 s18, s96, s16
	s_addc_u32 s19, s97, s28
	s_add_i32 s7, s34, s24
	global_load_lds_dwordx4 v[138:139], off
	v_lshl_add_u64 v[138:139], s[18:19], 0, v[130:131]
	s_add_u32 s18, s18, s29
	s_mov_b32 m0, s7
	s_addc_u32 s19, s19, s28
	global_load_lds_dwordx4 v[138:139], off
	v_lshl_add_u64 v[138:139], s[18:19], 0, v[130:131]
	s_add_i32 m0, s7, 0x2000
	s_nop 0
	global_load_lds_dwordx4 v[138:139], off
	v_lshl_add_u64 v[138:139], s[68:69], 0, v[134:135]
	s_mov_b32 m0, s25
	v_lshl_add_u64 v[206:207], v[138:139], 0, s[22:23]
	global_load_lds_dwordx4 v[138:139], off
	s_mov_b32 m0, s10
	s_nop 0
	global_load_lds_dwordx4 v[206:207], off
	s_waitcnt vmcnt(8)
	s_waitcnt lgkmcnt(0)
	s_barrier
; #define G8_STA(bufoff, ptr, sg, h) G8_STAGE1(bufoff, (ptr) + (h) * ((sg) ? hA1 : hA0), ((sg) ? voffA1 : voffA0), ((sg) ? r64A1 : r64A0))
; #define G8_STB(bufoff, ptr, sg, h) G8_STAGE1(bufoff, (ptr) + (h) * ((sg) ? hB1 : hB0), ((sg) ? voffB1 : voffB0), ((sg) ? r64B1 : r64B0))
; #define G8_LDA(dst, b, h) do { _Pragma("unroll") for (int m = 0; m < 4; ++m) _Pragma("unroll") for (int k = 0; k < 2; ++k) dst[m][k] = *(const LAS bf16x8*)(lds + G8_SA(b, h) + aoff + m * 2048 + k * 1024); } while (0)
; #define G8_LDB(dst, b, h) do { _Pragma("unroll") for (int n = 0; n < 2; ++n) _Pragma("unroll") for (int k = 0; k < 2; ++k) dst[n][k] = *(const LAS bf16x8*)(lds + G8_SB(b, h) + boff + n * 2048 + k * 1024); } while (0)
; #define G8_MMA(ai, bj, At, Bt) do { __builtin_amdgcn_s_setprio(1); _Pragma("unroll") for (int m = 0; m < 4; ++m) _Pragma("unroll") for (int n = 0; n < 2; ++n) _Pragma("unroll") for (int k = 0; k < 2; ++k) \
;         acc[ai][bj][m][n] = __builtin_amdgcn_mfma_f32_16x16x32_bf16(Bt[n][k], At[m][k], acc[ai][bj][m][n], 0, 0, 0); __builtin_amdgcn_s_setprio(0); } while (0)
; #define G8_WAIT_V(n) asm volatile("s_waitcnt vmcnt(" #n ")" ::: "memory")
; #define G8_WAIT_L(n) asm volatile("s_waitcnt lgkmcnt(" #n ")" ::: "memory")
; #define G8_BAR __builtin_amdgcn_s_barrier()
; #define G8_SCHED __builtin_amdgcn_sched_barrier(0)
; template <class P>
; __device__ __forceinline__ void gemm_phase(LAS unsigned char* lds, const P& p, const int G, const int c) {
;     ...
;             G8_LDA(At, 0, 1); G8_STB(G8_SB(0, 0), b2, sg2, 0); G8_STB(G8_SB(0, 1), b2, sg2, 1); G8_STA(G8_SA(0, 0), a2, sg2, 0);
;             G8_WAIT_V(8); G8_WAIT_L(0); G8_BAR; G8_MMA(1, 0, At, B0); G8_MMA(1, 1, At, B1); G8_BAR; G8_SCHED;
;             G8_LDB(B0, 1, 0); G8_LDB(B1, 1, 1); G8_SCHED; G8_LDA(At, 1, 0); G8_STA(G8_SA(0, 1), a2, sg2, 1);
;             G8_WAIT_V(8); G8_WAIT_L(0); G8_BAR; G8_MMA(0, 0, At, B0); G8_MMA(0, 1, At, B1); G8_BAR; G8_SCHED;
;             G8_LDA(At, 1, 1); G8_STB(G8_SB(1, 0), b3, sg2, 0); G8_STB(G8_SB(1, 1), b3, sg2, 1); G8_STA(G8_SA(1, 0), a3, sg2, 0);
	s_setprio 1
	s_waitcnt lgkmcnt(0)
	v_mfma_f32_16x16x32_bf16 v[62:65], v[150:153], v[182:185], v[62:65]
	v_mfma_f32_16x16x32_bf16 v[58:61], v[158:161], v[182:185], v[58:61]
	v_mfma_f32_16x16x32_bf16 v[46:49], v[150:153], v[190:193], v[46:49]
	v_mfma_f32_16x16x32_bf16 v[42:45], v[158:161], v[190:193], v[42:45]
	v_mfma_f32_16x16x32_bf16 v[30:33], v[150:153], v[198:201], v[30:33]
	v_mfma_f32_16x16x32_bf16 v[26:29], v[158:161], v[198:201], v[26:29]
	v_mfma_f32_16x16x32_bf16 v[14:17], v[150:153], v[210:213], v[14:17]
	v_mfma_f32_16x16x32_bf16 v[10:13], v[158:161], v[210:213], v[10:13]
	v_mfma_f32_16x16x32_bf16 v[62:65], v[154:157], v[186:189], v[62:65]
	v_mfma_f32_16x16x32_bf16 v[58:61], v[162:165], v[186:189], v[58:61]
	v_mfma_f32_16x16x32_bf16 v[46:49], v[154:157], v[194:197], v[46:49]
	v_mfma_f32_16x16x32_bf16 v[42:45], v[162:165], v[194:197], v[42:45]
	v_mfma_f32_16x16x32_bf16 v[30:33], v[154:157], v[202:205], v[30:33]
	v_mfma_f32_16x16x32_bf16 v[26:29], v[162:165], v[202:205], v[26:29]
	v_mfma_f32_16x16x32_bf16 v[14:17], v[154:157], v[214:217], v[14:17]
	v_mfma_f32_16x16x32_bf16 v[10:13], v[162:165], v[214:217], v[10:13]
	v_mfma_f32_16x16x32_bf16 v[54:57], v[166:169], v[182:185], v[54:57]
	v_mfma_f32_16x16x32_bf16 v[50:53], v[174:177], v[182:185], v[50:53]
	v_mfma_f32_16x16x32_bf16 v[38:41], v[166:169], v[190:193], v[38:41]
	v_mfma_f32_16x16x32_bf16 v[34:37], v[174:177], v[190:193], v[34:37]
	v_mfma_f32_16x16x32_bf16 v[22:25], v[166:169], v[198:201], v[22:25]
	v_mfma_f32_16x16x32_bf16 v[18:21], v[174:177], v[198:201], v[18:21]
	v_mfma_f32_16x16x32_bf16 v[6:9], v[166:169], v[210:213], v[6:9]
	v_mfma_f32_16x16x32_bf16 v[2:5], v[174:177], v[210:213], v[2:5]
	v_mfma_f32_16x16x32_bf16 v[54:57], v[170:173], v[186:189], v[54:57]
	v_mfma_f32_16x16x32_bf16 v[50:53], v[178:181], v[186:189], v[50:53]
	v_mfma_f32_16x16x32_bf16 v[38:41], v[170:173], v[194:197], v[38:41]
	v_mfma_f32_16x16x32_bf16 v[34:37], v[178:181], v[194:197], v[34:37]
	v_mfma_f32_16x16x32_bf16 v[22:25], v[170:173], v[202:205], v[22:25]
	v_mfma_f32_16x16x32_bf16 v[18:21], v[178:181], v[202:205], v[18:21]
	v_mfma_f32_16x16x32_bf16 v[6:9], v[170:173], v[214:217], v[6:9]
	v_mfma_f32_16x16x32_bf16 v[2:5], v[178:181], v[214:217], v[2:5]
	s_setprio 0
	s_barrier
	v_add_u32_e32 v149, s35, v137
	ds_read_b128 v[150:153], v149
	ds_read_b128 v[154:157], v149 offset:1024
	ds_read_b128 v[158:161], v149 offset:2048
	ds_read_b128 v[162:165], v149 offset:3072
	v_add_u32_e32 v149, s20, v137
	ds_read_b128 v[166:169], v149
	ds_read_b128 v[170:173], v149 offset:1024
	ds_read_b128 v[174:177], v149 offset:2048
	ds_read_b128 v[178:181], v149 offset:3072
	s_mov_b32 m0, s11
	v_lshl_add_u64 v[206:207], v[138:139], 0, s[36:37]
	ds_read_b128 v[182:185], v148 offset:32768
	ds_read_b128 v[186:189], v148 offset:33792
	ds_read_b128 v[190:193], v148 offset:34816
	ds_read_b128 v[194:197], v148 offset:35840
	ds_read_b128 v[198:201], v148 offset:36864
	ds_read_b128 v[202:205], v148 offset:37888
	ds_read_b128 v[210:213], v148 offset:38912
	ds_read_b128 v[214:217], v148 offset:39936
	global_load_lds_dwordx4 v[206:207], off
	v_lshl_add_u64 v[206:207], v[138:139], 0, s[38:39]
	s_mov_b32 m0, s33
	s_nop 0
	global_load_lds_dwordx4 v[206:207], off
	s_waitcnt vmcnt(8)
	s_waitcnt lgkmcnt(0)
	s_barrier
	s_setprio 1
	s_waitcnt lgkmcnt(0)
	v_mfma_f32_16x16x32_bf16 v[126:129], v[150:153], v[182:185], v[126:129]
	v_mfma_f32_16x16x32_bf16 v[122:125], v[158:161], v[182:185], v[122:125]
	v_mfma_f32_16x16x32_bf16 v[110:113], v[150:153], v[190:193], v[110:113]
	v_mfma_f32_16x16x32_bf16 v[106:109], v[158:161], v[190:193], v[106:109]
	v_mfma_f32_16x16x32_bf16 v[94:97], v[150:153], v[198:201], v[94:97]
	v_mfma_f32_16x16x32_bf16 v[90:93], v[158:161], v[198:201], v[90:93]
	v_mfma_f32_16x16x32_bf16 v[78:81], v[150:153], v[210:213], v[78:81]
	v_mfma_f32_16x16x32_bf16 v[74:77], v[158:161], v[210:213], v[74:77]
	v_mfma_f32_16x16x32_bf16 v[126:129], v[154:157], v[186:189], v[126:129]
	v_mfma_f32_16x16x32_bf16 v[122:125], v[162:165], v[186:189], v[122:125]
	v_mfma_f32_16x16x32_bf16 v[110:113], v[154:157], v[194:197], v[110:113]
	v_mfma_f32_16x16x32_bf16 v[106:109], v[162:165], v[194:197], v[106:109]
	v_mfma_f32_16x16x32_bf16 v[94:97], v[154:157], v[202:205], v[94:97]
	v_mfma_f32_16x16x32_bf16 v[90:93], v[162:165], v[202:205], v[90:93]
	v_mfma_f32_16x16x32_bf16 v[78:81], v[154:157], v[214:217], v[78:81]
	v_mfma_f32_16x16x32_bf16 v[74:77], v[162:165], v[214:217], v[74:77]
	v_mfma_f32_16x16x32_bf16 v[118:121], v[166:169], v[182:185], v[118:121]
	v_mfma_f32_16x16x32_bf16 v[114:117], v[174:177], v[182:185], v[114:117]
	v_mfma_f32_16x16x32_bf16 v[102:105], v[166:169], v[190:193], v[102:105]
	v_mfma_f32_16x16x32_bf16 v[98:101], v[174:177], v[190:193], v[98:101]
	v_mfma_f32_16x16x32_bf16 v[86:89], v[166:169], v[198:201], v[86:89]
	v_mfma_f32_16x16x32_bf16 v[82:85], v[174:177], v[198:201], v[82:85]
	v_mfma_f32_16x16x32_bf16 v[70:73], v[166:169], v[210:213], v[70:73]
	v_mfma_f32_16x16x32_bf16 v[66:69], v[174:177], v[210:213], v[66:69]
	v_mfma_f32_16x16x32_bf16 v[118:121], v[170:173], v[186:189], v[118:121]
	v_mfma_f32_16x16x32_bf16 v[114:117], v[178:181], v[186:189], v[114:117]
	v_mfma_f32_16x16x32_bf16 v[102:105], v[170:173], v[194:197], v[102:105]
	v_mfma_f32_16x16x32_bf16 v[98:101], v[178:181], v[194:197], v[98:101]
	v_mfma_f32_16x16x32_bf16 v[86:89], v[170:173], v[202:205], v[86:89]
	v_mfma_f32_16x16x32_bf16 v[82:85], v[178:181], v[202:205], v[82:85]
	v_mfma_f32_16x16x32_bf16 v[70:73], v[170:173], v[214:217], v[70:73]
	v_mfma_f32_16x16x32_bf16 v[66:69], v[178:181], v[214:217], v[66:69]
	s_setprio 0
	s_barrier
; #define G8_STA(bufoff, ptr, sg, h) G8_STAGE1(bufoff, (ptr) + (h) * ((sg) ? hA1 : hA0), ((sg) ? voffA1 : voffA0), ((sg) ? r64A1 : r64A0))
; #define G8_STB(bufoff, ptr, sg, h) G8_STAGE1(bufoff, (ptr) + (h) * ((sg) ? hB1 : hB0), ((sg) ? voffB1 : voffB0), ((sg) ? r64B1 : r64B0))
; #define G8_LDA(dst, b, h) do { _Pragma("unroll") for (int m = 0; m < 4; ++m) _Pragma("unroll") for (int k = 0; k < 2; ++k) dst[m][k] = *(const LAS bf16x8*)(lds + G8_SA(b, h) + aoff + m * 2048 + k * 1024); } while (0)
; #define G8_MMA(ai, bj, At, Bt) do { __builtin_amdgcn_s_setprio(1); _Pragma("unroll") for (int m = 0; m < 4; ++m) _Pragma("unroll") for (int n = 0; n < 2; ++n) _Pragma("unroll") for (int k = 0; k < 2; ++k) \
;         acc[ai][bj][m][n] = __builtin_amdgcn_mfma_f32_16x16x32_bf16(Bt[n][k], At[m][k], acc[ai][bj][m][n], 0, 0, 0); __builtin_amdgcn_s_setprio(0); } while (0)
; #define G8_WAIT_V(n) asm volatile("s_waitcnt vmcnt(" #n ")" ::: "memory")
; #define G8_WAIT_L(n) asm volatile("s_waitcnt lgkmcnt(" #n ")" ::: "memory")
; #define G8_BAR __builtin_amdgcn_s_barrier()
; #define G8_SCHED __builtin_amdgcn_sched_barrier(0)
; template <class P>
; __device__ __forceinline__ void gemm_phase(LAS unsigned char* lds, const P& p, const int G, const int c) {
;     ...
;             G8_LDA(At, 1, 1); G8_STB(G8_SB(1, 0), b3, sg2, 0); G8_STB(G8_SB(1, 1), b3, sg2, 1); G8_STA(G8_SA(1, 0), a3, sg2, 0);
;             G8_WAIT_V(8); G8_WAIT_L(0); G8_BAR; G8_MMA(1, 0, At, B0); G8_MMA(1, 1, At, B1); G8_BAR; G8_SCHED;
;         }
	s_add_u32 s6, s96, s6
	s_addc_u32 s7, s97, 0
	s_add_i32 s57, s35, s24
	v_lshl_add_u64 v[206:207], s[6:7], 0, v[130:131]
	s_mov_b32 m0, s57
	s_add_u32 s18, s6, s29
	ds_read_b128 v[182:185], v148 offset:49152
	ds_read_b128 v[186:189], v148 offset:50176
	ds_read_b128 v[190:193], v148 offset:51200
	ds_read_b128 v[194:197], v148 offset:52224
	ds_read_b128 v[198:201], v148 offset:53248
	ds_read_b128 v[202:205], v148 offset:54272
	ds_read_b128 v[210:213], v148 offset:55296
	ds_read_b128 v[214:217], v148 offset:56320
	global_load_lds_dwordx4 v[206:207], off
	s_addc_u32 s19, s7, s28
	s_add_i32 m0, s57, 0x2000
	s_add_u32 s6, s6, s16
	v_lshl_add_u64 v[206:207], s[18:19], 0, v[130:131]
	s_addc_u32 s7, s7, s28
	s_add_i32 s16, s20, s24
	global_load_lds_dwordx4 v[206:207], off
	v_lshl_add_u64 v[206:207], s[6:7], 0, v[130:131]
	s_add_u32 s6, s6, s29
	s_mov_b32 m0, s16
	s_addc_u32 s7, s7, s28
	global_load_lds_dwordx4 v[206:207], off
	v_lshl_add_u64 v[206:207], s[6:7], 0, v[130:131]
	s_add_i32 m0, s16, 0x2000
	s_nop 0
	global_load_lds_dwordx4 v[206:207], off
	v_lshl_add_u64 v[206:207], v[138:139], 0, s[40:41]
	s_mov_b32 m0, s47
	v_lshl_add_u64 v[138:139], v[138:139], 0, s[42:43]
	global_load_lds_dwordx4 v[206:207], off
	s_mov_b32 m0, s50
	s_nop 0
	global_load_lds_dwordx4 v[138:139], off
	s_waitcnt vmcnt(8)
	s_waitcnt lgkmcnt(0)
	s_barrier
	s_setprio 1
	s_waitcnt lgkmcnt(0)
	v_mfma_f32_16x16x32_bf16 v[62:65], v[150:153], v[182:185], v[62:65]
	v_mfma_f32_16x16x32_bf16 v[58:61], v[158:161], v[182:185], v[58:61]
	v_mfma_f32_16x16x32_bf16 v[46:49], v[150:153], v[190:193], v[46:49]
	v_mfma_f32_16x16x32_bf16 v[42:45], v[158:161], v[190:193], v[42:45]
	v_mfma_f32_16x16x32_bf16 v[30:33], v[150:153], v[198:201], v[30:33]
	v_mfma_f32_16x16x32_bf16 v[26:29], v[158:161], v[198:201], v[26:29]
	v_mfma_f32_16x16x32_bf16 v[14:17], v[150:153], v[210:213], v[14:17]
	v_mfma_f32_16x16x32_bf16 v[10:13], v[158:161], v[210:213], v[10:13]
	v_mfma_f32_16x16x32_bf16 v[62:65], v[154:157], v[186:189], v[62:65]
	v_mfma_f32_16x16x32_bf16 v[58:61], v[162:165], v[186:189], v[58:61]
	v_mfma_f32_16x16x32_bf16 v[46:49], v[154:157], v[194:197], v[46:49]
	v_mfma_f32_16x16x32_bf16 v[42:45], v[162:165], v[194:197], v[42:45]
	v_mfma_f32_16x16x32_bf16 v[30:33], v[154:157], v[202:205], v[30:33]
	v_mfma_f32_16x16x32_bf16 v[26:29], v[162:165], v[202:205], v[26:29]
	v_mfma_f32_16x16x32_bf16 v[14:17], v[154:157], v[214:217], v[14:17]
	v_mfma_f32_16x16x32_bf16 v[10:13], v[162:165], v[214:217], v[10:13]
	v_mfma_f32_16x16x32_bf16 v[54:57], v[166:169], v[182:185], v[54:57]
	v_mfma_f32_16x16x32_bf16 v[50:53], v[174:177], v[182:185], v[50:53]
	v_mfma_f32_16x16x32_bf16 v[38:41], v[166:169], v[190:193], v[38:41]
	v_mfma_f32_16x16x32_bf16 v[34:37], v[174:177], v[190:193], v[34:37]
	v_mfma_f32_16x16x32_bf16 v[22:25], v[166:169], v[198:201], v[22:25]
	v_mfma_f32_16x16x32_bf16 v[18:21], v[174:177], v[198:201], v[18:21]
	v_mfma_f32_16x16x32_bf16 v[6:9], v[166:169], v[210:213], v[6:9]
	v_mfma_f32_16x16x32_bf16 v[2:5], v[174:177], v[210:213], v[2:5]
	v_mfma_f32_16x16x32_bf16 v[54:57], v[170:173], v[186:189], v[54:57]
	v_mfma_f32_16x16x32_bf16 v[50:53], v[178:181], v[186:189], v[50:53]
	v_mfma_f32_16x16x32_bf16 v[38:41], v[170:173], v[194:197], v[38:41]
	v_mfma_f32_16x16x32_bf16 v[34:37], v[178:181], v[194:197], v[34:37]
	v_mfma_f32_16x16x32_bf16 v[22:25], v[170:173], v[202:205], v[22:25]
	v_mfma_f32_16x16x32_bf16 v[18:21], v[178:181], v[202:205], v[18:21]
	v_mfma_f32_16x16x32_bf16 v[6:9], v[170:173], v[214:217], v[6:9]
	v_mfma_f32_16x16x32_bf16 v[2:5], v[178:181], v[214:217], v[2:5]
	s_setprio 0
	s_barrier
	s_add_i32 s79, s79, 1
	s_add_u32 s90, s90, 0x20000
	s_addc_u32 s91, s91, 0
	s_add_u32 s92, s92, 0x40000
	s_addc_u32 s93, s93, 0
	s_add_u32 s94, s94, 0x40000
	s_addc_u32 s95, s95, 0
	s_cmp_gt_u32 s56, 9
	s_mov_b32 s18, s56
	s_cbranch_scc1 .LBB0_604

; #define G8_STA(bufoff, ptr, sg, h) G8_STAGE1(bufoff, (ptr) + (h) * ((sg) ? hA1 : hA0), ((sg) ? voffA1 : voffA0), ((sg) ? r64A1 : r64A0))
; #define G8_STB(bufoff, ptr, sg, h) G8_STAGE1(bufoff, (ptr) + (h) * ((sg) ? hB1 : hB0), ((sg) ? voffB1 : voffB0), ((sg) ? r64B1 : r64B0))
; #define G8_LDA(dst, b, h) do { _Pragma("unroll") for (int m = 0; m < 4; ++m) _Pragma("unroll") for (int k = 0; k < 2; ++k) dst[m][k] = *(const LAS bf16x8*)(lds + G8_SA(b, h) + aoff + m * 2048 + k * 1024); } while (0)
; #define G8_LDB(dst, b, h) do { _Pragma("unroll") for (int n = 0; n < 2; ++n) _Pragma("unroll") for (int k = 0; k < 2; ++k) dst[n][k] = *(const LAS bf16x8*)(lds + G8_SB(b, h) + boff + n * 2048 + k * 1024); } while (0)
; #define G8_MMA(ai, bj, At, Bt) do { __builtin_amdgcn_s_setprio(1); _Pragma("unroll") for (int m = 0; m < 4; ++m) _Pragma("unroll") for (int n = 0; n < 2; ++n) _Pragma("unroll") for (int k = 0; k < 2; ++k) \
;         acc[ai][bj][m][n] = __builtin_amdgcn_mfma_f32_16x16x32_bf16(Bt[n][k], At[m][k], acc[ai][bj][m][n], 0, 0, 0); __builtin_amdgcn_s_setprio(0); } while (0)
; #define G8_BAR __builtin_amdgcn_s_barrier()
; template <class P>
; __device__ __forceinline__ void gemm_phase(LAS unsigned char* lds, const P& p, const int G, const int c) {
;     ...
;         for (int t = 0; t < nt; t += 2) {
;             const bool last = (t == nt - 2);
;             const bool sg1 = (NS > 1) && (t + 1 >= nt0);
;             const bool sg2 = (NS > 1) && !last && (t + 2 >= nt0);
;             const char* a1 = sg1 ? cA1 + (long)(t + 1 - nt0) * ksA1 : cA0 + (long)(t + 1) * ksA0;
;             const char* a2 = last ? nA0 : (sg2 ? cA1 + (long)(t + 2 - nt0) * ksA1 : cA0 + (long)(t + 2) * ksA0);
;             const char* b2 = last ? nB0 : (sg2 ? cB1 + (long)(t + 2 - nt0) * ksB1 : cB0 + (long)(t + 2) * ksB0);
;             const char* a3 = a2 + (sg2 ? ksA1 : ksA0); const char* b3 = b2 + (sg2 ? ksB1 : ksB0);
;             G8_LDB(B0, 0, 0); G8_LDB(B1, 0, 1); G8_SCHED; G8_LDA(At, 0, 0); G8_STA(G8_SA(1, 1), a1, sg1, 1);
;             G8_WAIT_V(8); G8_WAIT_L(0); G8_BAR; G8_MMA(0, 0, At, B0); G8_MMA(0, 1, At, B1); G8_BAR; G8_SCHED;
;             G8_LDA(At, 0, 1); G8_STB(G8_SB(0, 0), b2, sg2, 0); G8_STB(G8_SB(0, 1), b2, sg2, 1); G8_STA(G8_SA(0, 0), a2, sg2, 0);
;             G8_WAIT_V(8); G8_WAIT_L(0); G8_BAR; G8_MMA(1, 0, At, B0); G8_MMA(1, 1, At, B1); G8_BAR; G8_SCHED;
.LBB0_679:
	v_add_u32_e32 v153, s50, v1
	ds_read_b128 v[170:173], v153
	ds_read_b128 v[174:177], v153 offset:1024
	ds_read_b128 v[178:181], v153 offset:2048
	ds_read_b128 v[182:185], v153 offset:3072
	v_add_u32_e32 v153, s51, v1
	ds_read_b128 v[186:189], v153
	ds_read_b128 v[190:193], v153 offset:1024
	ds_read_b128 v[194:197], v153 offset:2048
	ds_read_b128 v[198:201], v153 offset:3072
	s_and_b64 s[30:31], exec, s[30:31]
	s_cselect_b32 s31, s18, s59
	s_cselect_b32 s30, s19, s53
	v_lshl_add_u64 v[206:207], v[168:169], 0, s[62:63]
	v_lshl_add_u64 v[238:239], v[206:207], 0, s[40:41]
	s_add_i32 m0, s27, 0xc000
	ds_read_b128 v[202:205], v151
	ds_read_b128 v[210:213], v151 offset:1024
	ds_read_b128 v[214:217], v151 offset:2048
	ds_read_b128 v[218:221], v151 offset:3072
	ds_read_b128 v[222:225], v151 offset:4096
	ds_read_b128 v[226:229], v151 offset:5120
	ds_read_b128 v[230:233], v151 offset:6144
	ds_read_b128 v[234:237], v151 offset:7168
	global_load_lds_dwordx4 v[238:239], off
	v_lshl_add_u64 v[206:207], v[206:207], 0, s[42:43]
	s_add_i32 m0, s27, 0xe000
	s_nop 0
	global_load_lds_dwordx4 v[206:207], off
	s_waitcnt vmcnt(8)
	s_waitcnt lgkmcnt(0)
	s_barrier
	s_setprio 1
	s_waitcnt lgkmcnt(0)
	v_mfma_f32_16x16x32_bf16 v[126:129], v[170:173], v[202:205], v[126:129]
	v_mfma_f32_16x16x32_bf16 v[122:125], v[178:181], v[202:205], v[122:125]
	v_mfma_f32_16x16x32_bf16 v[110:113], v[170:173], v[214:217], v[110:113]
	v_mfma_f32_16x16x32_bf16 v[106:109], v[178:181], v[214:217], v[106:109]
	v_mfma_f32_16x16x32_bf16 v[94:97], v[170:173], v[222:225], v[94:97]
	v_mfma_f32_16x16x32_bf16 v[90:93], v[178:181], v[222:225], v[90:93]
	v_mfma_f32_16x16x32_bf16 v[78:81], v[170:173], v[230:233], v[78:81]
	v_mfma_f32_16x16x32_bf16 v[74:77], v[178:181], v[230:233], v[74:77]
	v_mfma_f32_16x16x32_bf16 v[126:129], v[174:177], v[210:213], v[126:129]
	v_mfma_f32_16x16x32_bf16 v[122:125], v[182:185], v[210:213], v[122:125]
	v_mfma_f32_16x16x32_bf16 v[110:113], v[174:177], v[218:221], v[110:113]
	v_mfma_f32_16x16x32_bf16 v[106:109], v[182:185], v[218:221], v[106:109]
	v_mfma_f32_16x16x32_bf16 v[94:97], v[174:177], v[226:229], v[94:97]
	v_mfma_f32_16x16x32_bf16 v[90:93], v[182:185], v[226:229], v[90:93]
	v_mfma_f32_16x16x32_bf16 v[78:81], v[174:177], v[234:237], v[78:81]
	v_mfma_f32_16x16x32_bf16 v[74:77], v[182:185], v[234:237], v[74:77]
	v_mfma_f32_16x16x32_bf16 v[118:121], v[186:189], v[202:205], v[118:121]
	v_mfma_f32_16x16x32_bf16 v[114:117], v[194:197], v[202:205], v[114:117]
	v_mfma_f32_16x16x32_bf16 v[102:105], v[186:189], v[214:217], v[102:105]
	v_mfma_f32_16x16x32_bf16 v[98:101], v[194:197], v[214:217], v[98:101]
	v_mfma_f32_16x16x32_bf16 v[86:89], v[186:189], v[222:225], v[86:89]
	v_mfma_f32_16x16x32_bf16 v[82:85], v[194:197], v[222:225], v[82:85]
	v_mfma_f32_16x16x32_bf16 v[70:73], v[186:189], v[230:233], v[70:73]
	v_mfma_f32_16x16x32_bf16 v[66:69], v[194:197], v[230:233], v[66:69]
	v_mfma_f32_16x16x32_bf16 v[118:121], v[190:193], v[210:213], v[118:121]
	v_mfma_f32_16x16x32_bf16 v[114:117], v[198:201], v[210:213], v[114:117]
	v_mfma_f32_16x16x32_bf16 v[102:105], v[190:193], v[218:221], v[102:105]
	v_mfma_f32_16x16x32_bf16 v[98:101], v[198:201], v[218:221], v[98:101]
	v_mfma_f32_16x16x32_bf16 v[86:89], v[190:193], v[226:229], v[86:89]
	v_mfma_f32_16x16x32_bf16 v[82:85], v[198:201], v[226:229], v[82:85]
	v_mfma_f32_16x16x32_bf16 v[70:73], v[190:193], v[234:237], v[70:73]
	v_mfma_f32_16x16x32_bf16 v[66:69], v[198:201], v[234:237], v[66:69]
	s_setprio 0
	s_barrier
	v_lshl_add_u64 v[206:207], s[30:31], 0, v[130:131]
	s_add_i32 s30, s50, s26
	s_mov_b32 m0, s30
	ds_read_b128 v[202:205], v151 offset:16384
	ds_read_b128 v[210:213], v151 offset:17408
	ds_read_b128 v[214:217], v151 offset:18432
	ds_read_b128 v[218:221], v151 offset:19456
	ds_read_b128 v[222:225], v151 offset:20480
	ds_read_b128 v[226:229], v151 offset:21504
	ds_read_b128 v[230:233], v151 offset:22528
	ds_read_b128 v[234:237], v151 offset:23552
	global_load_lds_dwordx4 v[206:207], off
	v_lshl_add_u64 v[238:239], v[206:207], 0, s[0:1]
	s_add_i32 m0, s30, 0x2000
	s_add_i32 s30, s51, s26
	global_load_lds_dwordx4 v[238:239], off
	v_lshl_add_u64 v[238:239], v[206:207], 0, s[4:5]
	s_mov_b32 m0, s30
	s_nop 0
	global_load_lds_dwordx4 v[238:239], off
	v_lshl_add_u64 v[238:239], v[206:207], 0, s[6:7]
	s_add_i32 m0, s30, 0x2000
	s_nop 0
	global_load_lds_dwordx4 v[238:239], off
	v_lshl_add_u64 v[238:239], s[28:29], 0, v[132:133]
	s_mov_b32 m0, s27
	v_lshl_add_u64 v[240:241], v[238:239], 0, s[0:1]
	global_load_lds_dwordx4 v[238:239], off
	s_mov_b32 m0, s33
	s_nop 0
	global_load_lds_dwordx4 v[240:241], off
	s_waitcnt vmcnt(8)
	s_waitcnt lgkmcnt(0)
	s_barrier
; #define G8_STA(bufoff, ptr, sg, h) G8_STAGE1(bufoff, (ptr) + (h) * ((sg) ? hA1 : hA0), ((sg) ? voffA1 : voffA0), ((sg) ? r64A1 : r64A0))
; #define G8_LDA(dst, b, h) do { _Pragma("unroll") for (int m = 0; m < 4; ++m) _Pragma("unroll") for (int k = 0; k < 2; ++k) dst[m][k] = *(const LAS bf16x8*)(lds + G8_SA(b, h) + aoff + m * 2048 + k * 1024); } while (0)
; #define G8_LDB(dst, b, h) do { _Pragma("unroll") for (int n = 0; n < 2; ++n) _Pragma("unroll") for (int k = 0; k < 2; ++k) dst[n][k] = *(const LAS bf16x8*)(lds + G8_SB(b, h) + boff + n * 2048 + k * 1024); } while (0)
; #define G8_MMA(ai, bj, At, Bt) do { __builtin_amdgcn_s_setprio(1); _Pragma("unroll") for (int m = 0; m < 4; ++m) _Pragma("unroll") for (int n = 0; n < 2; ++n) _Pragma("unroll") for (int k = 0; k < 2; ++k) \
;         acc[ai][bj][m][n] = __builtin_amdgcn_mfma_f32_16x16x32_bf16(Bt[n][k], At[m][k], acc[ai][bj][m][n], 0, 0, 0); __builtin_amdgcn_s_setprio(0); } while (0)
; #define G8_WAIT_V(n) asm volatile("s_waitcnt vmcnt(" #n ")" ::: "memory")
; #define G8_WAIT_L(n) asm volatile("s_waitcnt lgkmcnt(" #n ")" ::: "memory")
; #define G8_BAR __builtin_amdgcn_s_barrier()
; #define G8_SCHED __builtin_amdgcn_sched_barrier(0)
; template <class P>
; __device__ __forceinline__ void gemm_phase(LAS unsigned char* lds, const P& p, const int G, const int c) {
;     ...
;             G8_WAIT_V(8); G8_WAIT_L(0); G8_BAR; G8_MMA(1, 0, At, B0); G8_MMA(1, 1, At, B1); G8_BAR; G8_SCHED;
;             G8_LDB(B0, 1, 0); G8_LDB(B1, 1, 1); G8_SCHED; G8_LDA(At, 1, 0); G8_STA(G8_SA(0, 1), a2, sg2, 1);
;             G8_WAIT_V(8); G8_WAIT_L(0); G8_BAR; G8_MMA(0, 0, At, B0); G8_MMA(0, 1, At, B1); G8_BAR; G8_SCHED;
	s_setprio 1
	s_waitcnt lgkmcnt(0)
	v_mfma_f32_16x16x32_bf16 v[62:65], v[170:173], v[202:205], v[62:65]
	v_mfma_f32_16x16x32_bf16 v[58:61], v[178:181], v[202:205], v[58:61]
	v_mfma_f32_16x16x32_bf16 v[46:49], v[170:173], v[214:217], v[46:49]
	v_mfma_f32_16x16x32_bf16 v[42:45], v[178:181], v[214:217], v[42:45]
	v_mfma_f32_16x16x32_bf16 v[30:33], v[170:173], v[222:225], v[30:33]
	v_mfma_f32_16x16x32_bf16 v[26:29], v[178:181], v[222:225], v[26:29]
	v_mfma_f32_16x16x32_bf16 v[14:17], v[170:173], v[230:233], v[14:17]
	v_mfma_f32_16x16x32_bf16 v[10:13], v[178:181], v[230:233], v[10:13]
	v_mfma_f32_16x16x32_bf16 v[62:65], v[174:177], v[210:213], v[62:65]
	v_mfma_f32_16x16x32_bf16 v[58:61], v[182:185], v[210:213], v[58:61]
	v_mfma_f32_16x16x32_bf16 v[46:49], v[174:177], v[218:221], v[46:49]
	v_mfma_f32_16x16x32_bf16 v[42:45], v[182:185], v[218:221], v[42:45]
	v_mfma_f32_16x16x32_bf16 v[30:33], v[174:177], v[226:229], v[30:33]
	v_mfma_f32_16x16x32_bf16 v[26:29], v[182:185], v[226:229], v[26:29]
	v_mfma_f32_16x16x32_bf16 v[14:17], v[174:177], v[234:237], v[14:17]
	v_mfma_f32_16x16x32_bf16 v[10:13], v[182:185], v[234:237], v[10:13]
	v_mfma_f32_16x16x32_bf16 v[54:57], v[186:189], v[202:205], v[54:57]
	v_mfma_f32_16x16x32_bf16 v[50:53], v[194:197], v[202:205], v[50:53]
	v_mfma_f32_16x16x32_bf16 v[38:41], v[186:189], v[214:217], v[38:41]
	v_mfma_f32_16x16x32_bf16 v[34:37], v[194:197], v[214:217], v[34:37]
	v_mfma_f32_16x16x32_bf16 v[22:25], v[186:189], v[222:225], v[22:25]
	v_mfma_f32_16x16x32_bf16 v[18:21], v[194:197], v[222:225], v[18:21]
	v_mfma_f32_16x16x32_bf16 v[6:9], v[186:189], v[230:233], v[6:9]
	v_mfma_f32_16x16x32_bf16 v[2:5], v[194:197], v[230:233], v[2:5]
	v_mfma_f32_16x16x32_bf16 v[54:57], v[190:193], v[210:213], v[54:57]
	v_mfma_f32_16x16x32_bf16 v[50:53], v[198:201], v[210:213], v[50:53]
	v_mfma_f32_16x16x32_bf16 v[38:41], v[190:193], v[218:221], v[38:41]
	v_mfma_f32_16x16x32_bf16 v[34:37], v[198:201], v[218:221], v[34:37]
	v_mfma_f32_16x16x32_bf16 v[22:25], v[190:193], v[226:229], v[22:25]
	v_mfma_f32_16x16x32_bf16 v[18:21], v[198:201], v[226:229], v[18:21]
	v_mfma_f32_16x16x32_bf16 v[6:9], v[190:193], v[234:237], v[6:9]
	v_mfma_f32_16x16x32_bf16 v[2:5], v[198:201], v[234:237], v[2:5]
	s_setprio 0
	s_barrier
	s_add_i32 s28, 0, 0x18000
	v_add_u32_e32 v153, s28, v1
	s_add_i32 s29, 0, 0x1c000
	ds_read_b128 v[170:173], v153
	ds_read_b128 v[174:177], v153 offset:1024
	ds_read_b128 v[178:181], v153 offset:2048
	ds_read_b128 v[182:185], v153 offset:3072
	v_add_u32_e32 v153, s29, v1
	ds_read_b128 v[186:189], v153
	ds_read_b128 v[190:193], v153 offset:1024
	ds_read_b128 v[194:197], v153 offset:2048
	ds_read_b128 v[198:201], v153 offset:3072
	s_mov_b32 m0, s34
	v_lshl_add_u64 v[240:241], v[238:239], 0, s[4:5]
	ds_read_b128 v[202:205], v151 offset:32768
	ds_read_b128 v[210:213], v151 offset:33792
	ds_read_b128 v[214:217], v151 offset:34816
	ds_read_b128 v[218:221], v151 offset:35840
	ds_read_b128 v[222:225], v151 offset:36864
	ds_read_b128 v[226:229], v151 offset:37888
	ds_read_b128 v[230:233], v151 offset:38912
	ds_read_b128 v[234:237], v151 offset:39936
	global_load_lds_dwordx4 v[240:241], off
	v_lshl_add_u64 v[240:241], v[238:239], 0, s[6:7]
	s_mov_b32 m0, s35
	s_nop 0
	global_load_lds_dwordx4 v[240:241], off
	s_waitcnt vmcnt(8)
	s_waitcnt lgkmcnt(0)
	s_barrier
	s_setprio 1
	s_waitcnt lgkmcnt(0)
	v_mfma_f32_16x16x32_bf16 v[126:129], v[170:173], v[202:205], v[126:129]
	v_mfma_f32_16x16x32_bf16 v[122:125], v[178:181], v[202:205], v[122:125]
	v_mfma_f32_16x16x32_bf16 v[110:113], v[170:173], v[214:217], v[110:113]
	v_mfma_f32_16x16x32_bf16 v[106:109], v[178:181], v[214:217], v[106:109]
	v_mfma_f32_16x16x32_bf16 v[94:97], v[170:173], v[222:225], v[94:97]
	v_mfma_f32_16x16x32_bf16 v[90:93], v[178:181], v[222:225], v[90:93]
	v_mfma_f32_16x16x32_bf16 v[78:81], v[170:173], v[230:233], v[78:81]
	v_mfma_f32_16x16x32_bf16 v[74:77], v[178:181], v[230:233], v[74:77]
	v_mfma_f32_16x16x32_bf16 v[126:129], v[174:177], v[210:213], v[126:129]
	v_mfma_f32_16x16x32_bf16 v[122:125], v[182:185], v[210:213], v[122:125]
	v_mfma_f32_16x16x32_bf16 v[110:113], v[174:177], v[218:221], v[110:113]
	v_mfma_f32_16x16x32_bf16 v[106:109], v[182:185], v[218:221], v[106:109]
	v_mfma_f32_16x16x32_bf16 v[94:97], v[174:177], v[226:229], v[94:97]
	v_mfma_f32_16x16x32_bf16 v[90:93], v[182:185], v[226:229], v[90:93]
	v_mfma_f32_16x16x32_bf16 v[78:81], v[174:177], v[234:237], v[78:81]
	v_mfma_f32_16x16x32_bf16 v[74:77], v[182:185], v[234:237], v[74:77]
	v_mfma_f32_16x16x32_bf16 v[118:121], v[186:189], v[202:205], v[118:121]
	v_mfma_f32_16x16x32_bf16 v[114:117], v[194:197], v[202:205], v[114:117]
	v_mfma_f32_16x16x32_bf16 v[102:105], v[186:189], v[214:217], v[102:105]
	v_mfma_f32_16x16x32_bf16 v[98:101], v[194:197], v[214:217], v[98:101]
	v_mfma_f32_16x16x32_bf16 v[86:89], v[186:189], v[222:225], v[86:89]
	v_mfma_f32_16x16x32_bf16 v[82:85], v[194:197], v[222:225], v[82:85]
	v_mfma_f32_16x16x32_bf16 v[70:73], v[186:189], v[230:233], v[70:73]
	v_mfma_f32_16x16x32_bf16 v[66:69], v[194:197], v[230:233], v[66:69]
	v_mfma_f32_16x16x32_bf16 v[118:121], v[190:193], v[210:213], v[118:121]
	v_mfma_f32_16x16x32_bf16 v[114:117], v[198:201], v[210:213], v[114:117]
	v_mfma_f32_16x16x32_bf16 v[102:105], v[190:193], v[218:221], v[102:105]
	v_mfma_f32_16x16x32_bf16 v[98:101], v[198:201], v[218:221], v[98:101]
	v_mfma_f32_16x16x32_bf16 v[86:89], v[190:193], v[226:229], v[86:89]
	v_mfma_f32_16x16x32_bf16 v[82:85], v[198:201], v[226:229], v[82:85]
	v_mfma_f32_16x16x32_bf16 v[70:73], v[190:193], v[234:237], v[70:73]
	v_mfma_f32_16x16x32_bf16 v[66:69], v[198:201], v[234:237], v[66:69]
	s_setprio 0
	s_barrier
; #define G8_STA(bufoff, ptr, sg, h) G8_STAGE1(bufoff, (ptr) + (h) * ((sg) ? hA1 : hA0), ((sg) ? voffA1 : voffA0), ((sg) ? r64A1 : r64A0))
; #define G8_STB(bufoff, ptr, sg, h) G8_STAGE1(bufoff, (ptr) + (h) * ((sg) ? hB1 : hB0), ((sg) ? voffB1 : voffB0), ((sg) ? r64B1 : r64B0))
; #define G8_LDA(dst, b, h) do { _Pragma("unroll") for (int m = 0; m < 4; ++m) _Pragma("unroll") for (int k = 0; k < 2; ++k) dst[m][k] = *(const LAS bf16x8*)(lds + G8_SA(b, h) + aoff + m * 2048 + k * 1024); } while (0)
; #define G8_MMA(ai, bj, At, Bt) do { __builtin_amdgcn_s_setprio(1); _Pragma("unroll") for (int m = 0; m < 4; ++m) _Pragma("unroll") for (int n = 0; n < 2; ++n) _Pragma("unroll") for (int k = 0; k < 2; ++k) \
;         acc[ai][bj][m][n] = __builtin_amdgcn_mfma_f32_16x16x32_bf16(Bt[n][k], At[m][k], acc[ai][bj][m][n], 0, 0, 0); __builtin_amdgcn_s_setprio(0); } while (0)
; #define G8_WAIT_V(n) asm volatile("s_waitcnt vmcnt(" #n ")" ::: "memory")
; #define G8_WAIT_L(n) asm volatile("s_waitcnt lgkmcnt(" #n ")" ::: "memory")
; #define G8_BAR __builtin_amdgcn_s_barrier()
; #define G8_SCHED __builtin_amdgcn_sched_barrier(0)
; template <class P>
; __device__ __forceinline__ void gemm_phase(LAS unsigned char* lds, const P& p, const int G, const int c) {
;     ...
;             G8_LDA(At, 1, 1); G8_STB(G8_SB(1, 0), b3, sg2, 0); G8_STB(G8_SB(1, 1), b3, sg2, 1); G8_STA(G8_SA(1, 0), a3, sg2, 0);
;             G8_WAIT_V(8); G8_WAIT_L(0); G8_BAR; G8_MMA(1, 0, At, B0); G8_MMA(1, 1, At, B1); G8_BAR; G8_SCHED;
;         }
	s_add_i32 s28, s28, s26
	v_lshl_add_u64 v[240:241], v[206:207], 0, s[12:13]
	s_mov_b32 m0, s28
	ds_read_b128 v[202:205], v151 offset:49152
	ds_read_b128 v[210:213], v151 offset:50176
	ds_read_b128 v[214:217], v151 offset:51200
	ds_read_b128 v[218:221], v151 offset:52224
	ds_read_b128 v[222:225], v151 offset:53248
	ds_read_b128 v[226:229], v151 offset:54272
	ds_read_b128 v[230:233], v151 offset:55296
	ds_read_b128 v[234:237], v151 offset:56320
	global_load_lds_dwordx4 v[240:241], off
	v_lshl_add_u64 v[240:241], v[206:207], 0, s[14:15]
	s_add_i32 m0, s28, 0x2000
	s_add_i32 s28, s29, s26
	global_load_lds_dwordx4 v[240:241], off
	v_lshl_add_u64 v[240:241], v[206:207], 0, s[22:23]
	s_mov_b32 m0, s28
	v_lshl_add_u64 v[206:207], v[206:207], 0, s[36:37]
	global_load_lds_dwordx4 v[240:241], off
	s_add_i32 m0, s28, 0x2000
	s_nop 0
	global_load_lds_dwordx4 v[206:207], off
	v_lshl_add_u64 v[206:207], v[238:239], 0, s[16:17]
	s_mov_b32 m0, s46
	s_nop 0
	global_load_lds_dwordx4 v[206:207], off
	v_lshl_add_u64 v[206:207], v[238:239], 0, s[20:21]
	s_mov_b32 m0, s47
	s_nop 0
	global_load_lds_dwordx4 v[206:207], off
	s_waitcnt vmcnt(8)
	s_waitcnt lgkmcnt(0)
	s_barrier
	s_setprio 1
	s_waitcnt lgkmcnt(0)
	v_mfma_f32_16x16x32_bf16 v[62:65], v[170:173], v[202:205], v[62:65]
	v_mfma_f32_16x16x32_bf16 v[58:61], v[178:181], v[202:205], v[58:61]
	v_mfma_f32_16x16x32_bf16 v[46:49], v[170:173], v[214:217], v[46:49]
	v_mfma_f32_16x16x32_bf16 v[42:45], v[178:181], v[214:217], v[42:45]
	v_mfma_f32_16x16x32_bf16 v[30:33], v[170:173], v[222:225], v[30:33]
	v_mfma_f32_16x16x32_bf16 v[26:29], v[178:181], v[222:225], v[26:29]
	v_mfma_f32_16x16x32_bf16 v[14:17], v[170:173], v[230:233], v[14:17]
	v_mfma_f32_16x16x32_bf16 v[10:13], v[178:181], v[230:233], v[10:13]
	v_mfma_f32_16x16x32_bf16 v[62:65], v[174:177], v[210:213], v[62:65]
	v_mfma_f32_16x16x32_bf16 v[58:61], v[182:185], v[210:213], v[58:61]
	v_mfma_f32_16x16x32_bf16 v[46:49], v[174:177], v[218:221], v[46:49]
	v_mfma_f32_16x16x32_bf16 v[42:45], v[182:185], v[218:221], v[42:45]
	v_mfma_f32_16x16x32_bf16 v[30:33], v[174:177], v[226:229], v[30:33]
	v_mfma_f32_16x16x32_bf16 v[26:29], v[182:185], v[226:229], v[26:29]
	v_mfma_f32_16x16x32_bf16 v[14:17], v[174:177], v[234:237], v[14:17]
	v_mfma_f32_16x16x32_bf16 v[10:13], v[182:185], v[234:237], v[10:13]
	v_mfma_f32_16x16x32_bf16 v[54:57], v[186:189], v[202:205], v[54:57]
	v_mfma_f32_16x16x32_bf16 v[50:53], v[194:197], v[202:205], v[50:53]
	v_mfma_f32_16x16x32_bf16 v[38:41], v[186:189], v[214:217], v[38:41]
	v_mfma_f32_16x16x32_bf16 v[34:37], v[194:197], v[214:217], v[34:37]
	v_mfma_f32_16x16x32_bf16 v[22:25], v[186:189], v[222:225], v[22:25]
	v_mfma_f32_16x16x32_bf16 v[18:21], v[194:197], v[222:225], v[18:21]
	v_mfma_f32_16x16x32_bf16 v[6:9], v[186:189], v[230:233], v[6:9]
	v_mfma_f32_16x16x32_bf16 v[2:5], v[194:197], v[230:233], v[2:5]
	v_mfma_f32_16x16x32_bf16 v[54:57], v[190:193], v[210:213], v[54:57]
	v_mfma_f32_16x16x32_bf16 v[50:53], v[198:201], v[210:213], v[50:53]
	v_mfma_f32_16x16x32_bf16 v[38:41], v[190:193], v[218:221], v[38:41]
	v_mfma_f32_16x16x32_bf16 v[34:37], v[198:201], v[218:221], v[34:37]
	v_mfma_f32_16x16x32_bf16 v[22:25], v[190:193], v[226:229], v[22:25]
	v_mfma_f32_16x16x32_bf16 v[18:21], v[198:201], v[226:229], v[18:21]
	v_mfma_f32_16x16x32_bf16 v[6:9], v[190:193], v[234:237], v[6:9]
	v_mfma_f32_16x16x32_bf16 v[2:5], v[198:201], v[234:237], v[2:5]
	s_setprio 0
	s_barrier
	s_add_i32 s66, s66, 2
	s_add_u32 s53, s53, 0x100000
	s_addc_u32 s59, s59, 0
	s_add_u32 s62, s62, 0x820000
	s_addc_u32 s63, s63, 0
	s_cmp_gt_u32 s66, 13
	s_cbranch_scc1 .LBB0_682

; #define G8_STA(bufoff, ptr, sg, h) G8_STAGE1(bufoff, (ptr) + (h) * ((sg) ? hA1 : hA0), ((sg) ? voffA1 : voffA0), ((sg) ? r64A1 : r64A0))
; #define G8_STB(bufoff, ptr, sg, h) G8_STAGE1(bufoff, (ptr) + (h) * ((sg) ? hB1 : hB0), ((sg) ? voffB1 : voffB0), ((sg) ? r64B1 : r64B0))
; #define G8_LDA(dst, b, h) do { _Pragma("unroll") for (int m = 0; m < 4; ++m) _Pragma("unroll") for (int k = 0; k < 2; ++k) dst[m][k] = *(const LAS bf16x8*)(lds + G8_SA(b, h) + aoff + m * 2048 + k * 1024); } while (0)
; #define G8_LDB(dst, b, h) do { _Pragma("unroll") for (int n = 0; n < 2; ++n) _Pragma("unroll") for (int k = 0; k < 2; ++k) dst[n][k] = *(const LAS bf16x8*)(lds + G8_SB(b, h) + boff + n * 2048 + k * 1024); } while (0)
; #define G8_MMA(ai, bj, At, Bt) do { __builtin_amdgcn_s_setprio(1); _Pragma("unroll") for (int m = 0; m < 4; ++m) _Pragma("unroll") for (int n = 0; n < 2; ++n) _Pragma("unroll") for (int k = 0; k < 2; ++k) \
;         acc[ai][bj][m][n] = __builtin_amdgcn_mfma_f32_16x16x32_bf16(Bt[n][k], At[m][k], acc[ai][bj][m][n], 0, 0, 0); __builtin_amdgcn_s_setprio(0); } while (0)
; #define G8_BAR __builtin_amdgcn_s_barrier()
; template <class P>
; __device__ __forceinline__ void gemm_phase(LAS unsigned char* lds, const P& p, const int G, const int c) {
;     ...
;         for (int t = 0; t < nt; t += 2) {
;             const bool last = (t == nt - 2);
;             const bool sg1 = (NS > 1) && (t + 1 >= nt0);
;             const bool sg2 = (NS > 1) && !last && (t + 2 >= nt0);
;             const char* a1 = sg1 ? cA1 + (long)(t + 1 - nt0) * ksA1 : cA0 + (long)(t + 1) * ksA0;
;             const char* a2 = last ? nA0 : (sg2 ? cA1 + (long)(t + 2 - nt0) * ksA1 : cA0 + (long)(t + 2) * ksA0);
;             const char* b2 = last ? nB0 : (sg2 ? cB1 + (long)(t + 2 - nt0) * ksB1 : cB0 + (long)(t + 2) * ksB0);
;             const char* a3 = a2 + (sg2 ? ksA1 : ksA0); const char* b3 = b2 + (sg2 ? ksB1 : ksB0);
;             G8_LDB(B0, 0, 0); G8_LDB(B1, 0, 1); G8_SCHED; G8_LDA(At, 0, 0); G8_STA(G8_SA(1, 1), a1, sg1, 1);
;             G8_WAIT_V(8); G8_WAIT_L(0); G8_BAR; G8_MMA(0, 0, At, B0); G8_MMA(0, 1, At, B1); G8_BAR; G8_SCHED;
;             G8_LDA(At, 0, 1); G8_STB(G8_SB(0, 0), b2, sg2, 0); G8_STB(G8_SB(0, 1), b2, sg2, 1); G8_STA(G8_SA(0, 0), a2, sg2, 0);
;             G8_WAIT_V(8); G8_WAIT_L(0); G8_BAR; G8_MMA(1, 0, At, B0); G8_MMA(1, 1, At, B1); G8_BAR; G8_SCHED;
.LBB0_707:
	ds_read_b128 v[68:71], v230
	ds_read_b128 v[72:75], v230 offset:1024
	ds_read_b128 v[76:79], v230 offset:2048
	ds_read_b128 v[138:141], v230 offset:3072
	ds_read_b128 v[142:145], v231
	ds_read_b128 v[154:157], v231 offset:1024
	ds_read_b128 v[158:161], v231 offset:2048
	ds_read_b128 v[162:165], v231 offset:3072
	s_add_u32 s65, s74, s76
	s_addc_u32 s66, s75, s77
	s_add_u32 s65, s65, 0x800000
	s_addc_u32 s66, s66, 0
	s_cmp_eq_u32 s76, 0x7800000
	s_cselect_b32 s67, s18, s66
	s_cselect_b32 s66, s19, s65
	s_cselect_b32 s79, s61, s29
	s_cselect_b32 s78, s63, s28
	v_lshl_add_u64 v[80:81], v[66:67], 0, s[76:77]
	s_mov_b64 s[80:81], 0x401000
	v_lshl_add_u64 v[198:199], v[80:81], 0, s[80:81]
	s_add_i32 m0, s25, 0xc000
	ds_read_b128 v[166:169], v232
	ds_read_b128 v[170:173], v232 offset:1024
	ds_read_b128 v[174:177], v232 offset:2048
	ds_read_b128 v[178:181], v232 offset:3072
	ds_read_b128 v[182:185], v232 offset:4096
	ds_read_b128 v[186:189], v232 offset:5120
	ds_read_b128 v[190:193], v232 offset:6144
	ds_read_b128 v[194:197], v232 offset:7168
	global_load_lds_dwordx4 v[198:199], off
	v_lshl_add_u64 v[80:81], v[80:81], 0, s[54:55]
	s_add_i32 m0, s25, 0xe000
	s_nop 0
	global_load_lds_dwordx4 v[80:81], off
	s_waitcnt vmcnt(8)
	s_waitcnt lgkmcnt(0)
	s_barrier
	s_setprio 1
	s_waitcnt lgkmcnt(0)
	v_mfma_f32_16x16x32_bf16 v[150:153], v[68:71], v[166:169], v[150:153]
	v_mfma_f32_16x16x32_bf16 v[146:149], v[76:79], v[166:169], v[146:149]
	v_mfma_f32_16x16x32_bf16 v[126:129], v[68:71], v[174:177], v[126:129]
	v_mfma_f32_16x16x32_bf16 v[122:125], v[76:79], v[174:177], v[122:125]
	v_mfma_f32_16x16x32_bf16 v[110:113], v[68:71], v[182:185], v[110:113]
	v_mfma_f32_16x16x32_bf16 v[106:109], v[76:79], v[182:185], v[106:109]
	v_mfma_f32_16x16x32_bf16 v[94:97], v[68:71], v[190:193], v[94:97]
	v_mfma_f32_16x16x32_bf16 v[90:93], v[76:79], v[190:193], v[90:93]
	v_mfma_f32_16x16x32_bf16 v[150:153], v[72:75], v[170:173], v[150:153]
	v_mfma_f32_16x16x32_bf16 v[146:149], v[138:141], v[170:173], v[146:149]
	v_mfma_f32_16x16x32_bf16 v[126:129], v[72:75], v[178:181], v[126:129]
	v_mfma_f32_16x16x32_bf16 v[122:125], v[138:141], v[178:181], v[122:125]
	v_mfma_f32_16x16x32_bf16 v[110:113], v[72:75], v[186:189], v[110:113]
	v_mfma_f32_16x16x32_bf16 v[106:109], v[138:141], v[186:189], v[106:109]
	v_mfma_f32_16x16x32_bf16 v[94:97], v[72:75], v[194:197], v[94:97]
	v_mfma_f32_16x16x32_bf16 v[90:93], v[138:141], v[194:197], v[90:93]
	v_mfma_f32_16x16x32_bf16 v[134:137], v[142:145], v[166:169], v[134:137]
	v_mfma_f32_16x16x32_bf16 v[130:133], v[158:161], v[166:169], v[130:133]
	v_mfma_f32_16x16x32_bf16 v[118:121], v[142:145], v[174:177], v[118:121]
	v_mfma_f32_16x16x32_bf16 v[114:117], v[158:161], v[174:177], v[114:117]
	v_mfma_f32_16x16x32_bf16 v[102:105], v[142:145], v[182:185], v[102:105]
	v_mfma_f32_16x16x32_bf16 v[98:101], v[158:161], v[182:185], v[98:101]
	v_mfma_f32_16x16x32_bf16 v[86:89], v[142:145], v[190:193], v[86:89]
	v_mfma_f32_16x16x32_bf16 v[80:83], v[158:161], v[190:193], v[82:85]
	v_mfma_f32_16x16x32_bf16 v[134:137], v[154:157], v[170:173], v[134:137]
	v_mfma_f32_16x16x32_bf16 v[130:133], v[162:165], v[170:173], v[130:133]
	v_mfma_f32_16x16x32_bf16 v[118:121], v[154:157], v[178:181], v[118:121]
	v_mfma_f32_16x16x32_bf16 v[114:117], v[162:165], v[178:181], v[114:117]
	v_mfma_f32_16x16x32_bf16 v[102:105], v[154:157], v[186:189], v[102:105]
	v_mfma_f32_16x16x32_bf16 v[98:101], v[162:165], v[186:189], v[98:101]
	v_mfma_f32_16x16x32_bf16 v[86:89], v[154:157], v[194:197], v[86:89]
	v_mfma_f32_16x16x32_bf16 v[80:83], v[162:165], v[194:197], v[80:83]
	s_setprio 0
	s_barrier
	s_add_i32 s65, s50, s24
	v_lshl_add_u64 v[198:199], s[78:79], 0, v[202:203]
	s_mov_b32 m0, s65
	ds_read_b128 v[166:169], v232 offset:16384
	ds_read_b128 v[170:173], v232 offset:17408
	ds_read_b128 v[174:177], v232 offset:18432
	ds_read_b128 v[178:181], v232 offset:19456
	ds_read_b128 v[182:185], v232 offset:20480
	ds_read_b128 v[186:189], v232 offset:21504
	ds_read_b128 v[190:193], v232 offset:22528
	ds_read_b128 v[194:197], v232 offset:23552
	global_load_lds_dwordx4 v[198:199], off
	v_lshl_add_u64 v[84:85], v[198:199], 0, s[6:7]
	s_add_i32 m0, s65, 0x2000
	s_add_i32 s65, s51, s24
	global_load_lds_dwordx4 v[84:85], off
	v_lshl_add_u64 v[84:85], v[198:199], 0, s[8:9]
	s_mov_b32 m0, s65
	v_lshl_add_u64 v[200:201], s[66:67], 0, v[204:205]
	global_load_lds_dwordx4 v[84:85], off
	v_lshl_add_u64 v[84:85], v[198:199], 0, s[10:11]
	s_add_i32 m0, s65, 0x2000
	s_nop 0
	global_load_lds_dwordx4 v[84:85], off
	s_mov_b32 m0, s25
	v_lshl_add_u64 v[84:85], v[200:201], 0, s[12:13]
	global_load_lds_dwordx4 v[200:201], off
	s_mov_b32 m0, s26
	s_nop 0
	global_load_lds_dwordx4 v[84:85], off
	s_waitcnt vmcnt(8)
	s_waitcnt lgkmcnt(0)
	s_barrier
; #define G8_STA(bufoff, ptr, sg, h) G8_STAGE1(bufoff, (ptr) + (h) * ((sg) ? hA1 : hA0), ((sg) ? voffA1 : voffA0), ((sg) ? r64A1 : r64A0))
; #define G8_LDA(dst, b, h) do { _Pragma("unroll") for (int m = 0; m < 4; ++m) _Pragma("unroll") for (int k = 0; k < 2; ++k) dst[m][k] = *(const LAS bf16x8*)(lds + G8_SA(b, h) + aoff + m * 2048 + k * 1024); } while (0)
; #define G8_LDB(dst, b, h) do { _Pragma("unroll") for (int n = 0; n < 2; ++n) _Pragma("unroll") for (int k = 0; k < 2; ++k) dst[n][k] = *(const LAS bf16x8*)(lds + G8_SB(b, h) + boff + n * 2048 + k * 1024); } while (0)
; #define G8_MMA(ai, bj, At, Bt) do { __builtin_amdgcn_s_setprio(1); _Pragma("unroll") for (int m = 0; m < 4; ++m) _Pragma("unroll") for (int n = 0; n < 2; ++n) _Pragma("unroll") for (int k = 0; k < 2; ++k) \
;         acc[ai][bj][m][n] = __builtin_amdgcn_mfma_f32_16x16x32_bf16(Bt[n][k], At[m][k], acc[ai][bj][m][n], 0, 0, 0); __builtin_amdgcn_s_setprio(0); } while (0)
; #define G8_WAIT_V(n) asm volatile("s_waitcnt vmcnt(" #n ")" ::: "memory")
; #define G8_WAIT_L(n) asm volatile("s_waitcnt lgkmcnt(" #n ")" ::: "memory")
; #define G8_BAR __builtin_amdgcn_s_barrier()
; #define G8_SCHED __builtin_amdgcn_sched_barrier(0)
; template <class P>
; __device__ __forceinline__ void gemm_phase(LAS unsigned char* lds, const P& p, const int G, const int c) {
;     ...
;             G8_WAIT_V(8); G8_WAIT_L(0); G8_BAR; G8_MMA(1, 0, At, B0); G8_MMA(1, 1, At, B1); G8_BAR; G8_SCHED;
;             G8_LDB(B0, 1, 0); G8_LDB(B1, 1, 1); G8_SCHED; G8_LDA(At, 1, 0); G8_STA(G8_SA(0, 1), a2, sg2, 1);
;             G8_WAIT_V(8); G8_WAIT_L(0); G8_BAR; G8_MMA(0, 0, At, B0); G8_MMA(0, 1, At, B1); G8_BAR; G8_SCHED;
	s_setprio 1
	s_waitcnt lgkmcnt(0)
	v_mfma_f32_16x16x32_bf16 v[62:65], v[68:71], v[166:169], v[62:65]
	v_mfma_f32_16x16x32_bf16 v[58:61], v[76:79], v[166:169], v[58:61]
	v_mfma_f32_16x16x32_bf16 v[46:49], v[68:71], v[174:177], v[46:49]
	v_mfma_f32_16x16x32_bf16 v[42:45], v[76:79], v[174:177], v[42:45]
	v_mfma_f32_16x16x32_bf16 v[30:33], v[68:71], v[182:185], v[30:33]
	v_mfma_f32_16x16x32_bf16 v[26:29], v[76:79], v[182:185], v[26:29]
	v_mfma_f32_16x16x32_bf16 v[14:17], v[68:71], v[190:193], v[14:17]
	v_mfma_f32_16x16x32_bf16 v[10:13], v[76:79], v[190:193], v[10:13]
	v_mfma_f32_16x16x32_bf16 v[62:65], v[72:75], v[170:173], v[62:65]
	v_mfma_f32_16x16x32_bf16 v[58:61], v[138:141], v[170:173], v[58:61]
	v_mfma_f32_16x16x32_bf16 v[46:49], v[72:75], v[178:181], v[46:49]
	v_mfma_f32_16x16x32_bf16 v[42:45], v[138:141], v[178:181], v[42:45]
	v_mfma_f32_16x16x32_bf16 v[30:33], v[72:75], v[186:189], v[30:33]
	v_mfma_f32_16x16x32_bf16 v[26:29], v[138:141], v[186:189], v[26:29]
	v_mfma_f32_16x16x32_bf16 v[14:17], v[72:75], v[194:197], v[14:17]
	v_mfma_f32_16x16x32_bf16 v[10:13], v[138:141], v[194:197], v[10:13]
	v_mfma_f32_16x16x32_bf16 v[54:57], v[142:145], v[166:169], v[54:57]
	v_mfma_f32_16x16x32_bf16 v[50:53], v[158:161], v[166:169], v[50:53]
	v_mfma_f32_16x16x32_bf16 v[38:41], v[142:145], v[174:177], v[38:41]
	v_mfma_f32_16x16x32_bf16 v[34:37], v[158:161], v[174:177], v[34:37]
	v_mfma_f32_16x16x32_bf16 v[22:25], v[142:145], v[182:185], v[22:25]
	v_mfma_f32_16x16x32_bf16 v[18:21], v[158:161], v[182:185], v[18:21]
	v_mfma_f32_16x16x32_bf16 v[6:9], v[142:145], v[190:193], v[6:9]
	v_mfma_f32_16x16x32_bf16 v[2:5], v[158:161], v[190:193], v[2:5]
	v_mfma_f32_16x16x32_bf16 v[54:57], v[154:157], v[170:173], v[54:57]
	v_mfma_f32_16x16x32_bf16 v[50:53], v[162:165], v[170:173], v[50:53]
	v_mfma_f32_16x16x32_bf16 v[38:41], v[154:157], v[178:181], v[38:41]
	v_mfma_f32_16x16x32_bf16 v[34:37], v[162:165], v[178:181], v[34:37]
	v_mfma_f32_16x16x32_bf16 v[22:25], v[154:157], v[186:189], v[22:25]
	v_mfma_f32_16x16x32_bf16 v[18:21], v[162:165], v[186:189], v[18:21]
	v_mfma_f32_16x16x32_bf16 v[6:9], v[154:157], v[194:197], v[6:9]
	v_mfma_f32_16x16x32_bf16 v[2:5], v[162:165], v[194:197], v[2:5]
	s_setprio 0
	s_barrier
	s_add_i32 s65, 0, 0x18000
	v_add_u32_e32 v84, s65, v229
	s_add_i32 s66, 0, 0x1c000
	ds_read_b128 v[68:71], v84
	ds_read_b128 v[72:75], v84 offset:1024
	ds_read_b128 v[76:79], v84 offset:2048
	ds_read_b128 v[138:141], v84 offset:3072
	v_add_u32_e32 v84, s66, v229
	ds_read_b128 v[142:145], v84
	ds_read_b128 v[154:157], v84 offset:1024
	ds_read_b128 v[158:161], v84 offset:2048
	ds_read_b128 v[162:165], v84 offset:3072
	s_mov_b32 m0, s27
	v_lshl_add_u64 v[84:85], v[200:201], 0, s[14:15]
	ds_read_b128 v[166:169], v232 offset:32768
	ds_read_b128 v[170:173], v232 offset:33792
	ds_read_b128 v[174:177], v232 offset:34816
	ds_read_b128 v[178:181], v232 offset:35840
	ds_read_b128 v[182:185], v232 offset:36864
	ds_read_b128 v[186:189], v232 offset:37888
	ds_read_b128 v[190:193], v232 offset:38912
	ds_read_b128 v[194:197], v232 offset:39936
	global_load_lds_dwordx4 v[84:85], off
	v_lshl_add_u64 v[84:85], v[200:201], 0, s[16:17]
	s_mov_b32 m0, s31
	s_nop 0
	global_load_lds_dwordx4 v[84:85], off
	s_waitcnt vmcnt(8)
	s_waitcnt lgkmcnt(0)
	s_barrier
	s_setprio 1
	s_waitcnt lgkmcnt(0)
	v_mfma_f32_16x16x32_bf16 v[150:153], v[68:71], v[166:169], v[150:153]
	v_mfma_f32_16x16x32_bf16 v[146:149], v[76:79], v[166:169], v[146:149]
	v_mfma_f32_16x16x32_bf16 v[126:129], v[68:71], v[174:177], v[126:129]
	v_mfma_f32_16x16x32_bf16 v[122:125], v[76:79], v[174:177], v[122:125]
	v_mfma_f32_16x16x32_bf16 v[110:113], v[68:71], v[182:185], v[110:113]
	v_mfma_f32_16x16x32_bf16 v[106:109], v[76:79], v[182:185], v[106:109]
	v_mfma_f32_16x16x32_bf16 v[94:97], v[68:71], v[190:193], v[94:97]
	v_mfma_f32_16x16x32_bf16 v[90:93], v[76:79], v[190:193], v[90:93]
	v_mfma_f32_16x16x32_bf16 v[150:153], v[72:75], v[170:173], v[150:153]
	v_mfma_f32_16x16x32_bf16 v[146:149], v[138:141], v[170:173], v[146:149]
	v_mfma_f32_16x16x32_bf16 v[126:129], v[72:75], v[178:181], v[126:129]
	v_mfma_f32_16x16x32_bf16 v[122:125], v[138:141], v[178:181], v[122:125]
	v_mfma_f32_16x16x32_bf16 v[110:113], v[72:75], v[186:189], v[110:113]
	v_mfma_f32_16x16x32_bf16 v[106:109], v[138:141], v[186:189], v[106:109]
	v_mfma_f32_16x16x32_bf16 v[94:97], v[72:75], v[194:197], v[94:97]
	v_mfma_f32_16x16x32_bf16 v[90:93], v[138:141], v[194:197], v[90:93]
	v_mfma_f32_16x16x32_bf16 v[134:137], v[142:145], v[166:169], v[134:137]
	v_mfma_f32_16x16x32_bf16 v[130:133], v[158:161], v[166:169], v[130:133]
	v_mfma_f32_16x16x32_bf16 v[118:121], v[142:145], v[174:177], v[118:121]
	v_mfma_f32_16x16x32_bf16 v[114:117], v[158:161], v[174:177], v[114:117]
	v_mfma_f32_16x16x32_bf16 v[102:105], v[142:145], v[182:185], v[102:105]
	v_mfma_f32_16x16x32_bf16 v[98:101], v[158:161], v[182:185], v[98:101]
	v_mfma_f32_16x16x32_bf16 v[84:87], v[142:145], v[190:193], v[86:89]
	v_mfma_f32_16x16x32_bf16 v[80:83], v[158:161], v[190:193], v[80:83]
	v_mfma_f32_16x16x32_bf16 v[134:137], v[154:157], v[170:173], v[134:137]
	v_mfma_f32_16x16x32_bf16 v[130:133], v[162:165], v[170:173], v[130:133]
	v_mfma_f32_16x16x32_bf16 v[118:121], v[154:157], v[178:181], v[118:121]
	v_mfma_f32_16x16x32_bf16 v[114:117], v[162:165], v[178:181], v[114:117]
	v_mfma_f32_16x16x32_bf16 v[102:105], v[154:157], v[186:189], v[102:105]
	v_mfma_f32_16x16x32_bf16 v[98:101], v[162:165], v[186:189], v[98:101]
	v_mfma_f32_16x16x32_bf16 v[86:89], v[154:157], v[194:197], v[84:87]
	v_mfma_f32_16x16x32_bf16 v[82:85], v[162:165], v[194:197], v[80:83]
	s_setprio 0
	s_barrier
; #define G8_STA(bufoff, ptr, sg, h) G8_STAGE1(bufoff, (ptr) + (h) * ((sg) ? hA1 : hA0), ((sg) ? voffA1 : voffA0), ((sg) ? r64A1 : r64A0))
; #define G8_STB(bufoff, ptr, sg, h) G8_STAGE1(bufoff, (ptr) + (h) * ((sg) ? hB1 : hB0), ((sg) ? voffB1 : voffB0), ((sg) ? r64B1 : r64B0))
; #define G8_LDA(dst, b, h) do { _Pragma("unroll") for (int m = 0; m < 4; ++m) _Pragma("unroll") for (int k = 0; k < 2; ++k) dst[m][k] = *(const LAS bf16x8*)(lds + G8_SA(b, h) + aoff + m * 2048 + k * 1024); } while (0)
; #define G8_MMA(ai, bj, At, Bt) do { __builtin_amdgcn_s_setprio(1); _Pragma("unroll") for (int m = 0; m < 4; ++m) _Pragma("unroll") for (int n = 0; n < 2; ++n) _Pragma("unroll") for (int k = 0; k < 2; ++k) \
;         acc[ai][bj][m][n] = __builtin_amdgcn_mfma_f32_16x16x32_bf16(Bt[n][k], At[m][k], acc[ai][bj][m][n], 0, 0, 0); __builtin_amdgcn_s_setprio(0); } while (0)
; #define G8_WAIT_V(n) asm volatile("s_waitcnt vmcnt(" #n ")" ::: "memory")
; #define G8_WAIT_L(n) asm volatile("s_waitcnt lgkmcnt(" #n ")" ::: "memory")
; #define G8_BAR __builtin_amdgcn_s_barrier()
; #define G8_SCHED __builtin_amdgcn_sched_barrier(0)
; template <class P>
; __device__ __forceinline__ void gemm_phase(LAS unsigned char* lds, const P& p, const int G, const int c) {
;     ...
;             G8_LDA(At, 1, 1); G8_STB(G8_SB(1, 0), b3, sg2, 0); G8_STB(G8_SB(1, 1), b3, sg2, 1); G8_STA(G8_SA(1, 0), a3, sg2, 0);
;             G8_WAIT_V(8); G8_WAIT_L(0); G8_BAR; G8_MMA(1, 0, At, B0); G8_MMA(1, 1, At, B1); G8_BAR; G8_SCHED;
;         }
;         if (wr == 0) G8_BAR;
	s_add_i32 s65, s65, s24
	v_lshl_add_u64 v[80:81], v[198:199], 0, s[36:37]
	s_mov_b32 m0, s65
	ds_read_b128 v[166:169], v232 offset:49152
	ds_read_b128 v[170:173], v232 offset:50176
	ds_read_b128 v[174:177], v232 offset:51200
	ds_read_b128 v[178:181], v232 offset:52224
	ds_read_b128 v[182:185], v232 offset:53248
	ds_read_b128 v[186:189], v232 offset:54272
	ds_read_b128 v[190:193], v232 offset:55296
	ds_read_b128 v[194:197], v232 offset:56320
	global_load_lds_dwordx4 v[80:81], off
	v_lshl_add_u64 v[80:81], v[198:199], 0, s[38:39]
	s_add_i32 m0, s65, 0x2000
	s_add_i32 s65, s66, s24
	global_load_lds_dwordx4 v[80:81], off
	v_lshl_add_u64 v[80:81], v[198:199], 0, s[44:45]
	s_mov_b32 m0, s65
	s_nop 0
	global_load_lds_dwordx4 v[80:81], off
	v_lshl_add_u64 v[80:81], v[198:199], 0, s[48:49]
	s_add_i32 m0, s65, 0x2000
	s_nop 0
	global_load_lds_dwordx4 v[80:81], off
	v_lshl_add_u64 v[80:81], v[200:201], 0, s[40:41]
	s_mov_b32 m0, s46
	s_nop 0
	global_load_lds_dwordx4 v[80:81], off
	v_lshl_add_u64 v[80:81], v[200:201], 0, s[42:43]
	s_mov_b32 m0, s47
	s_nop 0
	global_load_lds_dwordx4 v[80:81], off
	s_waitcnt vmcnt(8)
	s_waitcnt lgkmcnt(0)
	s_barrier
	s_setprio 1
	s_waitcnt lgkmcnt(0)
	v_mfma_f32_16x16x32_bf16 v[62:65], v[68:71], v[166:169], v[62:65]
	v_mfma_f32_16x16x32_bf16 v[58:61], v[76:79], v[166:169], v[58:61]
	v_mfma_f32_16x16x32_bf16 v[46:49], v[68:71], v[174:177], v[46:49]
	v_mfma_f32_16x16x32_bf16 v[42:45], v[76:79], v[174:177], v[42:45]
	v_mfma_f32_16x16x32_bf16 v[30:33], v[68:71], v[182:185], v[30:33]
	v_mfma_f32_16x16x32_bf16 v[26:29], v[76:79], v[182:185], v[26:29]
	v_mfma_f32_16x16x32_bf16 v[14:17], v[68:71], v[190:193], v[14:17]
	v_mfma_f32_16x16x32_bf16 v[10:13], v[76:79], v[190:193], v[10:13]
	v_mfma_f32_16x16x32_bf16 v[62:65], v[72:75], v[170:173], v[62:65]
	v_mfma_f32_16x16x32_bf16 v[58:61], v[138:141], v[170:173], v[58:61]
	v_mfma_f32_16x16x32_bf16 v[46:49], v[72:75], v[178:181], v[46:49]
	v_mfma_f32_16x16x32_bf16 v[42:45], v[138:141], v[178:181], v[42:45]
	v_mfma_f32_16x16x32_bf16 v[30:33], v[72:75], v[186:189], v[30:33]
	v_mfma_f32_16x16x32_bf16 v[26:29], v[138:141], v[186:189], v[26:29]
	v_mfma_f32_16x16x32_bf16 v[14:17], v[72:75], v[194:197], v[14:17]
	v_mfma_f32_16x16x32_bf16 v[10:13], v[138:141], v[194:197], v[10:13]
	v_mfma_f32_16x16x32_bf16 v[54:57], v[142:145], v[166:169], v[54:57]
	v_mfma_f32_16x16x32_bf16 v[50:53], v[158:161], v[166:169], v[50:53]
	v_mfma_f32_16x16x32_bf16 v[38:41], v[142:145], v[174:177], v[38:41]
	v_mfma_f32_16x16x32_bf16 v[34:37], v[158:161], v[174:177], v[34:37]
	v_mfma_f32_16x16x32_bf16 v[22:25], v[142:145], v[182:185], v[22:25]
	v_mfma_f32_16x16x32_bf16 v[18:21], v[158:161], v[182:185], v[18:21]
	v_mfma_f32_16x16x32_bf16 v[6:9], v[142:145], v[190:193], v[6:9]
	v_mfma_f32_16x16x32_bf16 v[2:5], v[158:161], v[190:193], v[2:5]
	v_mfma_f32_16x16x32_bf16 v[54:57], v[154:157], v[170:173], v[54:57]
	v_mfma_f32_16x16x32_bf16 v[50:53], v[162:165], v[170:173], v[50:53]
	v_mfma_f32_16x16x32_bf16 v[38:41], v[154:157], v[178:181], v[38:41]
	v_mfma_f32_16x16x32_bf16 v[34:37], v[162:165], v[178:181], v[34:37]
	v_mfma_f32_16x16x32_bf16 v[22:25], v[154:157], v[186:189], v[22:25]
	v_mfma_f32_16x16x32_bf16 v[18:21], v[162:165], v[186:189], v[18:21]
	v_mfma_f32_16x16x32_bf16 v[6:9], v[154:157], v[194:197], v[6:9]
	v_mfma_f32_16x16x32_bf16 v[2:5], v[162:165], v[194:197], v[2:5]
	s_setprio 0
	s_barrier
	s_add_i32 s64, s64, 2
	s_add_u32 s28, s28, 0x80000
	s_addc_u32 s29, s29, 0
	s_add_u32 s76, s76, 0x800000
	s_addc_u32 s77, s77, 0
	s_cmp_gt_u32 s64, 29
	s_cbranch_scc0 .LBB0_707
	s_and_b64 vcc, exec, s[52:53]
	s_cbranch_vccz .LBB0_710
	s_barrier

; #define G8_STA(bufoff, ptr, sg, h) G8_STAGE1(bufoff, (ptr) + (h) * ((sg) ? hA1 : hA0), ((sg) ? voffA1 : voffA0), ((sg) ? r64A1 : r64A0))
; #define G8_STB(bufoff, ptr, sg, h) G8_STAGE1(bufoff, (ptr) + (h) * ((sg) ? hB1 : hB0), ((sg) ? voffB1 : voffB0), ((sg) ? r64B1 : r64B0))
; #define G8_LDA(dst, b, h) do { _Pragma("unroll") for (int m = 0; m < 4; ++m) _Pragma("unroll") for (int k = 0; k < 2; ++k) dst[m][k] = *(const LAS bf16x8*)(lds + G8_SA(b, h) + aoff + m * 2048 + k * 1024); } while (0)
; #define G8_LDB(dst, b, h) do { _Pragma("unroll") for (int n = 0; n < 2; ++n) _Pragma("unroll") for (int k = 0; k < 2; ++k) dst[n][k] = *(const LAS bf16x8*)(lds + G8_SB(b, h) + boff + n * 2048 + k * 1024); } while (0)
; #define G8_MMA(ai, bj, At, Bt) do { __builtin_amdgcn_s_setprio(1); _Pragma("unroll") for (int m = 0; m < 4; ++m) _Pragma("unroll") for (int n = 0; n < 2; ++n) _Pragma("unroll") for (int k = 0; k < 2; ++k) \
;         acc[ai][bj][m][n] = __builtin_amdgcn_mfma_f32_16x16x32_bf16(Bt[n][k], At[m][k], acc[ai][bj][m][n], 0, 0, 0); __builtin_amdgcn_s_setprio(0); } while (0)
; #define G8_BAR __builtin_amdgcn_s_barrier()
; template <class P>
; __device__ __forceinline__ void gemm_phase(LAS unsigned char* lds, const P& p, const int G, const int c) {
;     ...
;         for (int t = 0; t < nt; t += 2) {
;             const bool last = (t == nt - 2);
;             const bool sg1 = (NS > 1) && (t + 1 >= nt0);
;             const bool sg2 = (NS > 1) && !last && (t + 2 >= nt0);
;             const char* a1 = sg1 ? cA1 + (long)(t + 1 - nt0) * ksA1 : cA0 + (long)(t + 1) * ksA0;
;             const char* a2 = last ? nA0 : (sg2 ? cA1 + (long)(t + 2 - nt0) * ksA1 : cA0 + (long)(t + 2) * ksA0);
;             const char* b2 = last ? nB0 : (sg2 ? cB1 + (long)(t + 2 - nt0) * ksB1 : cB0 + (long)(t + 2) * ksB0);
;             const char* a3 = a2 + (sg2 ? ksA1 : ksA0); const char* b3 = b2 + (sg2 ? ksB1 : ksB0);
;             G8_LDB(B0, 0, 0); G8_LDB(B1, 0, 1); G8_SCHED; G8_LDA(At, 0, 0); G8_STA(G8_SA(1, 1), a1, sg1, 1);
;             G8_WAIT_V(8); G8_WAIT_L(0); G8_BAR; G8_MMA(0, 0, At, B0); G8_MMA(0, 1, At, B1); G8_BAR; G8_SCHED;
;             G8_LDA(At, 0, 1); G8_STB(G8_SB(0, 0), b2, sg2, 0); G8_STB(G8_SB(0, 1), b2, sg2, 1); G8_STA(G8_SA(0, 0), a2, sg2, 0);
;             G8_WAIT_V(8); G8_WAIT_L(0); G8_BAR; G8_MMA(1, 0, At, B0); G8_MMA(1, 1, At, B1); G8_BAR; G8_SCHED;
.LBB0_770:
	ds_read_b128 v[130:133], v158
	ds_read_b128 v[134:137], v158 offset:1024
	ds_read_b128 v[138:141], v158 offset:2048
	ds_read_b128 v[162:165], v158 offset:3072
	ds_read_b128 v[166:169], v159
	ds_read_b128 v[170:173], v159 offset:1024
	ds_read_b128 v[174:177], v159 offset:2048
	ds_read_b128 v[178:181], v159 offset:3072
	s_add_u32 s77, s70, s72
	s_addc_u32 s78, s71, s73
	s_add_u32 s77, s77, 0x800000
	s_addc_u32 s78, s78, 0
	s_cmp_eq_u32 s72, 0x7800000
	s_cselect_b32 s79, s18, s78
	s_cselect_b32 s78, s19, s77
	s_cselect_b32 s81, s57, s29
	s_cselect_b32 s80, s59, s28
	v_lshl_add_u64 v[142:143], v[128:129], 0, s[72:73]
	v_lshl_add_u64 v[154:155], v[142:143], 0, s[40:41]
	s_add_i32 m0, s27, 0xc000
	ds_read_b128 v[182:185], v160
	ds_read_b128 v[186:189], v160 offset:1024
	ds_read_b128 v[190:193], v160 offset:2048
	ds_read_b128 v[194:197], v160 offset:3072
	ds_read_b128 v[198:201], v160 offset:4096
	ds_read_b128 v[202:205], v160 offset:5120
	ds_read_b128 v[210:213], v160 offset:6144
	ds_read_b128 v[214:217], v160 offset:7168
	global_load_lds_dwordx4 v[154:155], off
	v_lshl_add_u64 v[142:143], v[142:143], 0, s[42:43]
	s_add_i32 m0, s27, 0xe000
	s_nop 0
	global_load_lds_dwordx4 v[142:143], off
	s_waitcnt vmcnt(8)
	s_waitcnt lgkmcnt(0)
	s_barrier
	s_setprio 1
	s_waitcnt lgkmcnt(0)
	v_mfma_f32_16x16x32_bf16 v[120:123], v[130:133], v[182:185], v[120:123]
	v_mfma_f32_16x16x32_bf16 v[124:127], v[138:141], v[182:185], v[124:127]
	v_mfma_f32_16x16x32_bf16 v[112:115], v[130:133], v[190:193], v[112:115]
	v_mfma_f32_16x16x32_bf16 v[116:119], v[138:141], v[190:193], v[116:119]
	v_mfma_f32_16x16x32_bf16 v[100:103], v[130:133], v[198:201], v[100:103]
	v_mfma_f32_16x16x32_bf16 v[108:111], v[138:141], v[198:201], v[108:111]
	v_mfma_f32_16x16x32_bf16 v[84:87], v[130:133], v[210:213], v[84:87]
	v_mfma_f32_16x16x32_bf16 v[72:75], v[138:141], v[210:213], v[72:75]
	v_mfma_f32_16x16x32_bf16 v[120:123], v[134:137], v[186:189], v[120:123]
	v_mfma_f32_16x16x32_bf16 v[124:127], v[162:165], v[186:189], v[124:127]
	v_mfma_f32_16x16x32_bf16 v[112:115], v[134:137], v[194:197], v[112:115]
	v_mfma_f32_16x16x32_bf16 v[116:119], v[162:165], v[194:197], v[116:119]
	v_mfma_f32_16x16x32_bf16 v[100:103], v[134:137], v[202:205], v[100:103]
	v_mfma_f32_16x16x32_bf16 v[108:111], v[162:165], v[202:205], v[108:111]
	v_mfma_f32_16x16x32_bf16 v[84:87], v[134:137], v[214:217], v[84:87]
	v_mfma_f32_16x16x32_bf16 v[72:75], v[162:165], v[214:217], v[72:75]
	v_mfma_f32_16x16x32_bf16 v[104:107], v[166:169], v[182:185], v[104:107]
	v_mfma_f32_16x16x32_bf16 v[92:95], v[174:177], v[182:185], v[92:95]
	v_mfma_f32_16x16x32_bf16 v[96:99], v[166:169], v[190:193], v[96:99]
	v_mfma_f32_16x16x32_bf16 v[80:83], v[174:177], v[190:193], v[80:83]
	v_mfma_f32_16x16x32_bf16 v[88:91], v[166:169], v[198:201], v[88:91]
	v_mfma_f32_16x16x32_bf16 v[76:79], v[174:177], v[198:201], v[76:79]
	v_mfma_f32_16x16x32_bf16 v[68:71], v[166:169], v[210:213], v[68:71]
	v_mfma_f32_16x16x32_bf16 v[64:67], v[174:177], v[210:213], v[64:67]
	v_mfma_f32_16x16x32_bf16 v[104:107], v[170:173], v[186:189], v[104:107]
	v_mfma_f32_16x16x32_bf16 v[92:95], v[178:181], v[186:189], v[92:95]
	v_mfma_f32_16x16x32_bf16 v[96:99], v[170:173], v[194:197], v[96:99]
	v_mfma_f32_16x16x32_bf16 v[80:83], v[178:181], v[194:197], v[80:83]
	v_mfma_f32_16x16x32_bf16 v[88:91], v[170:173], v[202:205], v[88:91]
	v_mfma_f32_16x16x32_bf16 v[76:79], v[178:181], v[202:205], v[76:79]
	v_mfma_f32_16x16x32_bf16 v[68:71], v[170:173], v[214:217], v[68:71]
	v_mfma_f32_16x16x32_bf16 v[64:67], v[178:181], v[214:217], v[64:67]
	s_setprio 0
	s_barrier
	s_add_i32 s77, s30, s26
	v_lshl_add_u64 v[142:143], s[80:81], 0, v[144:145]
	s_mov_b32 m0, s77
	ds_read_b128 v[182:185], v160 offset:16384
	ds_read_b128 v[186:189], v160 offset:17408
	ds_read_b128 v[190:193], v160 offset:18432
	ds_read_b128 v[194:197], v160 offset:19456
	ds_read_b128 v[198:201], v160 offset:20480
	ds_read_b128 v[202:205], v160 offset:21504
	ds_read_b128 v[210:213], v160 offset:22528
	ds_read_b128 v[214:217], v160 offset:23552
	global_load_lds_dwordx4 v[142:143], off
	v_lshl_add_u64 v[154:155], v[142:143], 0, s[4:5]
	s_add_i32 m0, s77, 0x2000
	s_add_i32 s77, s74, s26
	global_load_lds_dwordx4 v[154:155], off
	v_lshl_add_u64 v[154:155], v[142:143], 0, s[6:7]
	s_mov_b32 m0, s77
	s_nop 0
	global_load_lds_dwordx4 v[154:155], off
	v_lshl_add_u64 v[154:155], v[142:143], 0, s[8:9]
	s_add_i32 m0, s77, 0x2000
	s_nop 0
	global_load_lds_dwordx4 v[154:155], off
	v_lshl_add_u64 v[154:155], s[78:79], 0, v[146:147]
	s_mov_b32 m0, s27
	v_lshl_add_u64 v[206:207], v[154:155], 0, s[4:5]
	global_load_lds_dwordx4 v[154:155], off
	s_mov_b32 m0, s31
	s_nop 0
	global_load_lds_dwordx4 v[206:207], off
	s_waitcnt vmcnt(8)
	s_waitcnt lgkmcnt(0)
	s_barrier
; #define G8_STA(bufoff, ptr, sg, h) G8_STAGE1(bufoff, (ptr) + (h) * ((sg) ? hA1 : hA0), ((sg) ? voffA1 : voffA0), ((sg) ? r64A1 : r64A0))
; #define G8_LDA(dst, b, h) do { _Pragma("unroll") for (int m = 0; m < 4; ++m) _Pragma("unroll") for (int k = 0; k < 2; ++k) dst[m][k] = *(const LAS bf16x8*)(lds + G8_SA(b, h) + aoff + m * 2048 + k * 1024); } while (0)
; #define G8_LDB(dst, b, h) do { _Pragma("unroll") for (int n = 0; n < 2; ++n) _Pragma("unroll") for (int k = 0; k < 2; ++k) dst[n][k] = *(const LAS bf16x8*)(lds + G8_SB(b, h) + boff + n * 2048 + k * 1024); } while (0)
; #define G8_MMA(ai, bj, At, Bt) do { __builtin_amdgcn_s_setprio(1); _Pragma("unroll") for (int m = 0; m < 4; ++m) _Pragma("unroll") for (int n = 0; n < 2; ++n) _Pragma("unroll") for (int k = 0; k < 2; ++k) \
;         acc[ai][bj][m][n] = __builtin_amdgcn_mfma_f32_16x16x32_bf16(Bt[n][k], At[m][k], acc[ai][bj][m][n], 0, 0, 0); __builtin_amdgcn_s_setprio(0); } while (0)
; #define G8_WAIT_V(n) asm volatile("s_waitcnt vmcnt(" #n ")" ::: "memory")
; #define G8_WAIT_L(n) asm volatile("s_waitcnt lgkmcnt(" #n ")" ::: "memory")
; #define G8_BAR __builtin_amdgcn_s_barrier()
; #define G8_SCHED __builtin_amdgcn_sched_barrier(0)
; template <class P>
; __device__ __forceinline__ void gemm_phase(LAS unsigned char* lds, const P& p, const int G, const int c) {
;     ...
;             G8_WAIT_V(8); G8_WAIT_L(0); G8_BAR; G8_MMA(1, 0, At, B0); G8_MMA(1, 1, At, B1); G8_BAR; G8_SCHED;
;             G8_LDB(B0, 1, 0); G8_LDB(B1, 1, 1); G8_SCHED; G8_LDA(At, 1, 0); G8_STA(G8_SA(0, 1), a2, sg2, 1);
;             G8_WAIT_V(8); G8_WAIT_L(0); G8_BAR; G8_MMA(0, 0, At, B0); G8_MMA(0, 1, At, B1); G8_BAR; G8_SCHED;
	s_setprio 1
	s_waitcnt lgkmcnt(0)
	v_mfma_f32_16x16x32_bf16 v[60:63], v[130:133], v[182:185], v[60:63]
	v_mfma_f32_16x16x32_bf16 v[56:59], v[138:141], v[182:185], v[56:59]
	v_mfma_f32_16x16x32_bf16 v[52:55], v[130:133], v[190:193], v[52:55]
	v_mfma_f32_16x16x32_bf16 v[44:47], v[138:141], v[190:193], v[44:47]
	v_mfma_f32_16x16x32_bf16 v[36:39], v[130:133], v[198:201], v[36:39]
	v_mfma_f32_16x16x32_bf16 v[28:31], v[138:141], v[198:201], v[28:31]
	v_mfma_f32_16x16x32_bf16 v[20:23], v[130:133], v[210:213], v[20:23]
	v_mfma_f32_16x16x32_bf16 v[12:15], v[138:141], v[210:213], v[12:15]
	v_mfma_f32_16x16x32_bf16 v[60:63], v[134:137], v[186:189], v[60:63]
	v_mfma_f32_16x16x32_bf16 v[56:59], v[162:165], v[186:189], v[56:59]
	v_mfma_f32_16x16x32_bf16 v[52:55], v[134:137], v[194:197], v[52:55]
	v_mfma_f32_16x16x32_bf16 v[44:47], v[162:165], v[194:197], v[44:47]
	v_mfma_f32_16x16x32_bf16 v[36:39], v[134:137], v[202:205], v[36:39]
	v_mfma_f32_16x16x32_bf16 v[28:31], v[162:165], v[202:205], v[28:31]
	v_mfma_f32_16x16x32_bf16 v[20:23], v[134:137], v[214:217], v[20:23]
	v_mfma_f32_16x16x32_bf16 v[12:15], v[162:165], v[214:217], v[12:15]
	v_mfma_f32_16x16x32_bf16 v[48:51], v[166:169], v[182:185], v[48:51]
	v_mfma_f32_16x16x32_bf16 v[40:43], v[174:177], v[182:185], v[40:43]
	v_mfma_f32_16x16x32_bf16 v[32:35], v[166:169], v[190:193], v[32:35]
	v_mfma_f32_16x16x32_bf16 v[24:27], v[174:177], v[190:193], v[24:27]
	v_mfma_f32_16x16x32_bf16 v[16:19], v[166:169], v[198:201], v[16:19]
	v_mfma_f32_16x16x32_bf16 v[8:11], v[174:177], v[198:201], v[8:11]
	v_mfma_f32_16x16x32_bf16 v[4:7], v[166:169], v[210:213], v[4:7]
	v_mfma_f32_16x16x32_bf16 v[0:3], v[174:177], v[210:213], v[0:3]
	v_mfma_f32_16x16x32_bf16 v[48:51], v[170:173], v[186:189], v[48:51]
	v_mfma_f32_16x16x32_bf16 v[40:43], v[178:181], v[186:189], v[40:43]
	v_mfma_f32_16x16x32_bf16 v[32:35], v[170:173], v[194:197], v[32:35]
	v_mfma_f32_16x16x32_bf16 v[24:27], v[178:181], v[194:197], v[24:27]
	v_mfma_f32_16x16x32_bf16 v[16:19], v[170:173], v[202:205], v[16:19]
	v_mfma_f32_16x16x32_bf16 v[8:11], v[178:181], v[202:205], v[8:11]
	v_mfma_f32_16x16x32_bf16 v[4:7], v[170:173], v[214:217], v[4:7]
	v_mfma_f32_16x16x32_bf16 v[0:3], v[178:181], v[214:217], v[0:3]
	s_setprio 0
	s_barrier
	s_add_i32 s77, 0, 0x18000
	v_add_u32_e32 v161, s77, v156
	s_add_i32 s78, 0, 0x1c000
	ds_read_b128 v[130:133], v161
	ds_read_b128 v[134:137], v161 offset:1024
	ds_read_b128 v[138:141], v161 offset:2048
	ds_read_b128 v[162:165], v161 offset:3072
	v_add_u32_e32 v161, s78, v156
	ds_read_b128 v[166:169], v161
	ds_read_b128 v[170:173], v161 offset:1024
	ds_read_b128 v[174:177], v161 offset:2048
	ds_read_b128 v[178:181], v161 offset:3072
	s_mov_b32 m0, s33
	v_lshl_add_u64 v[206:207], v[154:155], 0, s[6:7]
	ds_read_b128 v[182:185], v160 offset:32768
	ds_read_b128 v[186:189], v160 offset:33792
	ds_read_b128 v[190:193], v160 offset:34816
	ds_read_b128 v[194:197], v160 offset:35840
	ds_read_b128 v[198:201], v160 offset:36864
	ds_read_b128 v[202:205], v160 offset:37888
	ds_read_b128 v[210:213], v160 offset:38912
	ds_read_b128 v[214:217], v160 offset:39936
	global_load_lds_dwordx4 v[206:207], off
	v_lshl_add_u64 v[206:207], v[154:155], 0, s[8:9]
	s_mov_b32 m0, s34
	s_nop 0
	global_load_lds_dwordx4 v[206:207], off
	s_waitcnt vmcnt(8)
	s_waitcnt lgkmcnt(0)
	s_barrier
	s_setprio 1
	s_waitcnt lgkmcnt(0)
	v_mfma_f32_16x16x32_bf16 v[120:123], v[130:133], v[182:185], v[120:123]
	v_mfma_f32_16x16x32_bf16 v[124:127], v[138:141], v[182:185], v[124:127]
	v_mfma_f32_16x16x32_bf16 v[112:115], v[130:133], v[190:193], v[112:115]
	v_mfma_f32_16x16x32_bf16 v[116:119], v[138:141], v[190:193], v[116:119]
	v_mfma_f32_16x16x32_bf16 v[100:103], v[130:133], v[198:201], v[100:103]
	v_mfma_f32_16x16x32_bf16 v[108:111], v[138:141], v[198:201], v[108:111]
	v_mfma_f32_16x16x32_bf16 v[84:87], v[130:133], v[210:213], v[84:87]
	v_mfma_f32_16x16x32_bf16 v[72:75], v[138:141], v[210:213], v[72:75]
	v_mfma_f32_16x16x32_bf16 v[120:123], v[134:137], v[186:189], v[120:123]
	v_mfma_f32_16x16x32_bf16 v[124:127], v[162:165], v[186:189], v[124:127]
	v_mfma_f32_16x16x32_bf16 v[112:115], v[134:137], v[194:197], v[112:115]
	v_mfma_f32_16x16x32_bf16 v[116:119], v[162:165], v[194:197], v[116:119]
	v_mfma_f32_16x16x32_bf16 v[100:103], v[134:137], v[202:205], v[100:103]
	v_mfma_f32_16x16x32_bf16 v[108:111], v[162:165], v[202:205], v[108:111]
	v_mfma_f32_16x16x32_bf16 v[84:87], v[134:137], v[214:217], v[84:87]
	v_mfma_f32_16x16x32_bf16 v[72:75], v[162:165], v[214:217], v[72:75]
	v_mfma_f32_16x16x32_bf16 v[104:107], v[166:169], v[182:185], v[104:107]
	v_mfma_f32_16x16x32_bf16 v[92:95], v[174:177], v[182:185], v[92:95]
	v_mfma_f32_16x16x32_bf16 v[96:99], v[166:169], v[190:193], v[96:99]
	v_mfma_f32_16x16x32_bf16 v[80:83], v[174:177], v[190:193], v[80:83]
	v_mfma_f32_16x16x32_bf16 v[88:91], v[166:169], v[198:201], v[88:91]
	v_mfma_f32_16x16x32_bf16 v[76:79], v[174:177], v[198:201], v[76:79]
	v_mfma_f32_16x16x32_bf16 v[68:71], v[166:169], v[210:213], v[68:71]
	v_mfma_f32_16x16x32_bf16 v[64:67], v[174:177], v[210:213], v[64:67]
	v_mfma_f32_16x16x32_bf16 v[104:107], v[170:173], v[186:189], v[104:107]
	v_mfma_f32_16x16x32_bf16 v[92:95], v[178:181], v[186:189], v[92:95]
	v_mfma_f32_16x16x32_bf16 v[96:99], v[170:173], v[194:197], v[96:99]
	v_mfma_f32_16x16x32_bf16 v[80:83], v[178:181], v[194:197], v[80:83]
	v_mfma_f32_16x16x32_bf16 v[88:91], v[170:173], v[202:205], v[88:91]
	v_mfma_f32_16x16x32_bf16 v[76:79], v[178:181], v[202:205], v[76:79]
	v_mfma_f32_16x16x32_bf16 v[68:71], v[170:173], v[214:217], v[68:71]
	v_mfma_f32_16x16x32_bf16 v[64:67], v[178:181], v[214:217], v[64:67]
	s_setprio 0
	s_barrier
; #define G8_STA(bufoff, ptr, sg, h) G8_STAGE1(bufoff, (ptr) + (h) * ((sg) ? hA1 : hA0), ((sg) ? voffA1 : voffA0), ((sg) ? r64A1 : r64A0))
; #define G8_STB(bufoff, ptr, sg, h) G8_STAGE1(bufoff, (ptr) + (h) * ((sg) ? hB1 : hB0), ((sg) ? voffB1 : voffB0), ((sg) ? r64B1 : r64B0))
; #define G8_LDA(dst, b, h) do { _Pragma("unroll") for (int m = 0; m < 4; ++m) _Pragma("unroll") for (int k = 0; k < 2; ++k) dst[m][k] = *(const LAS bf16x8*)(lds + G8_SA(b, h) + aoff + m * 2048 + k * 1024); } while (0)
; #define G8_MMA(ai, bj, At, Bt) do { __builtin_amdgcn_s_setprio(1); _Pragma("unroll") for (int m = 0; m < 4; ++m) _Pragma("unroll") for (int n = 0; n < 2; ++n) _Pragma("unroll") for (int k = 0; k < 2; ++k) \
;         acc[ai][bj][m][n] = __builtin_amdgcn_mfma_f32_16x16x32_bf16(Bt[n][k], At[m][k], acc[ai][bj][m][n], 0, 0, 0); __builtin_amdgcn_s_setprio(0); } while (0)
; #define G8_WAIT_V(n) asm volatile("s_waitcnt vmcnt(" #n ")" ::: "memory")
; #define G8_WAIT_L(n) asm volatile("s_waitcnt lgkmcnt(" #n ")" ::: "memory")
; #define G8_BAR __builtin_amdgcn_s_barrier()
; #define G8_SCHED __builtin_amdgcn_sched_barrier(0)
; template <class P>
; __device__ __forceinline__ void gemm_phase(LAS unsigned char* lds, const P& p, const int G, const int c) {
;     ...
;             G8_LDA(At, 1, 1); G8_STB(G8_SB(1, 0), b3, sg2, 0); G8_STB(G8_SB(1, 1), b3, sg2, 1); G8_STA(G8_SA(1, 0), a3, sg2, 0);
;             G8_WAIT_V(8); G8_WAIT_L(0); G8_BAR; G8_MMA(1, 0, At, B0); G8_MMA(1, 1, At, B1); G8_BAR; G8_SCHED;
;         }
;         if (wr == 0) G8_BAR;
	s_add_i32 s77, s77, s26
	v_lshl_add_u64 v[206:207], v[142:143], 0, s[12:13]
	s_mov_b32 m0, s77
	ds_read_b128 v[182:185], v160 offset:49152
	ds_read_b128 v[186:189], v160 offset:50176
	ds_read_b128 v[190:193], v160 offset:51200
	ds_read_b128 v[194:197], v160 offset:52224
	ds_read_b128 v[198:201], v160 offset:53248
	ds_read_b128 v[202:205], v160 offset:54272
	ds_read_b128 v[210:213], v160 offset:55296
	ds_read_b128 v[214:217], v160 offset:56320
	global_load_lds_dwordx4 v[206:207], off
	v_lshl_add_u64 v[206:207], v[142:143], 0, s[14:15]
	s_add_i32 m0, s77, 0x2000
	s_add_i32 s77, s78, s26
	global_load_lds_dwordx4 v[206:207], off
	v_lshl_add_u64 v[206:207], v[142:143], 0, s[22:23]
	s_mov_b32 m0, s77
	v_lshl_add_u64 v[142:143], v[142:143], 0, s[36:37]
	global_load_lds_dwordx4 v[206:207], off
	s_add_i32 m0, s77, 0x2000
	s_nop 0
	global_load_lds_dwordx4 v[142:143], off
	v_lshl_add_u64 v[142:143], v[154:155], 0, s[16:17]
	s_mov_b32 m0, s67
	s_nop 0
	global_load_lds_dwordx4 v[142:143], off
	v_lshl_add_u64 v[142:143], v[154:155], 0, s[20:21]
	s_mov_b32 m0, s69
	s_nop 0
	global_load_lds_dwordx4 v[142:143], off
	s_waitcnt vmcnt(8)
	s_waitcnt lgkmcnt(0)
	s_barrier
	s_setprio 1
	s_waitcnt lgkmcnt(0)
	v_mfma_f32_16x16x32_bf16 v[60:63], v[130:133], v[182:185], v[60:63]
	v_mfma_f32_16x16x32_bf16 v[56:59], v[138:141], v[182:185], v[56:59]
	v_mfma_f32_16x16x32_bf16 v[52:55], v[130:133], v[190:193], v[52:55]
	v_mfma_f32_16x16x32_bf16 v[44:47], v[138:141], v[190:193], v[44:47]
	v_mfma_f32_16x16x32_bf16 v[36:39], v[130:133], v[198:201], v[36:39]
	v_mfma_f32_16x16x32_bf16 v[28:31], v[138:141], v[198:201], v[28:31]
	v_mfma_f32_16x16x32_bf16 v[20:23], v[130:133], v[210:213], v[20:23]
	v_mfma_f32_16x16x32_bf16 v[12:15], v[138:141], v[210:213], v[12:15]
	v_mfma_f32_16x16x32_bf16 v[60:63], v[134:137], v[186:189], v[60:63]
	v_mfma_f32_16x16x32_bf16 v[56:59], v[162:165], v[186:189], v[56:59]
	v_mfma_f32_16x16x32_bf16 v[52:55], v[134:137], v[194:197], v[52:55]
	v_mfma_f32_16x16x32_bf16 v[44:47], v[162:165], v[194:197], v[44:47]
	v_mfma_f32_16x16x32_bf16 v[36:39], v[134:137], v[202:205], v[36:39]
	v_mfma_f32_16x16x32_bf16 v[28:31], v[162:165], v[202:205], v[28:31]
	v_mfma_f32_16x16x32_bf16 v[20:23], v[134:137], v[214:217], v[20:23]
	v_mfma_f32_16x16x32_bf16 v[12:15], v[162:165], v[214:217], v[12:15]
	v_mfma_f32_16x16x32_bf16 v[48:51], v[166:169], v[182:185], v[48:51]
	v_mfma_f32_16x16x32_bf16 v[40:43], v[174:177], v[182:185], v[40:43]
	v_mfma_f32_16x16x32_bf16 v[32:35], v[166:169], v[190:193], v[32:35]
	v_mfma_f32_16x16x32_bf16 v[24:27], v[174:177], v[190:193], v[24:27]
	v_mfma_f32_16x16x32_bf16 v[16:19], v[166:169], v[198:201], v[16:19]
	v_mfma_f32_16x16x32_bf16 v[8:11], v[174:177], v[198:201], v[8:11]
	v_mfma_f32_16x16x32_bf16 v[4:7], v[166:169], v[210:213], v[4:7]
	v_mfma_f32_16x16x32_bf16 v[0:3], v[174:177], v[210:213], v[0:3]
	v_mfma_f32_16x16x32_bf16 v[48:51], v[170:173], v[186:189], v[48:51]
	v_mfma_f32_16x16x32_bf16 v[40:43], v[178:181], v[186:189], v[40:43]
	v_mfma_f32_16x16x32_bf16 v[32:35], v[170:173], v[194:197], v[32:35]
	v_mfma_f32_16x16x32_bf16 v[24:27], v[178:181], v[194:197], v[24:27]
	v_mfma_f32_16x16x32_bf16 v[16:19], v[170:173], v[202:205], v[16:19]
	v_mfma_f32_16x16x32_bf16 v[8:11], v[178:181], v[202:205], v[8:11]
	v_mfma_f32_16x16x32_bf16 v[4:7], v[170:173], v[214:217], v[4:7]
	v_mfma_f32_16x16x32_bf16 v[0:3], v[178:181], v[214:217], v[0:3]
	s_setprio 0
	s_barrier
	s_add_i32 s76, s76, 2
	s_add_u32 s28, s28, 0x40000
	s_addc_u32 s29, s29, 0
	s_add_u32 s72, s72, 0x800000
	s_addc_u32 s73, s73, 0
	s_cmp_gt_u32 s76, 29
	s_cbranch_scc0 .LBB0_770
	s_and_b64 vcc, exec, s[38:39]
	s_cbranch_vccz .LBB0_773
	s_barrier
